# gla_prep item start: weight, gate-column and LDS-staging loads all issued before one wait (was 3 serialized round trips)
# baseline (speedup 1.0000x reference)
; __device__ __forceinline__ void gla_prep_item(LAS unsigned char* lds, int item, const bf16_t* Z, const float* W2, const float* Bg, bf16_t* KDT, float* DEC) {
;     ...
;     for (int i = tid; i < 1024; i += 512) { const int t = i >> 4, r = i & 15; zgs[i] = bf2f(Z[(row0 + t) * ZLD + ZZG + r]); }
;     __syncthreads();
;     const int h = tid >> 7, kd = tid & 127, col = h * 128 + kd;
;     float w[16];
; #pragma unroll
;     for (int r = 0; r < 16; ++r) w[r] = W2[r * 512 + col];
;     const float bias = Bg[col];
;     ...
;     bf16_t* dst = KDT + (size_t)((b * 4 + h) * 32 + c) * 8192 + (size_t)((kd >> 4) * 2 * 64 + (kd & 15)) * 8;
;     const bf16_t* gk = Z + row0 * ZLD + ZGK + col;
; #pragma unroll
;     for (int t8 = 0; t8 < 8; ++t8) {
;         float kv[8];
; #pragma unroll
;         for (int e = 0; e < 8; ++e) {
;             const int t = t8 * 8 + e;
;             bc += gv[t];
;             kv[e] = bf2f(gk[(size_t)t * ZLD]) * __expf(bend - bc);
.LBB0_597:
	s_ashr_i32 s8, s66, 5
	s_ashr_i32 s9, s8, 31
	s_lshl_b64 s[6:7], s[8:9], 11
	s_and_b32 s0, s65, 31
	v_or_b32_e32 v0, s6, v4
	v_lshl_or_b32 v0, s0, 6, v0
	s_movk_i32 s0, 0x1800
	v_mad_u64_u32 v[0:1], s[0:1], v0, s0, v[44:45]
	v_mad_i32_i24 v1, s7, v59, v1
	global_load_dword v65, v[6:7], off
	global_load_dword v66, v[6:7], off offset:2048
	global_load_dword v67, v[8:9], off
	global_load_dword v68, v[10:11], off
	global_load_dword v55, v[12:13], off
	global_load_dword v62, v[14:15], off
	global_load_dword v63, v[16:17], off
	global_load_dword v64, v[18:19], off
	global_load_dword v52, v[20:21], off
	global_load_dword v53, v[22:23], off
	global_load_dword v50, v[24:25], off
	global_load_dword v51, v[26:27], off
	global_load_dword v48, v[28:29], off
	global_load_dword v49, v[30:31], off
	global_load_dword v46, v[32:33], off
	global_load_dword v47, v[34:35], off
	global_load_dword v69, v[36:37], off
	s_and_b32 s9, s66, 31
	s_lshl_b32 s0, s9, 6
	s_or_b32 s6, s6, s0
	s_mulk_i32 s7, 0x1800
	v_mad_u64_u32 v[208:209], s[42:43], s6, v59, v[42:43]
	v_add_u32_e32 v209, s7, v209
	s_mov_b32 s43, 0
	global_load_ushort v140, v[208:209], off offset:2688
	s_mov_b32 s42, 0x2000
	v_lshl_add_u64 v[206:207], v[208:209], 0, s[42:43]
	global_load_ushort v141, v[206:207], off offset:640
	s_mov_b32 s42, 0x3000
	v_lshl_add_u64 v[206:207], v[208:209], 0, s[42:43]
	global_load_ushort v142, v[206:207], off offset:2688
	s_mov_b32 s42, 0x5000
	v_lshl_add_u64 v[206:207], v[208:209], 0, s[42:43]
	global_load_ushort v143, v[206:207], off offset:640
	s_mov_b32 s42, 0x6000
	v_lshl_add_u64 v[206:207], v[208:209], 0, s[42:43]
	global_load_ushort v144, v[206:207], off offset:2688
	s_mov_b32 s42, 0x8000
	v_lshl_add_u64 v[206:207], v[208:209], 0, s[42:43]
	global_load_ushort v145, v[206:207], off offset:640
	s_mov_b32 s42, 0x9000
	v_lshl_add_u64 v[206:207], v[208:209], 0, s[42:43]
	global_load_ushort v146, v[206:207], off offset:2688
	s_mov_b32 s42, 0xb000
	v_lshl_add_u64 v[206:207], v[208:209], 0, s[42:43]
	global_load_ushort v147, v[206:207], off offset:640
	s_mov_b32 s42, 0xc000
	v_lshl_add_u64 v[206:207], v[208:209], 0, s[42:43]
	global_load_ushort v148, v[206:207], off offset:2688
	s_mov_b32 s42, 0xe000
	v_lshl_add_u64 v[206:207], v[208:209], 0, s[42:43]
	global_load_ushort v149, v[206:207], off offset:640
	s_mov_b32 s42, 0xf000
	v_lshl_add_u64 v[206:207], v[208:209], 0, s[42:43]
	global_load_ushort v150, v[206:207], off offset:2688
	s_mov_b32 s42, 0x11000
	v_lshl_add_u64 v[206:207], v[208:209], 0, s[42:43]
	global_load_ushort v151, v[206:207], off offset:640
	s_mov_b32 s42, 0x12000
	v_lshl_add_u64 v[206:207], v[208:209], 0, s[42:43]
	global_load_ushort v152, v[206:207], off offset:2688
	s_mov_b32 s42, 0x14000
	v_lshl_add_u64 v[206:207], v[208:209], 0, s[42:43]
	global_load_ushort v153, v[206:207], off offset:640
	s_mov_b32 s42, 0x15000
	v_lshl_add_u64 v[206:207], v[208:209], 0, s[42:43]
	global_load_ushort v154, v[206:207], off offset:2688
	s_mov_b32 s42, 0x17000
	v_lshl_add_u64 v[206:207], v[208:209], 0, s[42:43]
	global_load_ushort v155, v[206:207], off offset:640
	s_mov_b32 s42, 0x18000
	v_lshl_add_u64 v[206:207], v[208:209], 0, s[42:43]
	global_load_ushort v156, v[206:207], off offset:2688
	s_mov_b32 s42, 0x1a000
	v_lshl_add_u64 v[206:207], v[208:209], 0, s[42:43]
	global_load_ushort v157, v[206:207], off offset:640
	s_mov_b32 s42, 0x1b000
	v_lshl_add_u64 v[206:207], v[208:209], 0, s[42:43]
	global_load_ushort v158, v[206:207], off offset:2688
	s_mov_b32 s42, 0x1d000
	v_lshl_add_u64 v[206:207], v[208:209], 0, s[42:43]
	global_load_ushort v159, v[206:207], off offset:640
	s_mov_b32 s42, 0x1e000
	v_lshl_add_u64 v[206:207], v[208:209], 0, s[42:43]
	global_load_ushort v160, v[206:207], off offset:2688
	s_mov_b32 s42, 0x20000
	v_lshl_add_u64 v[206:207], v[208:209], 0, s[42:43]
	global_load_ushort v161, v[206:207], off offset:640
	s_mov_b32 s42, 0x21000
	v_lshl_add_u64 v[206:207], v[208:209], 0, s[42:43]
	global_load_ushort v162, v[206:207], off offset:2688
	s_mov_b32 s42, 0x23000
	v_lshl_add_u64 v[206:207], v[208:209], 0, s[42:43]
	global_load_ushort v163, v[206:207], off offset:640
	s_mov_b32 s42, 0x24000
	v_lshl_add_u64 v[206:207], v[208:209], 0, s[42:43]
	global_load_ushort v164, v[206:207], off offset:2688
	s_mov_b32 s42, 0x26000
	v_lshl_add_u64 v[206:207], v[208:209], 0, s[42:43]
	global_load_ushort v165, v[206:207], off offset:640
	s_mov_b32 s42, 0x27000
	v_lshl_add_u64 v[206:207], v[208:209], 0, s[42:43]
	global_load_ushort v166, v[206:207], off offset:2688
	s_mov_b32 s42, 0x29000
	v_lshl_add_u64 v[206:207], v[208:209], 0, s[42:43]
	global_load_ushort v167, v[206:207], off offset:640
	s_mov_b32 s42, 0x2a000
	v_lshl_add_u64 v[206:207], v[208:209], 0, s[42:43]
	global_load_ushort v168, v[206:207], off offset:2688
	s_mov_b32 s42, 0x2c000
	v_lshl_add_u64 v[206:207], v[208:209], 0, s[42:43]
	global_load_ushort v169, v[206:207], off offset:640
	s_mov_b32 s42, 0x2d000
	v_lshl_add_u64 v[206:207], v[208:209], 0, s[42:43]
	global_load_ushort v170, v[206:207], off offset:2688
	s_mov_b32 s42, 0x2f000
	v_lshl_add_u64 v[206:207], v[208:209], 0, s[42:43]
	global_load_ushort v171, v[206:207], off offset:640
	s_mov_b32 s42, 0x30000
	v_lshl_add_u64 v[206:207], v[208:209], 0, s[42:43]
	global_load_ushort v172, v[206:207], off offset:2688
	s_mov_b32 s42, 0x32000
	v_lshl_add_u64 v[206:207], v[208:209], 0, s[42:43]
	global_load_ushort v173, v[206:207], off offset:640
	s_mov_b32 s42, 0x33000
	v_lshl_add_u64 v[206:207], v[208:209], 0, s[42:43]
	global_load_ushort v174, v[206:207], off offset:2688
	s_mov_b32 s42, 0x35000
	v_lshl_add_u64 v[206:207], v[208:209], 0, s[42:43]
; __device__ __forceinline__ float log_sigmoid(float x) { return fminf(x, 0.f) - __logf(1.f + __expf(-fabsf(x))); }
; __device__ __forceinline__ void gla_prep_item(LAS unsigned char* lds, int item, const bf16_t* Z, const float* W2, const float* Bg, bf16_t* KDT, float* DEC) {
;     ...
;     for (int i = tid; i < 1024; i += 512) { const int t = i >> 4, r = i & 15; zgs[i] = bf2f(Z[(row0 + t) * ZLD + ZZG + r]); }
;     __syncthreads();
;     const int h = tid >> 7, kd = tid & 127, col = h * 128 + kd;
;     float w[16];
; #pragma unroll
;     for (int r = 0; r < 16; ++r) w[r] = W2[r * 512 + col];
;     const float bias = Bg[col];
;     float bend = 0.f; float gv[64];
; #pragma unroll
;     for (int t = 0; t < 64; ++t) {
;         float x = bias;
; #pragma unroll
;         for (int r = 0; r < 16; ++r) x += zgs[t * 16 + r] * w[r];
;         gv[t] = log_sigmoid(x) * (1.f / 16.f); bend += gv[t];
	global_load_ushort v175, v[206:207], off offset:640
	s_mov_b32 s42, 0x36000
	v_lshl_add_u64 v[206:207], v[208:209], 0, s[42:43]
	global_load_ushort v176, v[206:207], off offset:2688
	s_mov_b32 s42, 0x38000
	v_lshl_add_u64 v[206:207], v[208:209], 0, s[42:43]
	global_load_ushort v177, v[206:207], off offset:640
	s_mov_b32 s42, 0x39000
	v_lshl_add_u64 v[206:207], v[208:209], 0, s[42:43]
	global_load_ushort v178, v[206:207], off offset:2688
	s_mov_b32 s42, 0x3b000
	v_lshl_add_u64 v[206:207], v[208:209], 0, s[42:43]
	global_load_ushort v179, v[206:207], off offset:640
	s_mov_b32 s42, 0x3c000
	v_lshl_add_u64 v[206:207], v[208:209], 0, s[42:43]
	global_load_ushort v180, v[206:207], off offset:2688
	s_mov_b32 s42, 0x3e000
	v_lshl_add_u64 v[206:207], v[208:209], 0, s[42:43]
	global_load_ushort v181, v[206:207], off offset:640
	s_mov_b32 s42, 0x3f000
	v_lshl_add_u64 v[206:207], v[208:209], 0, s[42:43]
	global_load_ushort v182, v[206:207], off offset:2688
	s_mov_b32 s42, 0x41000
	v_lshl_add_u64 v[206:207], v[208:209], 0, s[42:43]
	global_load_ushort v183, v[206:207], off offset:640
	s_mov_b32 s42, 0x42000
	v_lshl_add_u64 v[206:207], v[208:209], 0, s[42:43]
	global_load_ushort v186, v[206:207], off offset:2688
	s_mov_b32 s42, 0x44000
	v_lshl_add_u64 v[206:207], v[208:209], 0, s[42:43]
	global_load_ushort v187, v[206:207], off offset:640
	s_mov_b32 s42, 0x45000
	v_lshl_add_u64 v[206:207], v[208:209], 0, s[42:43]
	global_load_ushort v188, v[206:207], off offset:2688
	s_mov_b32 s42, 0x47000
	v_lshl_add_u64 v[206:207], v[208:209], 0, s[42:43]
	global_load_ushort v189, v[206:207], off offset:640
	s_mov_b32 s42, 0x48000
	v_lshl_add_u64 v[206:207], v[208:209], 0, s[42:43]
	global_load_ushort v190, v[206:207], off offset:2688
	s_mov_b32 s42, 0x4a000
	v_lshl_add_u64 v[206:207], v[208:209], 0, s[42:43]
	global_load_ushort v191, v[206:207], off offset:640
	s_mov_b32 s42, 0x4b000
	v_lshl_add_u64 v[206:207], v[208:209], 0, s[42:43]
	global_load_ushort v192, v[206:207], off offset:2688
	s_mov_b32 s42, 0x4d000
	v_lshl_add_u64 v[206:207], v[208:209], 0, s[42:43]
	global_load_ushort v193, v[206:207], off offset:640
	s_mov_b32 s42, 0x4e000
	v_lshl_add_u64 v[206:207], v[208:209], 0, s[42:43]
	global_load_ushort v194, v[206:207], off offset:2688
	s_mov_b32 s42, 0x50000
	v_lshl_add_u64 v[206:207], v[208:209], 0, s[42:43]
	global_load_ushort v195, v[206:207], off offset:640
	s_mov_b32 s42, 0x51000
	v_lshl_add_u64 v[206:207], v[208:209], 0, s[42:43]
	global_load_ushort v196, v[206:207], off offset:2688
	s_mov_b32 s42, 0x53000
	v_lshl_add_u64 v[206:207], v[208:209], 0, s[42:43]
	global_load_ushort v197, v[206:207], off offset:640
	s_mov_b32 s42, 0x54000
	v_lshl_add_u64 v[206:207], v[208:209], 0, s[42:43]
	global_load_ushort v198, v[206:207], off offset:2688
	s_mov_b32 s42, 0x56000
	v_lshl_add_u64 v[206:207], v[208:209], 0, s[42:43]
	global_load_ushort v199, v[206:207], off offset:640
	s_mov_b32 s42, 0x57000
	v_lshl_add_u64 v[206:207], v[208:209], 0, s[42:43]
	global_load_ushort v200, v[206:207], off offset:2688
	s_mov_b32 s42, 0x59000
	v_lshl_add_u64 v[206:207], v[208:209], 0, s[42:43]
	global_load_ushort v201, v[206:207], off offset:640
	s_mov_b32 s42, 0x5a000
	v_lshl_add_u64 v[206:207], v[208:209], 0, s[42:43]
	global_load_ushort v202, v[206:207], off offset:2688
	s_mov_b32 s42, 0x5c000
	v_lshl_add_u64 v[206:207], v[208:209], 0, s[42:43]
	global_load_ushort v203, v[206:207], off offset:640
	s_mov_b32 s42, 0x5d000
	v_lshl_add_u64 v[206:207], v[208:209], 0, s[42:43]
	global_load_ushort v204, v[206:207], off offset:2688
	s_mov_b32 s42, 0x5f000
	v_lshl_add_u64 v[206:207], v[208:209], 0, s[42:43]
	global_load_ushort v205, v[206:207], off offset:640
	v_mov_b32_e32 v2, v58
	global_load_ushort v210, v[0:1], off
	s_mov_b64 s[16:17], 0x30000
	v_lshl_add_u64 v[0:1], v[0:1], 0, s[16:17]
	global_load_ushort v211, v[0:1], off
	s_waitcnt vmcnt(0) lgkmcnt(0)
	v_lshlrev_b32_e32 v210, 16, v210
	v_lshlrev_b32_e32 v211, 16, v211
	ds_write_b32 v2, v210
	v_add_u32_e32 v2, 0x800, v2
	ds_write_b32 v2, v211
	s_waitcnt lgkmcnt(0)
	s_barrier
	ds_read_b128 v[0:3], v5
	ds_read_b128 v[70:73], v5 offset:16
	ds_read_b128 v[74:77], v5 offset:32
	ds_read_b128 v[78:81], v5 offset:48
	s_add_i32 s66, s66, s15
	s_add_i32 s65, s65, s15
	s_cmpk_gt_i32 s66, 0xff
	s_waitcnt vmcnt(0) lgkmcnt(3)
	v_fma_f32 v54, v65, v0, v69
	v_fmac_f32_e32 v54, v66, v1
	v_fmac_f32_e32 v54, v67, v2
	v_fmac_f32_e32 v54, v68, v3
	s_waitcnt lgkmcnt(2)
	v_fmac_f32_e32 v54, v55, v70
	v_fmac_f32_e32 v54, v62, v71
	v_fmac_f32_e32 v54, v63, v72
	v_fmac_f32_e32 v54, v64, v73
	s_waitcnt lgkmcnt(1)
	v_fmac_f32_e32 v54, v52, v74
	v_fmac_f32_e32 v54, v53, v75
	v_fmac_f32_e32 v54, v50, v76
	v_fmac_f32_e32 v54, v51, v77
	s_waitcnt lgkmcnt(0)
	v_pk_mul_f32 v[0:1], v[48:49], v[78:79]
	s_nop 0
	v_add_f32_e32 v0, v54, v0
	v_add_f32_e32 v2, v0, v1
	v_pk_mul_f32 v[0:1], v[46:47], v[80:81]
	s_nop 0
	v_add_f32_e32 v0, v2, v0
	v_add_f32_e32 v0, v0, v1
	v_min_f32_e32 v1, 0, v0
	v_mul_f32_e64 v0, |v0|, s11
	v_exp_f32_e32 v0, v0
	s_nop 0
	v_add_f32_e32 v0, 1.0, v0
	v_cmp_gt_f32_e32 vcc, s12, v0
	s_nop 1
	v_cndmask_b32_e64 v2, 0, 32, vcc
	v_ldexp_f32 v0, v0, v2
	v_log_f32_e32 v0, v0
	s_nop 0
	v_mul_f32_e32 v2, 0x3f317217, v0
	v_fma_f32 v2, v0, s13, -v2
	v_fmac_f32_e32 v2, 0x3377d1cf, v0
	v_fmac_f32_e32 v2, 0x3f317217, v0
	v_cmp_lt_f32_e64 s[0:1], |v0|, s36
	s_nop 1
	v_cndmask_b32_e64 v0, v0, v2, s[0:1]
	v_cndmask_b32_e32 v2, 0, v60, vcc
	v_sub_f32_e32 v0, v0, v2
	v_sub_f32_e32 v0, v1, v0
	s_mov_b32 s0, 0x3d800000
	v_fma_f32 v54, v0, s0, 0
	ds_read_b128 v[240:243], v5 offset:64
	ds_read_b128 v[244:247], v5 offset:80
	ds_read_b128 v[248:251], v5 offset:96
	ds_read_b128 v[252:255], v5 offset:112
	ds_read_b128 v[210:213], v5 offset:128
	ds_read_b128 v[214:217], v5 offset:144
	ds_read_b128 v[218:221], v5 offset:160
	ds_read_b128 v[222:225], v5 offset:176
	s_waitcnt lgkmcnt(4)
; __device__ __forceinline__ float log_sigmoid(float x) { return fminf(x, 0.f) - __logf(1.f + __expf(-fabsf(x))); }
; __device__ __forceinline__ void gla_prep_item(LAS unsigned char* lds, int item, const bf16_t* Z, const float* W2, const float* Bg, bf16_t* KDT, float* DEC) {
;     ...
;     float bend = 0.f; float gv[64];
; #pragma unroll
;     for (int t = 0; t < 64; ++t) {
;         float x = bias;
; #pragma unroll
;         for (int r = 0; r < 16; ++r) x += zgs[t * 16 + r] * w[r];
;         gv[t] = log_sigmoid(x) * (1.f / 16.f); bend += gv[t];
;     }
	v_fma_f32 v70, v65, v240, v69
	v_fmac_f32_e32 v70, v66, v241
	v_fmac_f32_e32 v70, v67, v242
	v_fmac_f32_e32 v70, v68, v243
	v_fmac_f32_e32 v70, v55, v244
	v_fmac_f32_e32 v70, v62, v245
	v_fmac_f32_e32 v70, v63, v246
	v_fmac_f32_e32 v70, v64, v247
	v_fmac_f32_e32 v70, v52, v248
	v_fmac_f32_e32 v70, v53, v249
	v_fmac_f32_e32 v70, v50, v250
	v_fmac_f32_e32 v70, v51, v251
	v_pk_mul_f32 v[0:1], v[48:49], v[252:253]
	s_nop 0
	v_add_f32_e32 v0, v70, v0
	v_add_f32_e32 v70, v0, v1
	v_pk_mul_f32 v[0:1], v[46:47], v[254:255]
	s_nop 0
	v_add_f32_e32 v0, v70, v0
	v_add_f32_e32 v0, v0, v1
	v_min_f32_e32 v1, 0, v0
	v_mul_f32_e64 v0, |v0|, s11
	v_exp_f32_e32 v0, v0
	s_nop 0
	v_add_f32_e32 v0, 1.0, v0
	v_cmp_gt_f32_e32 vcc, s12, v0
	s_nop 1
	v_cndmask_b32_e64 v2, 0, 32, vcc
	v_ldexp_f32 v0, v0, v2
	v_log_f32_e32 v0, v0
	s_nop 0
	v_mul_f32_e32 v2, 0x3f317217, v0
	v_fma_f32 v2, v0, s13, -v2
	v_fmac_f32_e32 v2, 0x3377d1cf, v0
	v_fmac_f32_e32 v2, 0x3f317217, v0
	v_cmp_lt_f32_e64 s[0:1], |v0|, s36
	s_nop 1
	v_cndmask_b32_e64 v0, v0, v2, s[0:1]
	v_cndmask_b32_e32 v2, 0, v60, vcc
	v_sub_f32_e32 v0, v0, v2
	v_sub_f32_e32 v0, v1, v0
	v_fmamk_f32 v70, v0, 0x3d800000, v54
	ds_read_b128 v[240:243], v5 offset:192
	ds_read_b128 v[244:247], v5 offset:208
	ds_read_b128 v[248:251], v5 offset:224
	ds_read_b128 v[252:255], v5 offset:240
	s_waitcnt lgkmcnt(4)
	v_fma_f32 v71, v65, v210, v69
	v_fmac_f32_e32 v71, v66, v211
	v_fmac_f32_e32 v71, v67, v212
	v_fmac_f32_e32 v71, v68, v213
	v_fmac_f32_e32 v71, v55, v214
	v_fmac_f32_e32 v71, v62, v215
	v_fmac_f32_e32 v71, v63, v216
	v_fmac_f32_e32 v71, v64, v217
	v_fmac_f32_e32 v71, v52, v218
	v_fmac_f32_e32 v71, v53, v219
	v_fmac_f32_e32 v71, v50, v220
	v_fmac_f32_e32 v71, v51, v221
	v_pk_mul_f32 v[0:1], v[48:49], v[222:223]
	s_nop 0
	v_add_f32_e32 v0, v71, v0
	v_add_f32_e32 v71, v0, v1
	v_pk_mul_f32 v[0:1], v[46:47], v[224:225]
	s_nop 0
	v_add_f32_e32 v0, v71, v0
	v_add_f32_e32 v0, v0, v1
	v_min_f32_e32 v1, 0, v0
	v_mul_f32_e64 v0, |v0|, s11
	v_exp_f32_e32 v0, v0
	s_nop 0
	v_add_f32_e32 v0, 1.0, v0
	v_cmp_gt_f32_e32 vcc, s12, v0
	s_nop 1
	v_cndmask_b32_e64 v2, 0, 32, vcc
	v_ldexp_f32 v0, v0, v2
	v_log_f32_e32 v0, v0
	s_nop 0
	v_mul_f32_e32 v2, 0x3f317217, v0
	v_fma_f32 v2, v0, s13, -v2
	v_fmac_f32_e32 v2, 0x3377d1cf, v0
	v_fmac_f32_e32 v2, 0x3f317217, v0
	v_cmp_lt_f32_e64 s[0:1], |v0|, s36
	s_nop 1
	v_cndmask_b32_e64 v0, v0, v2, s[0:1]
	v_cndmask_b32_e32 v2, 0, v60, vcc
	v_sub_f32_e32 v0, v0, v2
	v_sub_f32_e32 v0, v1, v0
	v_fmamk_f32 v71, v0, 0x3d800000, v70
	ds_read_b128 v[210:213], v5 offset:256
	ds_read_b128 v[214:217], v5 offset:272
	ds_read_b128 v[218:221], v5 offset:288
	ds_read_b128 v[222:225], v5 offset:304
	s_waitcnt lgkmcnt(4)
	v_fma_f32 v72, v65, v240, v69
	v_fmac_f32_e32 v72, v66, v241
	v_fmac_f32_e32 v72, v67, v242
	v_fmac_f32_e32 v72, v68, v243
	v_fmac_f32_e32 v72, v55, v244
	v_fmac_f32_e32 v72, v62, v245
	v_fmac_f32_e32 v72, v63, v246
	v_fmac_f32_e32 v72, v64, v247
	v_fmac_f32_e32 v72, v52, v248
	v_fmac_f32_e32 v72, v53, v249
	v_fmac_f32_e32 v72, v50, v250
	v_fmac_f32_e32 v72, v51, v251
	v_pk_mul_f32 v[0:1], v[48:49], v[252:253]
	s_nop 0
	v_add_f32_e32 v0, v72, v0
	v_add_f32_e32 v72, v0, v1
	v_pk_mul_f32 v[0:1], v[46:47], v[254:255]
	s_nop 0
	v_add_f32_e32 v0, v72, v0
	v_add_f32_e32 v0, v0, v1
	v_min_f32_e32 v1, 0, v0
	v_mul_f32_e64 v0, |v0|, s11
	v_exp_f32_e32 v0, v0
	s_nop 0
	v_add_f32_e32 v0, 1.0, v0
	v_cmp_gt_f32_e32 vcc, s12, v0
	s_nop 1
	v_cndmask_b32_e64 v2, 0, 32, vcc
	v_ldexp_f32 v0, v0, v2
	v_log_f32_e32 v0, v0
	s_nop 0
	v_mul_f32_e32 v2, 0x3f317217, v0
	v_fma_f32 v2, v0, s13, -v2
	v_fmac_f32_e32 v2, 0x3377d1cf, v0
	v_fmac_f32_e32 v2, 0x3f317217, v0
	v_cmp_lt_f32_e64 s[0:1], |v0|, s36
	s_nop 1
	v_cndmask_b32_e64 v0, v0, v2, s[0:1]
	v_cndmask_b32_e32 v2, 0, v60, vcc
	v_sub_f32_e32 v0, v0, v2
	v_sub_f32_e32 v0, v1, v0
	v_fmamk_f32 v72, v0, 0x3d800000, v71
	ds_read_b128 v[240:243], v5 offset:320
	ds_read_b128 v[244:247], v5 offset:336
	ds_read_b128 v[248:251], v5 offset:352
	ds_read_b128 v[252:255], v5 offset:368
	s_waitcnt lgkmcnt(4)
	v_fma_f32 v73, v65, v210, v69
	v_fmac_f32_e32 v73, v66, v211
	v_fmac_f32_e32 v73, v67, v212
	v_fmac_f32_e32 v73, v68, v213
	v_fmac_f32_e32 v73, v55, v214
	v_fmac_f32_e32 v73, v62, v215
	v_fmac_f32_e32 v73, v63, v216
	v_fmac_f32_e32 v73, v64, v217
	v_fmac_f32_e32 v73, v52, v218
	v_fmac_f32_e32 v73, v53, v219
	v_fmac_f32_e32 v73, v50, v220
	v_fmac_f32_e32 v73, v51, v221
	v_pk_mul_f32 v[0:1], v[48:49], v[222:223]
	s_nop 0
	v_add_f32_e32 v0, v73, v0
	v_add_f32_e32 v73, v0, v1
	v_pk_mul_f32 v[0:1], v[46:47], v[224:225]
	s_nop 0
	v_add_f32_e32 v0, v73, v0
	v_add_f32_e32 v0, v0, v1
	v_min_f32_e32 v1, 0, v0
	v_mul_f32_e64 v0, |v0|, s11
	v_exp_f32_e32 v0, v0
	s_nop 0
	v_add_f32_e32 v0, 1.0, v0
	v_cmp_gt_f32_e32 vcc, s12, v0
	s_nop 1
	v_cndmask_b32_e64 v2, 0, 32, vcc
	v_ldexp_f32 v0, v0, v2
	v_log_f32_e32 v0, v0
	s_nop 0
	v_mul_f32_e32 v2, 0x3f317217, v0
	v_fma_f32 v2, v0, s13, -v2
	v_fmac_f32_e32 v2, 0x3377d1cf, v0
	v_fmac_f32_e32 v2, 0x3f317217, v0
	v_cmp_lt_f32_e64 s[0:1], |v0|, s36
	s_nop 1
	v_cndmask_b32_e64 v0, v0, v2, s[0:1]
	v_cndmask_b32_e32 v2, 0, v60, vcc
	v_sub_f32_e32 v0, v0, v2
	v_sub_f32_e32 v0, v1, v0
	v_fmamk_f32 v73, v0, 0x3d800000, v72
	ds_read_b128 v[210:213], v5 offset:384
	ds_read_b128 v[214:217], v5 offset:400
	ds_read_b128 v[218:221], v5 offset:416
	ds_read_b128 v[222:225], v5 offset:432
	s_waitcnt lgkmcnt(4)
; __device__ __forceinline__ float log_sigmoid(float x) { return fminf(x, 0.f) - __logf(1.f + __expf(-fabsf(x))); }
; __device__ __forceinline__ void gla_prep_item(LAS unsigned char* lds, int item, const bf16_t* Z, const float* W2, const float* Bg, bf16_t* KDT, float* DEC) {
;     ...
;     float bend = 0.f; float gv[64];
; #pragma unroll
;     for (int t = 0; t < 64; ++t) {
;         float x = bias;
; #pragma unroll
;         for (int r = 0; r < 16; ++r) x += zgs[t * 16 + r] * w[r];
;         gv[t] = log_sigmoid(x) * (1.f / 16.f); bend += gv[t];
;     }
	v_fma_f32 v74, v65, v240, v69
	v_fmac_f32_e32 v74, v66, v241
	v_fmac_f32_e32 v74, v67, v242
	v_fmac_f32_e32 v74, v68, v243
	v_fmac_f32_e32 v74, v55, v244
	v_fmac_f32_e32 v74, v62, v245
	v_fmac_f32_e32 v74, v63, v246
	v_fmac_f32_e32 v74, v64, v247
	v_fmac_f32_e32 v74, v52, v248
	v_fmac_f32_e32 v74, v53, v249
	v_fmac_f32_e32 v74, v50, v250
	v_fmac_f32_e32 v74, v51, v251
	v_pk_mul_f32 v[0:1], v[48:49], v[252:253]
	s_nop 0
	v_add_f32_e32 v0, v74, v0
	v_add_f32_e32 v74, v0, v1
	v_pk_mul_f32 v[0:1], v[46:47], v[254:255]
	s_nop 0
	v_add_f32_e32 v0, v74, v0
	v_add_f32_e32 v0, v0, v1
	v_min_f32_e32 v1, 0, v0
	v_mul_f32_e64 v0, |v0|, s11
	v_exp_f32_e32 v0, v0
	s_nop 0
	v_add_f32_e32 v0, 1.0, v0
	v_cmp_gt_f32_e32 vcc, s12, v0
	s_nop 1
	v_cndmask_b32_e64 v2, 0, 32, vcc
	v_ldexp_f32 v0, v0, v2
	v_log_f32_e32 v0, v0
	s_nop 0
	v_mul_f32_e32 v2, 0x3f317217, v0
	v_fma_f32 v2, v0, s13, -v2
	v_fmac_f32_e32 v2, 0x3377d1cf, v0
	v_fmac_f32_e32 v2, 0x3f317217, v0
	v_cmp_lt_f32_e64 s[0:1], |v0|, s36
	s_nop 1
	v_cndmask_b32_e64 v0, v0, v2, s[0:1]
	v_cndmask_b32_e32 v2, 0, v60, vcc
	v_sub_f32_e32 v0, v0, v2
	v_sub_f32_e32 v0, v1, v0
	v_fmamk_f32 v74, v0, 0x3d800000, v73
	ds_read_b128 v[240:243], v5 offset:448
	ds_read_b128 v[244:247], v5 offset:464
	ds_read_b128 v[248:251], v5 offset:480
	ds_read_b128 v[252:255], v5 offset:496
	s_waitcnt lgkmcnt(4)
	v_fma_f32 v75, v65, v210, v69
	v_fmac_f32_e32 v75, v66, v211
	v_fmac_f32_e32 v75, v67, v212
	v_fmac_f32_e32 v75, v68, v213
	v_fmac_f32_e32 v75, v55, v214
	v_fmac_f32_e32 v75, v62, v215
	v_fmac_f32_e32 v75, v63, v216
	v_fmac_f32_e32 v75, v64, v217
	v_fmac_f32_e32 v75, v52, v218
	v_fmac_f32_e32 v75, v53, v219
	v_fmac_f32_e32 v75, v50, v220
	v_fmac_f32_e32 v75, v51, v221
	v_pk_mul_f32 v[0:1], v[48:49], v[222:223]
	s_nop 0
	v_add_f32_e32 v0, v75, v0
	v_add_f32_e32 v75, v0, v1
	v_pk_mul_f32 v[0:1], v[46:47], v[224:225]
	s_nop 0
	v_add_f32_e32 v0, v75, v0
	v_add_f32_e32 v0, v0, v1
	v_min_f32_e32 v1, 0, v0
	v_mul_f32_e64 v0, |v0|, s11
	v_exp_f32_e32 v0, v0
	s_nop 0
	v_add_f32_e32 v0, 1.0, v0
	v_cmp_gt_f32_e32 vcc, s12, v0
	s_nop 1
	v_cndmask_b32_e64 v2, 0, 32, vcc
	v_ldexp_f32 v0, v0, v2
	v_log_f32_e32 v0, v0
	s_nop 0
	v_mul_f32_e32 v2, 0x3f317217, v0
	v_fma_f32 v2, v0, s13, -v2
	v_fmac_f32_e32 v2, 0x3377d1cf, v0
	v_fmac_f32_e32 v2, 0x3f317217, v0
	v_cmp_lt_f32_e64 s[0:1], |v0|, s36
	s_nop 1
	v_cndmask_b32_e64 v0, v0, v2, s[0:1]
	v_cndmask_b32_e32 v2, 0, v60, vcc
	v_sub_f32_e32 v0, v0, v2
	v_sub_f32_e32 v0, v1, v0
	v_fmamk_f32 v75, v0, 0x3d800000, v74
	ds_read_b128 v[210:213], v5 offset:512
	ds_read_b128 v[214:217], v5 offset:528
	ds_read_b128 v[218:221], v5 offset:544
	ds_read_b128 v[222:225], v5 offset:560
	s_waitcnt lgkmcnt(4)
	v_fma_f32 v76, v65, v240, v69
	v_fmac_f32_e32 v76, v66, v241
	v_fmac_f32_e32 v76, v67, v242
	v_fmac_f32_e32 v76, v68, v243
	v_fmac_f32_e32 v76, v55, v244
	v_fmac_f32_e32 v76, v62, v245
	v_fmac_f32_e32 v76, v63, v246
	v_fmac_f32_e32 v76, v64, v247
	v_fmac_f32_e32 v76, v52, v248
	v_fmac_f32_e32 v76, v53, v249
	v_fmac_f32_e32 v76, v50, v250
	v_fmac_f32_e32 v76, v51, v251
	v_pk_mul_f32 v[0:1], v[48:49], v[252:253]
	s_nop 0
	v_add_f32_e32 v0, v76, v0
	v_add_f32_e32 v76, v0, v1
	v_pk_mul_f32 v[0:1], v[46:47], v[254:255]
	s_nop 0
	v_add_f32_e32 v0, v76, v0
	v_add_f32_e32 v0, v0, v1
	v_min_f32_e32 v1, 0, v0
	v_mul_f32_e64 v0, |v0|, s11
	v_exp_f32_e32 v0, v0
	s_nop 0
	v_add_f32_e32 v0, 1.0, v0
	v_cmp_gt_f32_e32 vcc, s12, v0
	s_nop 1
	v_cndmask_b32_e64 v2, 0, 32, vcc
	v_ldexp_f32 v0, v0, v2
	v_log_f32_e32 v0, v0
	s_nop 0
	v_mul_f32_e32 v2, 0x3f317217, v0
	v_fma_f32 v2, v0, s13, -v2
	v_fmac_f32_e32 v2, 0x3377d1cf, v0
	v_fmac_f32_e32 v2, 0x3f317217, v0
	v_cmp_lt_f32_e64 s[0:1], |v0|, s36
	s_nop 1
	v_cndmask_b32_e64 v0, v0, v2, s[0:1]
	v_cndmask_b32_e32 v2, 0, v60, vcc
	v_sub_f32_e32 v0, v0, v2
	v_sub_f32_e32 v0, v1, v0
	v_fmamk_f32 v77, v0, 0x3d800000, v75
	ds_read_b128 v[240:243], v5 offset:576
	ds_read_b128 v[244:247], v5 offset:592
	ds_read_b128 v[248:251], v5 offset:608
	ds_read_b128 v[252:255], v5 offset:624
	s_waitcnt lgkmcnt(4)
	v_fma_f32 v76, v65, v210, v69
	v_fmac_f32_e32 v76, v66, v211
	v_fmac_f32_e32 v76, v67, v212
	v_fmac_f32_e32 v76, v68, v213
	v_fmac_f32_e32 v76, v55, v214
	v_fmac_f32_e32 v76, v62, v215
	v_fmac_f32_e32 v76, v63, v216
	v_fmac_f32_e32 v76, v64, v217
	v_fmac_f32_e32 v76, v52, v218
	v_fmac_f32_e32 v76, v53, v219
	v_fmac_f32_e32 v76, v50, v220
	v_fmac_f32_e32 v76, v51, v221
	v_pk_mul_f32 v[0:1], v[48:49], v[222:223]
	s_nop 0
	v_add_f32_e32 v0, v76, v0
	v_add_f32_e32 v76, v0, v1
	v_pk_mul_f32 v[0:1], v[46:47], v[224:225]
	s_nop 0
	v_add_f32_e32 v0, v76, v0
	v_add_f32_e32 v0, v0, v1
	v_min_f32_e32 v1, 0, v0
	v_mul_f32_e64 v0, |v0|, s11
	v_exp_f32_e32 v0, v0
	s_nop 0
	v_add_f32_e32 v0, 1.0, v0
	v_cmp_gt_f32_e32 vcc, s12, v0
	s_nop 1
	v_cndmask_b32_e64 v2, 0, 32, vcc
	v_ldexp_f32 v0, v0, v2
	v_log_f32_e32 v0, v0
	s_nop 0
	v_mul_f32_e32 v2, 0x3f317217, v0
	v_fma_f32 v2, v0, s13, -v2
	v_fmac_f32_e32 v2, 0x3377d1cf, v0
	v_fmac_f32_e32 v2, 0x3f317217, v0
	v_cmp_lt_f32_e64 s[0:1], |v0|, s36
	s_nop 1
	v_cndmask_b32_e64 v0, v0, v2, s[0:1]
	v_cndmask_b32_e32 v2, 0, v60, vcc
	v_sub_f32_e32 v0, v0, v2
	v_sub_f32_e32 v0, v1, v0
	v_fmamk_f32 v76, v0, 0x3d800000, v77
	ds_read_b128 v[210:213], v5 offset:640
	ds_read_b128 v[214:217], v5 offset:656
	ds_read_b128 v[218:221], v5 offset:672
	ds_read_b128 v[222:225], v5 offset:688
	s_waitcnt lgkmcnt(4)
; __device__ __forceinline__ float log_sigmoid(float x) { return fminf(x, 0.f) - __logf(1.f + __expf(-fabsf(x))); }
; __device__ __forceinline__ void gla_prep_item(LAS unsigned char* lds, int item, const bf16_t* Z, const float* W2, const float* Bg, bf16_t* KDT, float* DEC) {
;     ...
;     float bend = 0.f; float gv[64];
; #pragma unroll
;     for (int t = 0; t < 64; ++t) {
;         float x = bias;
; #pragma unroll
;         for (int r = 0; r < 16; ++r) x += zgs[t * 16 + r] * w[r];
;         gv[t] = log_sigmoid(x) * (1.f / 16.f); bend += gv[t];
;     }
	v_fma_f32 v78, v65, v240, v69
	v_fmac_f32_e32 v78, v66, v241
	v_fmac_f32_e32 v78, v67, v242
	v_fmac_f32_e32 v78, v68, v243
	v_fmac_f32_e32 v78, v55, v244
	v_fmac_f32_e32 v78, v62, v245
	v_fmac_f32_e32 v78, v63, v246
	v_fmac_f32_e32 v78, v64, v247
	v_fmac_f32_e32 v78, v52, v248
	v_fmac_f32_e32 v78, v53, v249
	v_fmac_f32_e32 v78, v50, v250
	v_fmac_f32_e32 v78, v51, v251
	v_pk_mul_f32 v[0:1], v[48:49], v[252:253]
	s_nop 0
	v_add_f32_e32 v0, v78, v0
	v_add_f32_e32 v78, v0, v1
	v_pk_mul_f32 v[0:1], v[46:47], v[254:255]
	s_nop 0
	v_add_f32_e32 v0, v78, v0
	v_add_f32_e32 v0, v0, v1
	v_min_f32_e32 v1, 0, v0
	v_mul_f32_e64 v0, |v0|, s11
	v_exp_f32_e32 v0, v0
	s_nop 0
	v_add_f32_e32 v0, 1.0, v0
	v_cmp_gt_f32_e32 vcc, s12, v0
	s_nop 1
	v_cndmask_b32_e64 v2, 0, 32, vcc
	v_ldexp_f32 v0, v0, v2
	v_log_f32_e32 v0, v0
	s_nop 0
	v_mul_f32_e32 v2, 0x3f317217, v0
	v_fma_f32 v2, v0, s13, -v2
	v_fmac_f32_e32 v2, 0x3377d1cf, v0
	v_fmac_f32_e32 v2, 0x3f317217, v0
	v_cmp_lt_f32_e64 s[0:1], |v0|, s36
	s_nop 1
	v_cndmask_b32_e64 v0, v0, v2, s[0:1]
	v_cndmask_b32_e32 v2, 0, v60, vcc
	v_sub_f32_e32 v0, v0, v2
	v_sub_f32_e32 v0, v1, v0
	v_fmamk_f32 v78, v0, 0x3d800000, v76
	ds_read_b128 v[240:243], v5 offset:704
	ds_read_b128 v[244:247], v5 offset:720
	ds_read_b128 v[248:251], v5 offset:736
	ds_read_b128 v[252:255], v5 offset:752
	s_waitcnt lgkmcnt(4)
	v_fma_f32 v79, v65, v210, v69
	v_fmac_f32_e32 v79, v66, v211
	v_fmac_f32_e32 v79, v67, v212
	v_fmac_f32_e32 v79, v68, v213
	v_fmac_f32_e32 v79, v55, v214
	v_fmac_f32_e32 v79, v62, v215
	v_fmac_f32_e32 v79, v63, v216
	v_fmac_f32_e32 v79, v64, v217
	v_fmac_f32_e32 v79, v52, v218
	v_fmac_f32_e32 v79, v53, v219
	v_fmac_f32_e32 v79, v50, v220
	v_fmac_f32_e32 v79, v51, v221
	v_pk_mul_f32 v[0:1], v[48:49], v[222:223]
	s_nop 0
	v_add_f32_e32 v0, v79, v0
	v_add_f32_e32 v79, v0, v1
	v_pk_mul_f32 v[0:1], v[46:47], v[224:225]
	s_nop 0
	v_add_f32_e32 v0, v79, v0
	v_add_f32_e32 v0, v0, v1
	v_min_f32_e32 v1, 0, v0
	v_mul_f32_e64 v0, |v0|, s11
	v_exp_f32_e32 v0, v0
	s_nop 0
	v_add_f32_e32 v0, 1.0, v0
	v_cmp_gt_f32_e32 vcc, s12, v0
	s_nop 1
	v_cndmask_b32_e64 v2, 0, 32, vcc
	v_ldexp_f32 v0, v0, v2
	v_log_f32_e32 v0, v0
	s_nop 0
	v_mul_f32_e32 v2, 0x3f317217, v0
	v_fma_f32 v2, v0, s13, -v2
	v_fmac_f32_e32 v2, 0x3377d1cf, v0
	v_fmac_f32_e32 v2, 0x3f317217, v0
	v_cmp_lt_f32_e64 s[0:1], |v0|, s36
	s_nop 1
	v_cndmask_b32_e64 v0, v0, v2, s[0:1]
	v_cndmask_b32_e32 v2, 0, v60, vcc
	v_sub_f32_e32 v0, v0, v2
	v_sub_f32_e32 v0, v1, v0
	v_fmamk_f32 v79, v0, 0x3d800000, v78
	ds_read_b128 v[210:213], v5 offset:768
	ds_read_b128 v[214:217], v5 offset:784
	ds_read_b128 v[218:221], v5 offset:800
	ds_read_b128 v[222:225], v5 offset:816
	s_waitcnt lgkmcnt(4)
	v_fma_f32 v80, v65, v240, v69
	v_fmac_f32_e32 v80, v66, v241
	v_fmac_f32_e32 v80, v67, v242
	v_fmac_f32_e32 v80, v68, v243
	v_fmac_f32_e32 v80, v55, v244
	v_fmac_f32_e32 v80, v62, v245
	v_fmac_f32_e32 v80, v63, v246
	v_fmac_f32_e32 v80, v64, v247
	v_fmac_f32_e32 v80, v52, v248
	v_fmac_f32_e32 v80, v53, v249
	v_fmac_f32_e32 v80, v50, v250
	v_fmac_f32_e32 v80, v51, v251
	v_pk_mul_f32 v[0:1], v[48:49], v[252:253]
	s_nop 0
	v_add_f32_e32 v0, v80, v0
	v_add_f32_e32 v80, v0, v1
	v_pk_mul_f32 v[0:1], v[46:47], v[254:255]
	s_nop 0
	v_add_f32_e32 v0, v80, v0
	v_add_f32_e32 v0, v0, v1
	v_min_f32_e32 v1, 0, v0
	v_mul_f32_e64 v0, |v0|, s11
	v_exp_f32_e32 v0, v0
	s_nop 0
	v_add_f32_e32 v0, 1.0, v0
	v_cmp_gt_f32_e32 vcc, s12, v0
	s_nop 1
	v_cndmask_b32_e64 v2, 0, 32, vcc
	v_ldexp_f32 v0, v0, v2
	v_log_f32_e32 v0, v0
	s_nop 0
	v_mul_f32_e32 v2, 0x3f317217, v0
	v_fma_f32 v2, v0, s13, -v2
	v_fmac_f32_e32 v2, 0x3377d1cf, v0
	v_fmac_f32_e32 v2, 0x3f317217, v0
	v_cmp_lt_f32_e64 s[0:1], |v0|, s36
	s_nop 1
	v_cndmask_b32_e64 v0, v0, v2, s[0:1]
	v_cndmask_b32_e32 v2, 0, v60, vcc
	v_sub_f32_e32 v0, v0, v2
	v_sub_f32_e32 v0, v1, v0
	v_fmamk_f32 v80, v0, 0x3d800000, v79
	ds_read_b128 v[240:243], v5 offset:832
	ds_read_b128 v[244:247], v5 offset:848
	ds_read_b128 v[248:251], v5 offset:864
	ds_read_b128 v[252:255], v5 offset:880
	s_waitcnt lgkmcnt(4)
	v_fma_f32 v81, v65, v210, v69
	v_fmac_f32_e32 v81, v66, v211
	v_fmac_f32_e32 v81, v67, v212
	v_fmac_f32_e32 v81, v68, v213
	v_fmac_f32_e32 v81, v55, v214
	v_fmac_f32_e32 v81, v62, v215
	v_fmac_f32_e32 v81, v63, v216
	v_fmac_f32_e32 v81, v64, v217
	v_fmac_f32_e32 v81, v52, v218
	v_fmac_f32_e32 v81, v53, v219
	v_fmac_f32_e32 v81, v50, v220
	v_fmac_f32_e32 v81, v51, v221
	v_pk_mul_f32 v[0:1], v[48:49], v[222:223]
	s_nop 0
	v_add_f32_e32 v0, v81, v0
	v_add_f32_e32 v81, v0, v1
	v_pk_mul_f32 v[0:1], v[46:47], v[224:225]
	s_nop 0
	v_add_f32_e32 v0, v81, v0
	v_add_f32_e32 v0, v0, v1
	v_min_f32_e32 v1, 0, v0
	v_mul_f32_e64 v0, |v0|, s11
	v_exp_f32_e32 v0, v0
	s_nop 0
	v_add_f32_e32 v0, 1.0, v0
	v_cmp_gt_f32_e32 vcc, s12, v0
	s_nop 1
	v_cndmask_b32_e64 v2, 0, 32, vcc
	v_ldexp_f32 v0, v0, v2
	v_log_f32_e32 v0, v0
	s_nop 0
	v_mul_f32_e32 v2, 0x3f317217, v0
	v_fma_f32 v2, v0, s13, -v2
	v_fmac_f32_e32 v2, 0x3377d1cf, v0
	v_fmac_f32_e32 v2, 0x3f317217, v0
	v_cmp_lt_f32_e64 s[0:1], |v0|, s36
	s_nop 1
	v_cndmask_b32_e64 v0, v0, v2, s[0:1]
	v_cndmask_b32_e32 v2, 0, v60, vcc
	v_sub_f32_e32 v0, v0, v2
	v_sub_f32_e32 v0, v1, v0
	v_fmamk_f32 v81, v0, 0x3d800000, v80
	ds_read_b128 v[210:213], v5 offset:896
	ds_read_b128 v[214:217], v5 offset:912
	ds_read_b128 v[218:221], v5 offset:928
	ds_read_b128 v[222:225], v5 offset:944
	s_waitcnt lgkmcnt(4)
; __device__ __forceinline__ float log_sigmoid(float x) { return fminf(x, 0.f) - __logf(1.f + __expf(-fabsf(x))); }
; __device__ __forceinline__ void gla_prep_item(LAS unsigned char* lds, int item, const bf16_t* Z, const float* W2, const float* Bg, bf16_t* KDT, float* DEC) {
;     ...
;     float bend = 0.f; float gv[64];
; #pragma unroll
;     for (int t = 0; t < 64; ++t) {
;         float x = bias;
; #pragma unroll
;         for (int r = 0; r < 16; ++r) x += zgs[t * 16 + r] * w[r];
;         gv[t] = log_sigmoid(x) * (1.f / 16.f); bend += gv[t];
;     }
	v_fma_f32 v82, v65, v240, v69
	v_fmac_f32_e32 v82, v66, v241
	v_fmac_f32_e32 v82, v67, v242
	v_fmac_f32_e32 v82, v68, v243
	v_fmac_f32_e32 v82, v55, v244
	v_fmac_f32_e32 v82, v62, v245
	v_fmac_f32_e32 v82, v63, v246
	v_fmac_f32_e32 v82, v64, v247
	v_fmac_f32_e32 v82, v52, v248
	v_fmac_f32_e32 v82, v53, v249
	v_fmac_f32_e32 v82, v50, v250
	v_fmac_f32_e32 v82, v51, v251
	v_pk_mul_f32 v[0:1], v[48:49], v[252:253]
	s_nop 0
	v_add_f32_e32 v0, v82, v0
	v_add_f32_e32 v82, v0, v1
	v_pk_mul_f32 v[0:1], v[46:47], v[254:255]
	s_nop 0
	v_add_f32_e32 v0, v82, v0
	v_add_f32_e32 v0, v0, v1
	v_min_f32_e32 v1, 0, v0
	v_mul_f32_e64 v0, |v0|, s11
	v_exp_f32_e32 v0, v0
	s_nop 0
	v_add_f32_e32 v0, 1.0, v0
	v_cmp_gt_f32_e32 vcc, s12, v0
	s_nop 1
	v_cndmask_b32_e64 v2, 0, 32, vcc
	v_ldexp_f32 v0, v0, v2
	v_log_f32_e32 v0, v0
	s_nop 0
	v_mul_f32_e32 v2, 0x3f317217, v0
	v_fma_f32 v2, v0, s13, -v2
	v_fmac_f32_e32 v2, 0x3377d1cf, v0
	v_fmac_f32_e32 v2, 0x3f317217, v0
	v_cmp_lt_f32_e64 s[0:1], |v0|, s36
	s_nop 1
	v_cndmask_b32_e64 v0, v0, v2, s[0:1]
	v_cndmask_b32_e32 v2, 0, v60, vcc
	v_sub_f32_e32 v0, v0, v2
	v_sub_f32_e32 v0, v1, v0
	v_fmamk_f32 v82, v0, 0x3d800000, v81
	ds_read_b128 v[240:243], v5 offset:960
	ds_read_b128 v[244:247], v5 offset:976
	ds_read_b128 v[248:251], v5 offset:992
	ds_read_b128 v[252:255], v5 offset:1008
	s_waitcnt lgkmcnt(4)
	v_fma_f32 v83, v65, v210, v69
	v_fmac_f32_e32 v83, v66, v211
	v_fmac_f32_e32 v83, v67, v212
	v_fmac_f32_e32 v83, v68, v213
	v_fmac_f32_e32 v83, v55, v214
	v_fmac_f32_e32 v83, v62, v215
	v_fmac_f32_e32 v83, v63, v216
	v_fmac_f32_e32 v83, v64, v217
	v_fmac_f32_e32 v83, v52, v218
	v_fmac_f32_e32 v83, v53, v219
	v_fmac_f32_e32 v83, v50, v220
	v_fmac_f32_e32 v83, v51, v221
	v_pk_mul_f32 v[0:1], v[48:49], v[222:223]
	s_nop 0
	v_add_f32_e32 v0, v83, v0
	v_add_f32_e32 v83, v0, v1
	v_pk_mul_f32 v[0:1], v[46:47], v[224:225]
	s_nop 0
	v_add_f32_e32 v0, v83, v0
	v_add_f32_e32 v0, v0, v1
	v_min_f32_e32 v1, 0, v0
	v_mul_f32_e64 v0, |v0|, s11
	v_exp_f32_e32 v0, v0
	s_nop 0
	v_add_f32_e32 v0, 1.0, v0
	v_cmp_gt_f32_e32 vcc, s12, v0
	s_nop 1
	v_cndmask_b32_e64 v2, 0, 32, vcc
	v_ldexp_f32 v0, v0, v2
	v_log_f32_e32 v0, v0
	s_nop 0
	v_mul_f32_e32 v2, 0x3f317217, v0
	v_fma_f32 v2, v0, s13, -v2
	v_fmac_f32_e32 v2, 0x3377d1cf, v0
	v_fmac_f32_e32 v2, 0x3f317217, v0
	v_cmp_lt_f32_e64 s[0:1], |v0|, s36
	s_nop 1
	v_cndmask_b32_e64 v0, v0, v2, s[0:1]
	v_cndmask_b32_e32 v2, 0, v60, vcc
	v_sub_f32_e32 v0, v0, v2
	v_sub_f32_e32 v0, v1, v0
	v_fmamk_f32 v83, v0, 0x3d800000, v82
	ds_read_b128 v[210:213], v5 offset:1024
	ds_read_b128 v[214:217], v5 offset:1040
	ds_read_b128 v[218:221], v5 offset:1056
	ds_read_b128 v[222:225], v5 offset:1072
	s_waitcnt lgkmcnt(4)
	v_fma_f32 v84, v65, v240, v69
	v_fmac_f32_e32 v84, v66, v241
	v_fmac_f32_e32 v84, v67, v242
	v_fmac_f32_e32 v84, v68, v243
	v_fmac_f32_e32 v84, v55, v244
	v_fmac_f32_e32 v84, v62, v245
	v_fmac_f32_e32 v84, v63, v246
	v_fmac_f32_e32 v84, v64, v247
	v_fmac_f32_e32 v84, v52, v248
	v_fmac_f32_e32 v84, v53, v249
	v_fmac_f32_e32 v84, v50, v250
	v_fmac_f32_e32 v84, v51, v251
	v_pk_mul_f32 v[0:1], v[48:49], v[252:253]
	s_nop 0
	v_add_f32_e32 v0, v84, v0
	v_add_f32_e32 v84, v0, v1
	v_pk_mul_f32 v[0:1], v[46:47], v[254:255]
	s_nop 0
	v_add_f32_e32 v0, v84, v0
	v_add_f32_e32 v0, v0, v1
	v_min_f32_e32 v1, 0, v0
	v_mul_f32_e64 v0, |v0|, s11
	v_exp_f32_e32 v0, v0
	s_nop 0
	v_add_f32_e32 v0, 1.0, v0
	v_cmp_gt_f32_e32 vcc, s12, v0
	s_nop 1
	v_cndmask_b32_e64 v2, 0, 32, vcc
	v_ldexp_f32 v0, v0, v2
	v_log_f32_e32 v0, v0
	s_nop 0
	v_mul_f32_e32 v2, 0x3f317217, v0
	v_fma_f32 v2, v0, s13, -v2
	v_fmac_f32_e32 v2, 0x3377d1cf, v0
	v_fmac_f32_e32 v2, 0x3f317217, v0
	v_cmp_lt_f32_e64 s[0:1], |v0|, s36
	s_nop 1
	v_cndmask_b32_e64 v0, v0, v2, s[0:1]
	v_cndmask_b32_e32 v2, 0, v60, vcc
	v_sub_f32_e32 v0, v0, v2
	v_sub_f32_e32 v0, v1, v0
	v_fmamk_f32 v84, v0, 0x3d800000, v83
	ds_read_b128 v[240:243], v5 offset:1088
	ds_read_b128 v[244:247], v5 offset:1104
	ds_read_b128 v[248:251], v5 offset:1120
	ds_read_b128 v[252:255], v5 offset:1136
	s_waitcnt lgkmcnt(4)
	v_fma_f32 v85, v65, v210, v69
	v_fmac_f32_e32 v85, v66, v211
	v_fmac_f32_e32 v85, v67, v212
	v_fmac_f32_e32 v85, v68, v213
	v_fmac_f32_e32 v85, v55, v214
	v_fmac_f32_e32 v85, v62, v215
	v_fmac_f32_e32 v85, v63, v216
	v_fmac_f32_e32 v85, v64, v217
	v_fmac_f32_e32 v85, v52, v218
	v_fmac_f32_e32 v85, v53, v219
	v_fmac_f32_e32 v85, v50, v220
	v_fmac_f32_e32 v85, v51, v221
	v_pk_mul_f32 v[0:1], v[48:49], v[222:223]
	s_nop 0
	v_add_f32_e32 v0, v85, v0
	v_add_f32_e32 v85, v0, v1
	v_pk_mul_f32 v[0:1], v[46:47], v[224:225]
	s_nop 0
	v_add_f32_e32 v0, v85, v0
	v_add_f32_e32 v0, v0, v1
	v_min_f32_e32 v1, 0, v0
	v_mul_f32_e64 v0, |v0|, s11
	v_exp_f32_e32 v0, v0
	s_nop 0
	v_add_f32_e32 v0, 1.0, v0
	v_cmp_gt_f32_e32 vcc, s12, v0
	s_nop 1
	v_cndmask_b32_e64 v2, 0, 32, vcc
	v_ldexp_f32 v0, v0, v2
	v_log_f32_e32 v0, v0
	s_nop 0
	v_mul_f32_e32 v2, 0x3f317217, v0
	v_fma_f32 v2, v0, s13, -v2
	v_fmac_f32_e32 v2, 0x3377d1cf, v0
	v_fmac_f32_e32 v2, 0x3f317217, v0
	v_cmp_lt_f32_e64 s[0:1], |v0|, s36
	s_nop 1
	v_cndmask_b32_e64 v0, v0, v2, s[0:1]
	v_cndmask_b32_e32 v2, 0, v60, vcc
	v_sub_f32_e32 v0, v0, v2
	v_sub_f32_e32 v0, v1, v0
	v_fmamk_f32 v85, v0, 0x3d800000, v84
	ds_read_b128 v[210:213], v5 offset:1152
	ds_read_b128 v[214:217], v5 offset:1168
	ds_read_b128 v[218:221], v5 offset:1184
	ds_read_b128 v[222:225], v5 offset:1200
	s_waitcnt lgkmcnt(4)
; __device__ __forceinline__ float log_sigmoid(float x) { return fminf(x, 0.f) - __logf(1.f + __expf(-fabsf(x))); }
; __device__ __forceinline__ void gla_prep_item(LAS unsigned char* lds, int item, const bf16_t* Z, const float* W2, const float* Bg, bf16_t* KDT, float* DEC) {
;     ...
;     float bend = 0.f; float gv[64];
; #pragma unroll
;     for (int t = 0; t < 64; ++t) {
;         float x = bias;
; #pragma unroll
;         for (int r = 0; r < 16; ++r) x += zgs[t * 16 + r] * w[r];
;         gv[t] = log_sigmoid(x) * (1.f / 16.f); bend += gv[t];
;     }
	v_fma_f32 v86, v65, v240, v69
	v_fmac_f32_e32 v86, v66, v241
	v_fmac_f32_e32 v86, v67, v242
	v_fmac_f32_e32 v86, v68, v243
	v_fmac_f32_e32 v86, v55, v244
	v_fmac_f32_e32 v86, v62, v245
	v_fmac_f32_e32 v86, v63, v246
	v_fmac_f32_e32 v86, v64, v247
	v_fmac_f32_e32 v86, v52, v248
	v_fmac_f32_e32 v86, v53, v249
	v_fmac_f32_e32 v86, v50, v250
	v_fmac_f32_e32 v86, v51, v251
	v_pk_mul_f32 v[0:1], v[48:49], v[252:253]
	s_nop 0
	v_add_f32_e32 v0, v86, v0
	v_add_f32_e32 v86, v0, v1
	v_pk_mul_f32 v[0:1], v[46:47], v[254:255]
	s_nop 0
	v_add_f32_e32 v0, v86, v0
	v_add_f32_e32 v0, v0, v1
	v_min_f32_e32 v1, 0, v0
	v_mul_f32_e64 v0, |v0|, s11
	v_exp_f32_e32 v0, v0
	s_nop 0
	v_add_f32_e32 v0, 1.0, v0
	v_cmp_gt_f32_e32 vcc, s12, v0
	s_nop 1
	v_cndmask_b32_e64 v2, 0, 32, vcc
	v_ldexp_f32 v0, v0, v2
	v_log_f32_e32 v0, v0
	s_nop 0
	v_mul_f32_e32 v2, 0x3f317217, v0
	v_fma_f32 v2, v0, s13, -v2
	v_fmac_f32_e32 v2, 0x3377d1cf, v0
	v_fmac_f32_e32 v2, 0x3f317217, v0
	v_cmp_lt_f32_e64 s[0:1], |v0|, s36
	s_nop 1
	v_cndmask_b32_e64 v0, v0, v2, s[0:1]
	v_cndmask_b32_e32 v2, 0, v60, vcc
	v_sub_f32_e32 v0, v0, v2
	v_sub_f32_e32 v0, v1, v0
	v_fmamk_f32 v86, v0, 0x3d800000, v85
	ds_read_b128 v[240:243], v5 offset:1216
	ds_read_b128 v[244:247], v5 offset:1232
	ds_read_b128 v[248:251], v5 offset:1248
	ds_read_b128 v[252:255], v5 offset:1264
	s_waitcnt lgkmcnt(4)
	v_fma_f32 v87, v65, v210, v69
	v_fmac_f32_e32 v87, v66, v211
	v_fmac_f32_e32 v87, v67, v212
	v_fmac_f32_e32 v87, v68, v213
	v_fmac_f32_e32 v87, v55, v214
	v_fmac_f32_e32 v87, v62, v215
	v_fmac_f32_e32 v87, v63, v216
	v_fmac_f32_e32 v87, v64, v217
	v_fmac_f32_e32 v87, v52, v218
	v_fmac_f32_e32 v87, v53, v219
	v_fmac_f32_e32 v87, v50, v220
	v_fmac_f32_e32 v87, v51, v221
	v_pk_mul_f32 v[0:1], v[48:49], v[222:223]
	s_nop 0
	v_add_f32_e32 v0, v87, v0
	v_add_f32_e32 v87, v0, v1
	v_pk_mul_f32 v[0:1], v[46:47], v[224:225]
	s_nop 0
	v_add_f32_e32 v0, v87, v0
	v_add_f32_e32 v0, v0, v1
	v_min_f32_e32 v1, 0, v0
	v_mul_f32_e64 v0, |v0|, s11
	v_exp_f32_e32 v0, v0
	s_nop 0
	v_add_f32_e32 v0, 1.0, v0
	v_cmp_gt_f32_e32 vcc, s12, v0
	s_nop 1
	v_cndmask_b32_e64 v2, 0, 32, vcc
	v_ldexp_f32 v0, v0, v2
	v_log_f32_e32 v0, v0
	s_nop 0
	v_mul_f32_e32 v2, 0x3f317217, v0
	v_fma_f32 v2, v0, s13, -v2
	v_fmac_f32_e32 v2, 0x3377d1cf, v0
	v_fmac_f32_e32 v2, 0x3f317217, v0
	v_cmp_lt_f32_e64 s[0:1], |v0|, s36
	s_nop 1
	v_cndmask_b32_e64 v0, v0, v2, s[0:1]
	v_cndmask_b32_e32 v2, 0, v60, vcc
	v_sub_f32_e32 v0, v0, v2
	v_sub_f32_e32 v0, v1, v0
	v_fmamk_f32 v87, v0, 0x3d800000, v86
	ds_read_b128 v[210:213], v5 offset:1280
	ds_read_b128 v[214:217], v5 offset:1296
	ds_read_b128 v[218:221], v5 offset:1312
	ds_read_b128 v[222:225], v5 offset:1328
	s_waitcnt lgkmcnt(4)
	v_fma_f32 v88, v65, v240, v69
	v_fmac_f32_e32 v88, v66, v241
	v_fmac_f32_e32 v88, v67, v242
	v_fmac_f32_e32 v88, v68, v243
	v_fmac_f32_e32 v88, v55, v244
	v_fmac_f32_e32 v88, v62, v245
	v_fmac_f32_e32 v88, v63, v246
	v_fmac_f32_e32 v88, v64, v247
	v_fmac_f32_e32 v88, v52, v248
	v_fmac_f32_e32 v88, v53, v249
	v_fmac_f32_e32 v88, v50, v250
	v_fmac_f32_e32 v88, v51, v251
	v_pk_mul_f32 v[0:1], v[48:49], v[252:253]
	s_nop 0
	v_add_f32_e32 v0, v88, v0
	v_add_f32_e32 v88, v0, v1
	v_pk_mul_f32 v[0:1], v[46:47], v[254:255]
	s_nop 0
	v_add_f32_e32 v0, v88, v0
	v_add_f32_e32 v0, v0, v1
	v_min_f32_e32 v1, 0, v0
	v_mul_f32_e64 v0, |v0|, s11
	v_exp_f32_e32 v0, v0
	s_nop 0
	v_add_f32_e32 v0, 1.0, v0
	v_cmp_gt_f32_e32 vcc, s12, v0
	s_nop 1
	v_cndmask_b32_e64 v2, 0, 32, vcc
	v_ldexp_f32 v0, v0, v2
	v_log_f32_e32 v0, v0
	s_nop 0
	v_mul_f32_e32 v2, 0x3f317217, v0
	v_fma_f32 v2, v0, s13, -v2
	v_fmac_f32_e32 v2, 0x3377d1cf, v0
	v_fmac_f32_e32 v2, 0x3f317217, v0
	v_cmp_lt_f32_e64 s[0:1], |v0|, s36
	s_nop 1
	v_cndmask_b32_e64 v0, v0, v2, s[0:1]
	v_cndmask_b32_e32 v2, 0, v60, vcc
	v_sub_f32_e32 v0, v0, v2
	v_sub_f32_e32 v0, v1, v0
	v_fmamk_f32 v88, v0, 0x3d800000, v87
	ds_read_b128 v[240:243], v5 offset:1344
	ds_read_b128 v[244:247], v5 offset:1360
	ds_read_b128 v[248:251], v5 offset:1376
	ds_read_b128 v[252:255], v5 offset:1392
	s_waitcnt lgkmcnt(4)
	v_fma_f32 v89, v65, v210, v69
	v_fmac_f32_e32 v89, v66, v211
	v_fmac_f32_e32 v89, v67, v212
	v_fmac_f32_e32 v89, v68, v213
	v_fmac_f32_e32 v89, v55, v214
	v_fmac_f32_e32 v89, v62, v215
	v_fmac_f32_e32 v89, v63, v216
	v_fmac_f32_e32 v89, v64, v217
	v_fmac_f32_e32 v89, v52, v218
	v_fmac_f32_e32 v89, v53, v219
	v_fmac_f32_e32 v89, v50, v220
	v_fmac_f32_e32 v89, v51, v221
	v_pk_mul_f32 v[0:1], v[48:49], v[222:223]
	s_nop 0
	v_add_f32_e32 v0, v89, v0
	v_add_f32_e32 v89, v0, v1
	v_pk_mul_f32 v[0:1], v[46:47], v[224:225]
	s_nop 0
	v_add_f32_e32 v0, v89, v0
	v_add_f32_e32 v0, v0, v1
	v_min_f32_e32 v1, 0, v0
	v_mul_f32_e64 v0, |v0|, s11
	v_exp_f32_e32 v0, v0
	s_nop 0
	v_add_f32_e32 v0, 1.0, v0
	v_cmp_gt_f32_e32 vcc, s12, v0
	s_nop 1
	v_cndmask_b32_e64 v2, 0, 32, vcc
	v_ldexp_f32 v0, v0, v2
	v_log_f32_e32 v0, v0
	s_nop 0
	v_mul_f32_e32 v2, 0x3f317217, v0
	v_fma_f32 v2, v0, s13, -v2
	v_fmac_f32_e32 v2, 0x3377d1cf, v0
	v_fmac_f32_e32 v2, 0x3f317217, v0
	v_cmp_lt_f32_e64 s[0:1], |v0|, s36
	s_nop 1
	v_cndmask_b32_e64 v0, v0, v2, s[0:1]
	v_cndmask_b32_e32 v2, 0, v60, vcc
	v_sub_f32_e32 v0, v0, v2
	v_sub_f32_e32 v0, v1, v0
	v_fmamk_f32 v89, v0, 0x3d800000, v88
	ds_read_b128 v[210:213], v5 offset:1408
	ds_read_b128 v[214:217], v5 offset:1424
	ds_read_b128 v[218:221], v5 offset:1440
	ds_read_b128 v[222:225], v5 offset:1456
	s_waitcnt lgkmcnt(4)
; __device__ __forceinline__ float log_sigmoid(float x) { return fminf(x, 0.f) - __logf(1.f + __expf(-fabsf(x))); }
; __device__ __forceinline__ void gla_prep_item(LAS unsigned char* lds, int item, const bf16_t* Z, const float* W2, const float* Bg, bf16_t* KDT, float* DEC) {
;     ...
;     float bend = 0.f; float gv[64];
; #pragma unroll
;     for (int t = 0; t < 64; ++t) {
;         float x = bias;
; #pragma unroll
;         for (int r = 0; r < 16; ++r) x += zgs[t * 16 + r] * w[r];
;         gv[t] = log_sigmoid(x) * (1.f / 16.f); bend += gv[t];
;     }
	v_fma_f32 v90, v65, v240, v69
	v_fmac_f32_e32 v90, v66, v241
	v_fmac_f32_e32 v90, v67, v242
	v_fmac_f32_e32 v90, v68, v243
	v_fmac_f32_e32 v90, v55, v244
	v_fmac_f32_e32 v90, v62, v245
	v_fmac_f32_e32 v90, v63, v246
	v_fmac_f32_e32 v90, v64, v247
	v_fmac_f32_e32 v90, v52, v248
	v_fmac_f32_e32 v90, v53, v249
	v_fmac_f32_e32 v90, v50, v250
	v_fmac_f32_e32 v90, v51, v251
	v_pk_mul_f32 v[0:1], v[48:49], v[252:253]
	s_nop 0
	v_add_f32_e32 v0, v90, v0
	v_add_f32_e32 v90, v0, v1
	v_pk_mul_f32 v[0:1], v[46:47], v[254:255]
	s_nop 0
	v_add_f32_e32 v0, v90, v0
	v_add_f32_e32 v0, v0, v1
	v_min_f32_e32 v1, 0, v0
	v_mul_f32_e64 v0, |v0|, s11
	v_exp_f32_e32 v0, v0
	s_nop 0
	v_add_f32_e32 v0, 1.0, v0
	v_cmp_gt_f32_e32 vcc, s12, v0
	s_nop 1
	v_cndmask_b32_e64 v2, 0, 32, vcc
	v_ldexp_f32 v0, v0, v2
	v_log_f32_e32 v0, v0
	s_nop 0
	v_mul_f32_e32 v2, 0x3f317217, v0
	v_fma_f32 v2, v0, s13, -v2
	v_fmac_f32_e32 v2, 0x3377d1cf, v0
	v_fmac_f32_e32 v2, 0x3f317217, v0
	v_cmp_lt_f32_e64 s[0:1], |v0|, s36
	s_nop 1
	v_cndmask_b32_e64 v0, v0, v2, s[0:1]
	v_cndmask_b32_e32 v2, 0, v60, vcc
	v_sub_f32_e32 v0, v0, v2
	v_sub_f32_e32 v0, v1, v0
	v_fmamk_f32 v90, v0, 0x3d800000, v89
	ds_read_b128 v[240:243], v5 offset:1472
	ds_read_b128 v[244:247], v5 offset:1488
	ds_read_b128 v[248:251], v5 offset:1504
	ds_read_b128 v[252:255], v5 offset:1520
	s_waitcnt lgkmcnt(4)
	v_fma_f32 v91, v65, v210, v69
	v_fmac_f32_e32 v91, v66, v211
	v_fmac_f32_e32 v91, v67, v212
	v_fmac_f32_e32 v91, v68, v213
	v_fmac_f32_e32 v91, v55, v214
	v_fmac_f32_e32 v91, v62, v215
	v_fmac_f32_e32 v91, v63, v216
	v_fmac_f32_e32 v91, v64, v217
	v_fmac_f32_e32 v91, v52, v218
	v_fmac_f32_e32 v91, v53, v219
	v_fmac_f32_e32 v91, v50, v220
	v_fmac_f32_e32 v91, v51, v221
	v_pk_mul_f32 v[0:1], v[48:49], v[222:223]
	s_nop 0
	v_add_f32_e32 v0, v91, v0
	v_add_f32_e32 v91, v0, v1
	v_pk_mul_f32 v[0:1], v[46:47], v[224:225]
	s_nop 0
	v_add_f32_e32 v0, v91, v0
	v_add_f32_e32 v0, v0, v1
	v_min_f32_e32 v1, 0, v0
	v_mul_f32_e64 v0, |v0|, s11
	v_exp_f32_e32 v0, v0
	s_nop 0
	v_add_f32_e32 v0, 1.0, v0
	v_cmp_gt_f32_e32 vcc, s12, v0
	s_nop 1
	v_cndmask_b32_e64 v2, 0, 32, vcc
	v_ldexp_f32 v0, v0, v2
	v_log_f32_e32 v0, v0
	s_nop 0
	v_mul_f32_e32 v2, 0x3f317217, v0
	v_fma_f32 v2, v0, s13, -v2
	v_fmac_f32_e32 v2, 0x3377d1cf, v0
	v_fmac_f32_e32 v2, 0x3f317217, v0
	v_cmp_lt_f32_e64 s[0:1], |v0|, s36
	s_nop 1
	v_cndmask_b32_e64 v0, v0, v2, s[0:1]
	v_cndmask_b32_e32 v2, 0, v60, vcc
	v_sub_f32_e32 v0, v0, v2
	v_sub_f32_e32 v0, v1, v0
	v_fmamk_f32 v91, v0, 0x3d800000, v90
	ds_read_b128 v[210:213], v5 offset:1536
	ds_read_b128 v[214:217], v5 offset:1552
	ds_read_b128 v[218:221], v5 offset:1568
	ds_read_b128 v[222:225], v5 offset:1584
	s_waitcnt lgkmcnt(4)
	v_fma_f32 v92, v65, v240, v69
	v_fmac_f32_e32 v92, v66, v241
	v_fmac_f32_e32 v92, v67, v242
	v_fmac_f32_e32 v92, v68, v243
	v_fmac_f32_e32 v92, v55, v244
	v_fmac_f32_e32 v92, v62, v245
	v_fmac_f32_e32 v92, v63, v246
	v_fmac_f32_e32 v92, v64, v247
	v_fmac_f32_e32 v92, v52, v248
	v_fmac_f32_e32 v92, v53, v249
	v_fmac_f32_e32 v92, v50, v250
	v_fmac_f32_e32 v92, v51, v251
	v_pk_mul_f32 v[0:1], v[48:49], v[252:253]
	s_nop 0
	v_add_f32_e32 v0, v92, v0
	v_add_f32_e32 v92, v0, v1
	v_pk_mul_f32 v[0:1], v[46:47], v[254:255]
	s_nop 0
	v_add_f32_e32 v0, v92, v0
	v_add_f32_e32 v0, v0, v1
	v_min_f32_e32 v1, 0, v0
	v_mul_f32_e64 v0, |v0|, s11
	v_exp_f32_e32 v0, v0
	s_nop 0
	v_add_f32_e32 v0, 1.0, v0
	v_cmp_gt_f32_e32 vcc, s12, v0
	s_nop 1
	v_cndmask_b32_e64 v2, 0, 32, vcc
	v_ldexp_f32 v0, v0, v2
	v_log_f32_e32 v0, v0
	s_nop 0
	v_mul_f32_e32 v2, 0x3f317217, v0
	v_fma_f32 v2, v0, s13, -v2
	v_fmac_f32_e32 v2, 0x3377d1cf, v0
	v_fmac_f32_e32 v2, 0x3f317217, v0
	v_cmp_lt_f32_e64 s[0:1], |v0|, s36
	s_nop 1
	v_cndmask_b32_e64 v0, v0, v2, s[0:1]
	v_cndmask_b32_e32 v2, 0, v60, vcc
	v_sub_f32_e32 v0, v0, v2
	v_sub_f32_e32 v0, v1, v0
	v_fmamk_f32 v92, v0, 0x3d800000, v91
	ds_read_b128 v[240:243], v5 offset:1600
	ds_read_b128 v[244:247], v5 offset:1616
	ds_read_b128 v[248:251], v5 offset:1632
	ds_read_b128 v[252:255], v5 offset:1648
	s_waitcnt lgkmcnt(4)
	v_fma_f32 v93, v65, v210, v69
	v_fmac_f32_e32 v93, v66, v211
	v_fmac_f32_e32 v93, v67, v212
	v_fmac_f32_e32 v93, v68, v213
	v_fmac_f32_e32 v93, v55, v214
	v_fmac_f32_e32 v93, v62, v215
	v_fmac_f32_e32 v93, v63, v216
	v_fmac_f32_e32 v93, v64, v217
	v_fmac_f32_e32 v93, v52, v218
	v_fmac_f32_e32 v93, v53, v219
	v_fmac_f32_e32 v93, v50, v220
	v_fmac_f32_e32 v93, v51, v221
	v_pk_mul_f32 v[0:1], v[48:49], v[222:223]
	s_nop 0
	v_add_f32_e32 v0, v93, v0
	v_add_f32_e32 v93, v0, v1
	v_pk_mul_f32 v[0:1], v[46:47], v[224:225]
	s_nop 0
	v_add_f32_e32 v0, v93, v0
	v_add_f32_e32 v0, v0, v1
	v_min_f32_e32 v1, 0, v0
	v_mul_f32_e64 v0, |v0|, s11
	v_exp_f32_e32 v0, v0
	s_nop 0
	v_add_f32_e32 v0, 1.0, v0
	v_cmp_gt_f32_e32 vcc, s12, v0
	s_nop 1
	v_cndmask_b32_e64 v2, 0, 32, vcc
	v_ldexp_f32 v0, v0, v2
	v_log_f32_e32 v0, v0
	s_nop 0
	v_mul_f32_e32 v2, 0x3f317217, v0
	v_fma_f32 v2, v0, s13, -v2
	v_fmac_f32_e32 v2, 0x3377d1cf, v0
	v_fmac_f32_e32 v2, 0x3f317217, v0
	v_cmp_lt_f32_e64 s[0:1], |v0|, s36
	s_nop 1
	v_cndmask_b32_e64 v0, v0, v2, s[0:1]
	v_cndmask_b32_e32 v2, 0, v60, vcc
	v_sub_f32_e32 v0, v0, v2
	v_sub_f32_e32 v0, v1, v0
	v_fmamk_f32 v93, v0, 0x3d800000, v92
	ds_read_b128 v[210:213], v5 offset:1664
	ds_read_b128 v[214:217], v5 offset:1680
	ds_read_b128 v[218:221], v5 offset:1696
	ds_read_b128 v[222:225], v5 offset:1712
	s_waitcnt lgkmcnt(4)
; __device__ __forceinline__ float log_sigmoid(float x) { return fminf(x, 0.f) - __logf(1.f + __expf(-fabsf(x))); }
; __device__ __forceinline__ void gla_prep_item(LAS unsigned char* lds, int item, const bf16_t* Z, const float* W2, const float* Bg, bf16_t* KDT, float* DEC) {
;     ...
;     float bend = 0.f; float gv[64];
; #pragma unroll
;     for (int t = 0; t < 64; ++t) {
;         float x = bias;
; #pragma unroll
;         for (int r = 0; r < 16; ++r) x += zgs[t * 16 + r] * w[r];
;         gv[t] = log_sigmoid(x) * (1.f / 16.f); bend += gv[t];
;     }
	v_fma_f32 v94, v65, v240, v69
	v_fmac_f32_e32 v94, v66, v241
	v_fmac_f32_e32 v94, v67, v242
	v_fmac_f32_e32 v94, v68, v243
	v_fmac_f32_e32 v94, v55, v244
	v_fmac_f32_e32 v94, v62, v245
	v_fmac_f32_e32 v94, v63, v246
	v_fmac_f32_e32 v94, v64, v247
	v_fmac_f32_e32 v94, v52, v248
	v_fmac_f32_e32 v94, v53, v249
	v_fmac_f32_e32 v94, v50, v250
	v_fmac_f32_e32 v94, v51, v251
	v_pk_mul_f32 v[0:1], v[48:49], v[252:253]
	s_nop 0
	v_add_f32_e32 v0, v94, v0
	v_add_f32_e32 v94, v0, v1
	v_pk_mul_f32 v[0:1], v[46:47], v[254:255]
	s_nop 0
	v_add_f32_e32 v0, v94, v0
	v_add_f32_e32 v0, v0, v1
	v_min_f32_e32 v1, 0, v0
	v_mul_f32_e64 v0, |v0|, s11
	v_exp_f32_e32 v0, v0
	s_nop 0
	v_add_f32_e32 v0, 1.0, v0
	v_cmp_gt_f32_e32 vcc, s12, v0
	s_nop 1
	v_cndmask_b32_e64 v2, 0, 32, vcc
	v_ldexp_f32 v0, v0, v2
	v_log_f32_e32 v0, v0
	s_nop 0
	v_mul_f32_e32 v2, 0x3f317217, v0
	v_fma_f32 v2, v0, s13, -v2
	v_fmac_f32_e32 v2, 0x3377d1cf, v0
	v_fmac_f32_e32 v2, 0x3f317217, v0
	v_cmp_lt_f32_e64 s[0:1], |v0|, s36
	s_nop 1
	v_cndmask_b32_e64 v0, v0, v2, s[0:1]
	v_cndmask_b32_e32 v2, 0, v60, vcc
	v_sub_f32_e32 v0, v0, v2
	v_sub_f32_e32 v0, v1, v0
	v_fmamk_f32 v94, v0, 0x3d800000, v93
	ds_read_b128 v[240:243], v5 offset:1728
	ds_read_b128 v[244:247], v5 offset:1744
	ds_read_b128 v[248:251], v5 offset:1760
	ds_read_b128 v[252:255], v5 offset:1776
	s_waitcnt lgkmcnt(4)
	v_fma_f32 v95, v65, v210, v69
	v_fmac_f32_e32 v95, v66, v211
	v_fmac_f32_e32 v95, v67, v212
	v_fmac_f32_e32 v95, v68, v213
	v_fmac_f32_e32 v95, v55, v214
	v_fmac_f32_e32 v95, v62, v215
	v_fmac_f32_e32 v95, v63, v216
	v_fmac_f32_e32 v95, v64, v217
	v_fmac_f32_e32 v95, v52, v218
	v_fmac_f32_e32 v95, v53, v219
	v_fmac_f32_e32 v95, v50, v220
	v_fmac_f32_e32 v95, v51, v221
	v_pk_mul_f32 v[0:1], v[48:49], v[222:223]
	s_nop 0
	v_add_f32_e32 v0, v95, v0
	v_add_f32_e32 v95, v0, v1
	v_pk_mul_f32 v[0:1], v[46:47], v[224:225]
	s_nop 0
	v_add_f32_e32 v0, v95, v0
	v_add_f32_e32 v0, v0, v1
	v_min_f32_e32 v1, 0, v0
	v_mul_f32_e64 v0, |v0|, s11
	v_exp_f32_e32 v0, v0
	s_nop 0
	v_add_f32_e32 v0, 1.0, v0
	v_cmp_gt_f32_e32 vcc, s12, v0
	s_nop 1
	v_cndmask_b32_e64 v2, 0, 32, vcc
	v_ldexp_f32 v0, v0, v2
	v_log_f32_e32 v0, v0
	s_nop 0
	v_mul_f32_e32 v2, 0x3f317217, v0
	v_fma_f32 v2, v0, s13, -v2
	v_fmac_f32_e32 v2, 0x3377d1cf, v0
	v_fmac_f32_e32 v2, 0x3f317217, v0
	v_cmp_lt_f32_e64 s[0:1], |v0|, s36
	s_nop 1
	v_cndmask_b32_e64 v0, v0, v2, s[0:1]
	v_cndmask_b32_e32 v2, 0, v60, vcc
	v_sub_f32_e32 v0, v0, v2
	v_sub_f32_e32 v0, v1, v0
	v_fmamk_f32 v95, v0, 0x3d800000, v94
	ds_read_b128 v[210:213], v5 offset:1792
	ds_read_b128 v[214:217], v5 offset:1808
	ds_read_b128 v[218:221], v5 offset:1824
	ds_read_b128 v[222:225], v5 offset:1840
	s_waitcnt lgkmcnt(4)
	v_fma_f32 v96, v65, v240, v69
	v_fmac_f32_e32 v96, v66, v241
	v_fmac_f32_e32 v96, v67, v242
	v_fmac_f32_e32 v96, v68, v243
	v_fmac_f32_e32 v96, v55, v244
	v_fmac_f32_e32 v96, v62, v245
	v_fmac_f32_e32 v96, v63, v246
	v_fmac_f32_e32 v96, v64, v247
	v_fmac_f32_e32 v96, v52, v248
	v_fmac_f32_e32 v96, v53, v249
	v_fmac_f32_e32 v96, v50, v250
	v_fmac_f32_e32 v96, v51, v251
	v_pk_mul_f32 v[0:1], v[48:49], v[252:253]
	s_nop 0
	v_add_f32_e32 v0, v96, v0
	v_add_f32_e32 v96, v0, v1
	v_pk_mul_f32 v[0:1], v[46:47], v[254:255]
	s_nop 0
	v_add_f32_e32 v0, v96, v0
	v_add_f32_e32 v0, v0, v1
	v_min_f32_e32 v1, 0, v0
	v_mul_f32_e64 v0, |v0|, s11
	v_exp_f32_e32 v0, v0
	s_nop 0
	v_add_f32_e32 v0, 1.0, v0
	v_cmp_gt_f32_e32 vcc, s12, v0
	s_nop 1
	v_cndmask_b32_e64 v2, 0, 32, vcc
	v_ldexp_f32 v0, v0, v2
	v_log_f32_e32 v0, v0
	s_nop 0
	v_mul_f32_e32 v2, 0x3f317217, v0
	v_fma_f32 v2, v0, s13, -v2
	v_fmac_f32_e32 v2, 0x3377d1cf, v0
	v_fmac_f32_e32 v2, 0x3f317217, v0
	v_cmp_lt_f32_e64 s[0:1], |v0|, s36
	s_nop 1
	v_cndmask_b32_e64 v0, v0, v2, s[0:1]
	v_cndmask_b32_e32 v2, 0, v60, vcc
	v_sub_f32_e32 v0, v0, v2
	v_sub_f32_e32 v0, v1, v0
	v_fmamk_f32 v96, v0, 0x3d800000, v95
	ds_read_b128 v[240:243], v5 offset:1856
	ds_read_b128 v[244:247], v5 offset:1872
	ds_read_b128 v[248:251], v5 offset:1888
	ds_read_b128 v[252:255], v5 offset:1904
	s_waitcnt lgkmcnt(4)
	v_fma_f32 v97, v65, v210, v69
	v_fmac_f32_e32 v97, v66, v211
	v_fmac_f32_e32 v97, v67, v212
	v_fmac_f32_e32 v97, v68, v213
	v_fmac_f32_e32 v97, v55, v214
	v_fmac_f32_e32 v97, v62, v215
	v_fmac_f32_e32 v97, v63, v216
	v_fmac_f32_e32 v97, v64, v217
	v_fmac_f32_e32 v97, v52, v218
	v_fmac_f32_e32 v97, v53, v219
	v_fmac_f32_e32 v97, v50, v220
	v_fmac_f32_e32 v97, v51, v221
	v_pk_mul_f32 v[0:1], v[48:49], v[222:223]
	s_nop 0
	v_add_f32_e32 v0, v97, v0
	v_add_f32_e32 v97, v0, v1
	v_pk_mul_f32 v[0:1], v[46:47], v[224:225]
	s_nop 0
	v_add_f32_e32 v0, v97, v0
	v_add_f32_e32 v0, v0, v1
	v_min_f32_e32 v1, 0, v0
	v_mul_f32_e64 v0, |v0|, s11
	v_exp_f32_e32 v0, v0
	s_nop 0
	v_add_f32_e32 v0, 1.0, v0
	v_cmp_gt_f32_e32 vcc, s12, v0
	s_nop 1
	v_cndmask_b32_e64 v2, 0, 32, vcc
	v_ldexp_f32 v0, v0, v2
	v_log_f32_e32 v0, v0
	s_nop 0
	v_mul_f32_e32 v2, 0x3f317217, v0
	v_fma_f32 v2, v0, s13, -v2
	v_fmac_f32_e32 v2, 0x3377d1cf, v0
	v_fmac_f32_e32 v2, 0x3f317217, v0
	v_cmp_lt_f32_e64 s[0:1], |v0|, s36
	s_nop 1
	v_cndmask_b32_e64 v0, v0, v2, s[0:1]
	v_cndmask_b32_e32 v2, 0, v60, vcc
	v_sub_f32_e32 v0, v0, v2
	v_sub_f32_e32 v0, v1, v0
	v_fmamk_f32 v97, v0, 0x3d800000, v96
	ds_read_b128 v[210:213], v5 offset:1920
	ds_read_b128 v[214:217], v5 offset:1936
	ds_read_b128 v[218:221], v5 offset:1952
	ds_read_b128 v[222:225], v5 offset:1968
	s_waitcnt lgkmcnt(4)
; __device__ __forceinline__ float log_sigmoid(float x) { return fminf(x, 0.f) - __logf(1.f + __expf(-fabsf(x))); }
; __device__ __forceinline__ void gla_prep_item(LAS unsigned char* lds, int item, const bf16_t* Z, const float* W2, const float* Bg, bf16_t* KDT, float* DEC) {
;     ...
;     float bend = 0.f; float gv[64];
; #pragma unroll
;     for (int t = 0; t < 64; ++t) {
;         float x = bias;
; #pragma unroll
;         for (int r = 0; r < 16; ++r) x += zgs[t * 16 + r] * w[r];
;         gv[t] = log_sigmoid(x) * (1.f / 16.f); bend += gv[t];
;     }
	v_fma_f32 v98, v65, v240, v69
	v_fmac_f32_e32 v98, v66, v241
	v_fmac_f32_e32 v98, v67, v242
	v_fmac_f32_e32 v98, v68, v243
	v_fmac_f32_e32 v98, v55, v244
	v_fmac_f32_e32 v98, v62, v245
	v_fmac_f32_e32 v98, v63, v246
	v_fmac_f32_e32 v98, v64, v247
	v_fmac_f32_e32 v98, v52, v248
	v_fmac_f32_e32 v98, v53, v249
	v_fmac_f32_e32 v98, v50, v250
	v_fmac_f32_e32 v98, v51, v251
	v_pk_mul_f32 v[0:1], v[48:49], v[252:253]
	s_nop 0
	v_add_f32_e32 v0, v98, v0
	v_add_f32_e32 v98, v0, v1
	v_pk_mul_f32 v[0:1], v[46:47], v[254:255]
	s_nop 0
	v_add_f32_e32 v0, v98, v0
	v_add_f32_e32 v0, v0, v1
	v_min_f32_e32 v1, 0, v0
	v_mul_f32_e64 v0, |v0|, s11
	v_exp_f32_e32 v0, v0
	s_nop 0
	v_add_f32_e32 v0, 1.0, v0
	v_cmp_gt_f32_e32 vcc, s12, v0
	s_nop 1
	v_cndmask_b32_e64 v2, 0, 32, vcc
	v_ldexp_f32 v0, v0, v2
	v_log_f32_e32 v0, v0
	s_nop 0
	v_mul_f32_e32 v2, 0x3f317217, v0
	v_fma_f32 v2, v0, s13, -v2
	v_fmac_f32_e32 v2, 0x3377d1cf, v0
	v_fmac_f32_e32 v2, 0x3f317217, v0
	v_cmp_lt_f32_e64 s[0:1], |v0|, s36
	s_nop 1
	v_cndmask_b32_e64 v0, v0, v2, s[0:1]
	v_cndmask_b32_e32 v2, 0, v60, vcc
	v_sub_f32_e32 v0, v0, v2
	v_sub_f32_e32 v0, v1, v0
	v_fmamk_f32 v98, v0, 0x3d800000, v97
	ds_read_b128 v[240:243], v5 offset:1984
	ds_read_b128 v[244:247], v5 offset:2000
	ds_read_b128 v[248:251], v5 offset:2016
	ds_read_b128 v[252:255], v5 offset:2032
	s_waitcnt lgkmcnt(4)
	v_fma_f32 v99, v65, v210, v69
	v_fmac_f32_e32 v99, v66, v211
	v_fmac_f32_e32 v99, v67, v212
	v_fmac_f32_e32 v99, v68, v213
	v_fmac_f32_e32 v99, v55, v214
	v_fmac_f32_e32 v99, v62, v215
	v_fmac_f32_e32 v99, v63, v216
	v_fmac_f32_e32 v99, v64, v217
	v_fmac_f32_e32 v99, v52, v218
	v_fmac_f32_e32 v99, v53, v219
	v_fmac_f32_e32 v99, v50, v220
	v_fmac_f32_e32 v99, v51, v221
	v_pk_mul_f32 v[0:1], v[48:49], v[222:223]
	s_nop 0
	v_add_f32_e32 v0, v99, v0
	v_add_f32_e32 v99, v0, v1
	v_pk_mul_f32 v[0:1], v[46:47], v[224:225]
	s_nop 0
	v_add_f32_e32 v0, v99, v0
	v_add_f32_e32 v0, v0, v1
	v_min_f32_e32 v1, 0, v0
	v_mul_f32_e64 v0, |v0|, s11
	v_exp_f32_e32 v0, v0
	s_nop 0
	v_add_f32_e32 v0, 1.0, v0
	v_cmp_gt_f32_e32 vcc, s12, v0
	s_nop 1
	v_cndmask_b32_e64 v2, 0, 32, vcc
	v_ldexp_f32 v0, v0, v2
	v_log_f32_e32 v0, v0
	s_nop 0
	v_mul_f32_e32 v2, 0x3f317217, v0
	v_fma_f32 v2, v0, s13, -v2
	v_fmac_f32_e32 v2, 0x3377d1cf, v0
	v_fmac_f32_e32 v2, 0x3f317217, v0
	v_cmp_lt_f32_e64 s[0:1], |v0|, s36
	s_nop 1
	v_cndmask_b32_e64 v0, v0, v2, s[0:1]
	v_cndmask_b32_e32 v2, 0, v60, vcc
	v_sub_f32_e32 v0, v0, v2
	v_sub_f32_e32 v0, v1, v0
	v_fmamk_f32 v99, v0, 0x3d800000, v98
	ds_read_b128 v[210:213], v5 offset:2048
	ds_read_b128 v[214:217], v5 offset:2064
	ds_read_b128 v[218:221], v5 offset:2080
	ds_read_b128 v[222:225], v5 offset:2096
	s_waitcnt lgkmcnt(4)
	v_fma_f32 v100, v65, v240, v69
	v_fmac_f32_e32 v100, v66, v241
	v_fmac_f32_e32 v100, v67, v242
	v_fmac_f32_e32 v100, v68, v243
	v_fmac_f32_e32 v100, v55, v244
	v_fmac_f32_e32 v100, v62, v245
	v_fmac_f32_e32 v100, v63, v246
	v_fmac_f32_e32 v100, v64, v247
	v_fmac_f32_e32 v100, v52, v248
	v_fmac_f32_e32 v100, v53, v249
	v_fmac_f32_e32 v100, v50, v250
	v_fmac_f32_e32 v100, v51, v251
	v_pk_mul_f32 v[0:1], v[48:49], v[252:253]
	s_nop 0
	v_add_f32_e32 v0, v100, v0
	v_add_f32_e32 v100, v0, v1
	v_pk_mul_f32 v[0:1], v[46:47], v[254:255]
	s_nop 0
	v_add_f32_e32 v0, v100, v0
	v_add_f32_e32 v0, v0, v1
	v_min_f32_e32 v1, 0, v0
	v_mul_f32_e64 v0, |v0|, s11
	v_exp_f32_e32 v0, v0
	s_nop 0
	v_add_f32_e32 v0, 1.0, v0
	v_cmp_gt_f32_e32 vcc, s12, v0
	s_nop 1
	v_cndmask_b32_e64 v2, 0, 32, vcc
	v_ldexp_f32 v0, v0, v2
	v_log_f32_e32 v0, v0
	s_nop 0
	v_mul_f32_e32 v2, 0x3f317217, v0
	v_fma_f32 v2, v0, s13, -v2
	v_fmac_f32_e32 v2, 0x3377d1cf, v0
	v_fmac_f32_e32 v2, 0x3f317217, v0
	v_cmp_lt_f32_e64 s[0:1], |v0|, s36
	s_nop 1
	v_cndmask_b32_e64 v0, v0, v2, s[0:1]
	v_cndmask_b32_e32 v2, 0, v60, vcc
	v_sub_f32_e32 v0, v0, v2
	v_sub_f32_e32 v0, v1, v0
	v_fmamk_f32 v100, v0, 0x3d800000, v99
	ds_read_b128 v[240:243], v5 offset:2112
	ds_read_b128 v[244:247], v5 offset:2128
	ds_read_b128 v[248:251], v5 offset:2144
	ds_read_b128 v[252:255], v5 offset:2160
	s_waitcnt lgkmcnt(4)
	v_fma_f32 v101, v65, v210, v69
	v_fmac_f32_e32 v101, v66, v211
	v_fmac_f32_e32 v101, v67, v212
	v_fmac_f32_e32 v101, v68, v213
	v_fmac_f32_e32 v101, v55, v214
	v_fmac_f32_e32 v101, v62, v215
	v_fmac_f32_e32 v101, v63, v216
	v_fmac_f32_e32 v101, v64, v217
	v_fmac_f32_e32 v101, v52, v218
	v_fmac_f32_e32 v101, v53, v219
	v_fmac_f32_e32 v101, v50, v220
	v_fmac_f32_e32 v101, v51, v221
	v_pk_mul_f32 v[0:1], v[48:49], v[222:223]
	s_nop 0
	v_add_f32_e32 v0, v101, v0
	v_add_f32_e32 v101, v0, v1
	v_pk_mul_f32 v[0:1], v[46:47], v[224:225]
	s_nop 0
	v_add_f32_e32 v0, v101, v0
	v_add_f32_e32 v0, v0, v1
	v_min_f32_e32 v1, 0, v0
	v_mul_f32_e64 v0, |v0|, s11
	v_exp_f32_e32 v0, v0
	s_nop 0
	v_add_f32_e32 v0, 1.0, v0
	v_cmp_gt_f32_e32 vcc, s12, v0
	s_nop 1
	v_cndmask_b32_e64 v2, 0, 32, vcc
	v_ldexp_f32 v0, v0, v2
	v_log_f32_e32 v0, v0
	s_nop 0
	v_mul_f32_e32 v2, 0x3f317217, v0
	v_fma_f32 v2, v0, s13, -v2
	v_fmac_f32_e32 v2, 0x3377d1cf, v0
	v_fmac_f32_e32 v2, 0x3f317217, v0
	v_cmp_lt_f32_e64 s[0:1], |v0|, s36
	s_nop 1
	v_cndmask_b32_e64 v0, v0, v2, s[0:1]
	v_cndmask_b32_e32 v2, 0, v60, vcc
	v_sub_f32_e32 v0, v0, v2
	v_sub_f32_e32 v0, v1, v0
	v_fmamk_f32 v101, v0, 0x3d800000, v100
	ds_read_b128 v[210:213], v5 offset:2176
	ds_read_b128 v[214:217], v5 offset:2192
	ds_read_b128 v[218:221], v5 offset:2208
	ds_read_b128 v[222:225], v5 offset:2224
	s_waitcnt lgkmcnt(4)
; __device__ __forceinline__ float log_sigmoid(float x) { return fminf(x, 0.f) - __logf(1.f + __expf(-fabsf(x))); }
; __device__ __forceinline__ void gla_prep_item(LAS unsigned char* lds, int item, const bf16_t* Z, const float* W2, const float* Bg, bf16_t* KDT, float* DEC) {
;     ...
;     float bend = 0.f; float gv[64];
; #pragma unroll
;     for (int t = 0; t < 64; ++t) {
;         float x = bias;
; #pragma unroll
;         for (int r = 0; r < 16; ++r) x += zgs[t * 16 + r] * w[r];
;         gv[t] = log_sigmoid(x) * (1.f / 16.f); bend += gv[t];
;     }
	v_fma_f32 v102, v65, v240, v69
	v_fmac_f32_e32 v102, v66, v241
	v_fmac_f32_e32 v102, v67, v242
	v_fmac_f32_e32 v102, v68, v243
	v_fmac_f32_e32 v102, v55, v244
	v_fmac_f32_e32 v102, v62, v245
	v_fmac_f32_e32 v102, v63, v246
	v_fmac_f32_e32 v102, v64, v247
	v_fmac_f32_e32 v102, v52, v248
	v_fmac_f32_e32 v102, v53, v249
	v_fmac_f32_e32 v102, v50, v250
	v_fmac_f32_e32 v102, v51, v251
	v_pk_mul_f32 v[0:1], v[48:49], v[252:253]
	s_nop 0
	v_add_f32_e32 v0, v102, v0
	v_add_f32_e32 v102, v0, v1
	v_pk_mul_f32 v[0:1], v[46:47], v[254:255]
	s_nop 0
	v_add_f32_e32 v0, v102, v0
	v_add_f32_e32 v0, v0, v1
	v_min_f32_e32 v1, 0, v0
	v_mul_f32_e64 v0, |v0|, s11
	v_exp_f32_e32 v0, v0
	s_nop 0
	v_add_f32_e32 v0, 1.0, v0
	v_cmp_gt_f32_e32 vcc, s12, v0
	s_nop 1
	v_cndmask_b32_e64 v2, 0, 32, vcc
	v_ldexp_f32 v0, v0, v2
	v_log_f32_e32 v0, v0
	s_nop 0
	v_mul_f32_e32 v2, 0x3f317217, v0
	v_fma_f32 v2, v0, s13, -v2
	v_fmac_f32_e32 v2, 0x3377d1cf, v0
	v_fmac_f32_e32 v2, 0x3f317217, v0
	v_cmp_lt_f32_e64 s[0:1], |v0|, s36
	s_nop 1
	v_cndmask_b32_e64 v0, v0, v2, s[0:1]
	v_cndmask_b32_e32 v2, 0, v60, vcc
	v_sub_f32_e32 v0, v0, v2
	v_sub_f32_e32 v0, v1, v0
	v_fmamk_f32 v102, v0, 0x3d800000, v101
	ds_read_b128 v[240:243], v5 offset:2240
	ds_read_b128 v[244:247], v5 offset:2256
	ds_read_b128 v[248:251], v5 offset:2272
	ds_read_b128 v[252:255], v5 offset:2288
	s_waitcnt lgkmcnt(4)
	v_fma_f32 v103, v65, v210, v69
	v_fmac_f32_e32 v103, v66, v211
	v_fmac_f32_e32 v103, v67, v212
	v_fmac_f32_e32 v103, v68, v213
	v_fmac_f32_e32 v103, v55, v214
	v_fmac_f32_e32 v103, v62, v215
	v_fmac_f32_e32 v103, v63, v216
	v_fmac_f32_e32 v103, v64, v217
	v_fmac_f32_e32 v103, v52, v218
	v_fmac_f32_e32 v103, v53, v219
	v_fmac_f32_e32 v103, v50, v220
	v_fmac_f32_e32 v103, v51, v221
	v_pk_mul_f32 v[0:1], v[48:49], v[222:223]
	s_nop 0
	v_add_f32_e32 v0, v103, v0
	v_add_f32_e32 v103, v0, v1
	v_pk_mul_f32 v[0:1], v[46:47], v[224:225]
	s_nop 0
	v_add_f32_e32 v0, v103, v0
	v_add_f32_e32 v0, v0, v1
	v_min_f32_e32 v1, 0, v0
	v_mul_f32_e64 v0, |v0|, s11
	v_exp_f32_e32 v0, v0
	s_nop 0
	v_add_f32_e32 v0, 1.0, v0
	v_cmp_gt_f32_e32 vcc, s12, v0
	s_nop 1
	v_cndmask_b32_e64 v2, 0, 32, vcc
	v_ldexp_f32 v0, v0, v2
	v_log_f32_e32 v0, v0
	s_nop 0
	v_mul_f32_e32 v2, 0x3f317217, v0
	v_fma_f32 v2, v0, s13, -v2
	v_fmac_f32_e32 v2, 0x3377d1cf, v0
	v_fmac_f32_e32 v2, 0x3f317217, v0
	v_cmp_lt_f32_e64 s[0:1], |v0|, s36
	s_nop 1
	v_cndmask_b32_e64 v0, v0, v2, s[0:1]
	v_cndmask_b32_e32 v2, 0, v60, vcc
	v_sub_f32_e32 v0, v0, v2
	v_sub_f32_e32 v0, v1, v0
	v_fmamk_f32 v103, v0, 0x3d800000, v102
	ds_read_b128 v[210:213], v5 offset:2304
	ds_read_b128 v[214:217], v5 offset:2320
	ds_read_b128 v[218:221], v5 offset:2336
	ds_read_b128 v[222:225], v5 offset:2352
	s_waitcnt lgkmcnt(4)
	v_fma_f32 v104, v65, v240, v69
	v_fmac_f32_e32 v104, v66, v241
	v_fmac_f32_e32 v104, v67, v242
	v_fmac_f32_e32 v104, v68, v243
	v_fmac_f32_e32 v104, v55, v244
	v_fmac_f32_e32 v104, v62, v245
	v_fmac_f32_e32 v104, v63, v246
	v_fmac_f32_e32 v104, v64, v247
	v_fmac_f32_e32 v104, v52, v248
	v_fmac_f32_e32 v104, v53, v249
	v_fmac_f32_e32 v104, v50, v250
	v_fmac_f32_e32 v104, v51, v251
	v_pk_mul_f32 v[0:1], v[48:49], v[252:253]
	s_nop 0
	v_add_f32_e32 v0, v104, v0
	v_add_f32_e32 v104, v0, v1
	v_pk_mul_f32 v[0:1], v[46:47], v[254:255]
	s_nop 0
	v_add_f32_e32 v0, v104, v0
	v_add_f32_e32 v0, v0, v1
	v_min_f32_e32 v1, 0, v0
	v_mul_f32_e64 v0, |v0|, s11
	v_exp_f32_e32 v0, v0
	s_nop 0
	v_add_f32_e32 v0, 1.0, v0
	v_cmp_gt_f32_e32 vcc, s12, v0
	s_nop 1
	v_cndmask_b32_e64 v2, 0, 32, vcc
	v_ldexp_f32 v0, v0, v2
	v_log_f32_e32 v0, v0
	s_nop 0
	v_mul_f32_e32 v2, 0x3f317217, v0
	v_fma_f32 v2, v0, s13, -v2
	v_fmac_f32_e32 v2, 0x3377d1cf, v0
	v_fmac_f32_e32 v2, 0x3f317217, v0
	v_cmp_lt_f32_e64 s[0:1], |v0|, s36
	s_nop 1
	v_cndmask_b32_e64 v0, v0, v2, s[0:1]
	v_cndmask_b32_e32 v2, 0, v60, vcc
	v_sub_f32_e32 v0, v0, v2
	v_sub_f32_e32 v0, v1, v0
	v_fmamk_f32 v104, v0, 0x3d800000, v103
	ds_read_b128 v[240:243], v5 offset:2368
	ds_read_b128 v[244:247], v5 offset:2384
	ds_read_b128 v[248:251], v5 offset:2400
	ds_read_b128 v[252:255], v5 offset:2416
	s_waitcnt lgkmcnt(4)
	v_fma_f32 v105, v65, v210, v69
	v_fmac_f32_e32 v105, v66, v211
	v_fmac_f32_e32 v105, v67, v212
	v_fmac_f32_e32 v105, v68, v213
	v_fmac_f32_e32 v105, v55, v214
	v_fmac_f32_e32 v105, v62, v215
	v_fmac_f32_e32 v105, v63, v216
	v_fmac_f32_e32 v105, v64, v217
	v_fmac_f32_e32 v105, v52, v218
	v_fmac_f32_e32 v105, v53, v219
	v_fmac_f32_e32 v105, v50, v220
	v_fmac_f32_e32 v105, v51, v221
	v_pk_mul_f32 v[0:1], v[48:49], v[222:223]
	s_nop 0
	v_add_f32_e32 v0, v105, v0
	v_add_f32_e32 v105, v0, v1
	v_pk_mul_f32 v[0:1], v[46:47], v[224:225]
	s_nop 0
	v_add_f32_e32 v0, v105, v0
	v_add_f32_e32 v0, v0, v1
	v_min_f32_e32 v1, 0, v0
	v_mul_f32_e64 v0, |v0|, s11
	v_exp_f32_e32 v0, v0
	s_nop 0
	v_add_f32_e32 v0, 1.0, v0
	v_cmp_gt_f32_e32 vcc, s12, v0
	s_nop 1
	v_cndmask_b32_e64 v2, 0, 32, vcc
	v_ldexp_f32 v0, v0, v2
	v_log_f32_e32 v0, v0
	s_nop 0
	v_mul_f32_e32 v2, 0x3f317217, v0
	v_fma_f32 v2, v0, s13, -v2
	v_fmac_f32_e32 v2, 0x3377d1cf, v0
	v_fmac_f32_e32 v2, 0x3f317217, v0
	v_cmp_lt_f32_e64 s[0:1], |v0|, s36
	s_nop 1
	v_cndmask_b32_e64 v0, v0, v2, s[0:1]
	v_cndmask_b32_e32 v2, 0, v60, vcc
	v_sub_f32_e32 v0, v0, v2
	v_sub_f32_e32 v0, v1, v0
	v_fmamk_f32 v105, v0, 0x3d800000, v104
	ds_read_b128 v[210:213], v5 offset:2432
	ds_read_b128 v[214:217], v5 offset:2448
	ds_read_b128 v[218:221], v5 offset:2464
	ds_read_b128 v[222:225], v5 offset:2480
	s_waitcnt lgkmcnt(4)
; __device__ __forceinline__ float log_sigmoid(float x) { return fminf(x, 0.f) - __logf(1.f + __expf(-fabsf(x))); }
; __device__ __forceinline__ void gla_prep_item(LAS unsigned char* lds, int item, const bf16_t* Z, const float* W2, const float* Bg, bf16_t* KDT, float* DEC) {
;     ...
;     float bend = 0.f; float gv[64];
; #pragma unroll
;     for (int t = 0; t < 64; ++t) {
;         float x = bias;
; #pragma unroll
;         for (int r = 0; r < 16; ++r) x += zgs[t * 16 + r] * w[r];
;         gv[t] = log_sigmoid(x) * (1.f / 16.f); bend += gv[t];
;     }
	v_fma_f32 v106, v65, v240, v69
	v_fmac_f32_e32 v106, v66, v241
	v_fmac_f32_e32 v106, v67, v242
	v_fmac_f32_e32 v106, v68, v243
	v_fmac_f32_e32 v106, v55, v244
	v_fmac_f32_e32 v106, v62, v245
	v_fmac_f32_e32 v106, v63, v246
	v_fmac_f32_e32 v106, v64, v247
	v_fmac_f32_e32 v106, v52, v248
	v_fmac_f32_e32 v106, v53, v249
	v_fmac_f32_e32 v106, v50, v250
	v_fmac_f32_e32 v106, v51, v251
	v_pk_mul_f32 v[0:1], v[48:49], v[252:253]
	s_nop 0
	v_add_f32_e32 v0, v106, v0
	v_add_f32_e32 v106, v0, v1
	v_pk_mul_f32 v[0:1], v[46:47], v[254:255]
	s_nop 0
	v_add_f32_e32 v0, v106, v0
	v_add_f32_e32 v0, v0, v1
	v_min_f32_e32 v1, 0, v0
	v_mul_f32_e64 v0, |v0|, s11
	v_exp_f32_e32 v0, v0
	s_nop 0
	v_add_f32_e32 v0, 1.0, v0
	v_cmp_gt_f32_e32 vcc, s12, v0
	s_nop 1
	v_cndmask_b32_e64 v2, 0, 32, vcc
	v_ldexp_f32 v0, v0, v2
	v_log_f32_e32 v0, v0
	s_nop 0
	v_mul_f32_e32 v2, 0x3f317217, v0
	v_fma_f32 v2, v0, s13, -v2
	v_fmac_f32_e32 v2, 0x3377d1cf, v0
	v_fmac_f32_e32 v2, 0x3f317217, v0
	v_cmp_lt_f32_e64 s[0:1], |v0|, s36
	s_nop 1
	v_cndmask_b32_e64 v0, v0, v2, s[0:1]
	v_cndmask_b32_e32 v2, 0, v60, vcc
	v_sub_f32_e32 v0, v0, v2
	v_sub_f32_e32 v0, v1, v0
	v_fmamk_f32 v106, v0, 0x3d800000, v105
	ds_read_b128 v[240:243], v5 offset:2496
	ds_read_b128 v[244:247], v5 offset:2512
	ds_read_b128 v[248:251], v5 offset:2528
	ds_read_b128 v[252:255], v5 offset:2544
	s_waitcnt lgkmcnt(4)
	v_fma_f32 v107, v65, v210, v69
	v_fmac_f32_e32 v107, v66, v211
	v_fmac_f32_e32 v107, v67, v212
	v_fmac_f32_e32 v107, v68, v213
	v_fmac_f32_e32 v107, v55, v214
	v_fmac_f32_e32 v107, v62, v215
	v_fmac_f32_e32 v107, v63, v216
	v_fmac_f32_e32 v107, v64, v217
	v_fmac_f32_e32 v107, v52, v218
	v_fmac_f32_e32 v107, v53, v219
	v_fmac_f32_e32 v107, v50, v220
	v_fmac_f32_e32 v107, v51, v221
	v_pk_mul_f32 v[0:1], v[48:49], v[222:223]
	s_nop 0
	v_add_f32_e32 v0, v107, v0
	v_add_f32_e32 v107, v0, v1
	v_pk_mul_f32 v[0:1], v[46:47], v[224:225]
	s_nop 0
	v_add_f32_e32 v0, v107, v0
	v_add_f32_e32 v0, v0, v1
	v_min_f32_e32 v1, 0, v0
	v_mul_f32_e64 v0, |v0|, s11
	v_exp_f32_e32 v0, v0
	s_nop 0
	v_add_f32_e32 v0, 1.0, v0
	v_cmp_gt_f32_e32 vcc, s12, v0
	s_nop 1
	v_cndmask_b32_e64 v2, 0, 32, vcc
	v_ldexp_f32 v0, v0, v2
	v_log_f32_e32 v0, v0
	s_nop 0
	v_mul_f32_e32 v2, 0x3f317217, v0
	v_fma_f32 v2, v0, s13, -v2
	v_fmac_f32_e32 v2, 0x3377d1cf, v0
	v_fmac_f32_e32 v2, 0x3f317217, v0
	v_cmp_lt_f32_e64 s[0:1], |v0|, s36
	s_nop 1
	v_cndmask_b32_e64 v0, v0, v2, s[0:1]
	v_cndmask_b32_e32 v2, 0, v60, vcc
	v_sub_f32_e32 v0, v0, v2
	v_sub_f32_e32 v0, v1, v0
	v_fmamk_f32 v107, v0, 0x3d800000, v106
	ds_read_b128 v[210:213], v5 offset:2560
	ds_read_b128 v[214:217], v5 offset:2576
	ds_read_b128 v[218:221], v5 offset:2592
	ds_read_b128 v[222:225], v5 offset:2608
	s_waitcnt lgkmcnt(4)
	v_fma_f32 v108, v65, v240, v69
	v_fmac_f32_e32 v108, v66, v241
	v_fmac_f32_e32 v108, v67, v242
	v_fmac_f32_e32 v108, v68, v243
	v_fmac_f32_e32 v108, v55, v244
	v_fmac_f32_e32 v108, v62, v245
	v_fmac_f32_e32 v108, v63, v246
	v_fmac_f32_e32 v108, v64, v247
	v_fmac_f32_e32 v108, v52, v248
	v_fmac_f32_e32 v108, v53, v249
	v_fmac_f32_e32 v108, v50, v250
	v_fmac_f32_e32 v108, v51, v251
	v_pk_mul_f32 v[0:1], v[48:49], v[252:253]
	s_nop 0
	v_add_f32_e32 v0, v108, v0
	v_add_f32_e32 v108, v0, v1
	v_pk_mul_f32 v[0:1], v[46:47], v[254:255]
	s_nop 0
	v_add_f32_e32 v0, v108, v0
	v_add_f32_e32 v0, v0, v1
	v_min_f32_e32 v1, 0, v0
	v_mul_f32_e64 v0, |v0|, s11
	v_exp_f32_e32 v0, v0
	s_nop 0
	v_add_f32_e32 v0, 1.0, v0
	v_cmp_gt_f32_e32 vcc, s12, v0
	s_nop 1
	v_cndmask_b32_e64 v2, 0, 32, vcc
	v_ldexp_f32 v0, v0, v2
	v_log_f32_e32 v0, v0
	s_nop 0
	v_mul_f32_e32 v2, 0x3f317217, v0
	v_fma_f32 v2, v0, s13, -v2
	v_fmac_f32_e32 v2, 0x3377d1cf, v0
	v_fmac_f32_e32 v2, 0x3f317217, v0
	v_cmp_lt_f32_e64 s[0:1], |v0|, s36
	s_nop 1
	v_cndmask_b32_e64 v0, v0, v2, s[0:1]
	v_cndmask_b32_e32 v2, 0, v60, vcc
	v_sub_f32_e32 v0, v0, v2
	v_sub_f32_e32 v0, v1, v0
	v_fmamk_f32 v108, v0, 0x3d800000, v107
	ds_read_b128 v[240:243], v5 offset:2624
	ds_read_b128 v[244:247], v5 offset:2640
	ds_read_b128 v[248:251], v5 offset:2656
	ds_read_b128 v[252:255], v5 offset:2672
	s_waitcnt lgkmcnt(4)
	v_fma_f32 v109, v65, v210, v69
	v_fmac_f32_e32 v109, v66, v211
	v_fmac_f32_e32 v109, v67, v212
	v_fmac_f32_e32 v109, v68, v213
	v_fmac_f32_e32 v109, v55, v214
	v_fmac_f32_e32 v109, v62, v215
	v_fmac_f32_e32 v109, v63, v216
	v_fmac_f32_e32 v109, v64, v217
	v_fmac_f32_e32 v109, v52, v218
	v_fmac_f32_e32 v109, v53, v219
	v_fmac_f32_e32 v109, v50, v220
	v_fmac_f32_e32 v109, v51, v221
	v_pk_mul_f32 v[0:1], v[48:49], v[222:223]
	s_nop 0
	v_add_f32_e32 v0, v109, v0
	v_add_f32_e32 v109, v0, v1
	v_pk_mul_f32 v[0:1], v[46:47], v[224:225]
	s_nop 0
	v_add_f32_e32 v0, v109, v0
	v_add_f32_e32 v0, v0, v1
	v_min_f32_e32 v1, 0, v0
	v_mul_f32_e64 v0, |v0|, s11
	v_exp_f32_e32 v0, v0
	s_nop 0
	v_add_f32_e32 v0, 1.0, v0
	v_cmp_gt_f32_e32 vcc, s12, v0
	s_nop 1
	v_cndmask_b32_e64 v2, 0, 32, vcc
	v_ldexp_f32 v0, v0, v2
	v_log_f32_e32 v0, v0
	s_nop 0
	v_mul_f32_e32 v2, 0x3f317217, v0
	v_fma_f32 v2, v0, s13, -v2
	v_fmac_f32_e32 v2, 0x3377d1cf, v0
	v_fmac_f32_e32 v2, 0x3f317217, v0
	v_cmp_lt_f32_e64 s[0:1], |v0|, s36
	s_nop 1
	v_cndmask_b32_e64 v0, v0, v2, s[0:1]
	v_cndmask_b32_e32 v2, 0, v60, vcc
	v_sub_f32_e32 v0, v0, v2
	v_sub_f32_e32 v0, v1, v0
	v_fmamk_f32 v109, v0, 0x3d800000, v108
	ds_read_b128 v[210:213], v5 offset:2688
	ds_read_b128 v[214:217], v5 offset:2704
	ds_read_b128 v[218:221], v5 offset:2720
	ds_read_b128 v[222:225], v5 offset:2736
	s_waitcnt lgkmcnt(4)
; __device__ __forceinline__ float log_sigmoid(float x) { return fminf(x, 0.f) - __logf(1.f + __expf(-fabsf(x))); }
; __device__ __forceinline__ void gla_prep_item(LAS unsigned char* lds, int item, const bf16_t* Z, const float* W2, const float* Bg, bf16_t* KDT, float* DEC) {
;     ...
;     float bend = 0.f; float gv[64];
; #pragma unroll
;     for (int t = 0; t < 64; ++t) {
;         float x = bias;
; #pragma unroll
;         for (int r = 0; r < 16; ++r) x += zgs[t * 16 + r] * w[r];
;         gv[t] = log_sigmoid(x) * (1.f / 16.f); bend += gv[t];
;     }
	v_fma_f32 v110, v65, v240, v69
	v_fmac_f32_e32 v110, v66, v241
	v_fmac_f32_e32 v110, v67, v242
	v_fmac_f32_e32 v110, v68, v243
	v_fmac_f32_e32 v110, v55, v244
	v_fmac_f32_e32 v110, v62, v245
	v_fmac_f32_e32 v110, v63, v246
	v_fmac_f32_e32 v110, v64, v247
	v_fmac_f32_e32 v110, v52, v248
	v_fmac_f32_e32 v110, v53, v249
	v_fmac_f32_e32 v110, v50, v250
	v_fmac_f32_e32 v110, v51, v251
	v_pk_mul_f32 v[0:1], v[48:49], v[252:253]
	s_nop 0
	v_add_f32_e32 v0, v110, v0
	v_add_f32_e32 v110, v0, v1
	v_pk_mul_f32 v[0:1], v[46:47], v[254:255]
	s_nop 0
	v_add_f32_e32 v0, v110, v0
	v_add_f32_e32 v0, v0, v1
	v_min_f32_e32 v1, 0, v0
	v_mul_f32_e64 v0, |v0|, s11
	v_exp_f32_e32 v0, v0
	s_nop 0
	v_add_f32_e32 v0, 1.0, v0
	v_cmp_gt_f32_e32 vcc, s12, v0
	s_nop 1
	v_cndmask_b32_e64 v2, 0, 32, vcc
	v_ldexp_f32 v0, v0, v2
	v_log_f32_e32 v0, v0
	s_nop 0
	v_mul_f32_e32 v2, 0x3f317217, v0
	v_fma_f32 v2, v0, s13, -v2
	v_fmac_f32_e32 v2, 0x3377d1cf, v0
	v_fmac_f32_e32 v2, 0x3f317217, v0
	v_cmp_lt_f32_e64 s[0:1], |v0|, s36
	s_nop 1
	v_cndmask_b32_e64 v0, v0, v2, s[0:1]
	v_cndmask_b32_e32 v2, 0, v60, vcc
	v_sub_f32_e32 v0, v0, v2
	v_sub_f32_e32 v0, v1, v0
	v_fmamk_f32 v110, v0, 0x3d800000, v109
	ds_read_b128 v[240:243], v5 offset:2752
	ds_read_b128 v[244:247], v5 offset:2768
	ds_read_b128 v[248:251], v5 offset:2784
	ds_read_b128 v[252:255], v5 offset:2800
	s_waitcnt lgkmcnt(4)
	v_fma_f32 v111, v65, v210, v69
	v_fmac_f32_e32 v111, v66, v211
	v_fmac_f32_e32 v111, v67, v212
	v_fmac_f32_e32 v111, v68, v213
	v_fmac_f32_e32 v111, v55, v214
	v_fmac_f32_e32 v111, v62, v215
	v_fmac_f32_e32 v111, v63, v216
	v_fmac_f32_e32 v111, v64, v217
	v_fmac_f32_e32 v111, v52, v218
	v_fmac_f32_e32 v111, v53, v219
	v_fmac_f32_e32 v111, v50, v220
	v_fmac_f32_e32 v111, v51, v221
	v_pk_mul_f32 v[0:1], v[48:49], v[222:223]
	s_nop 0
	v_add_f32_e32 v0, v111, v0
	v_add_f32_e32 v111, v0, v1
	v_pk_mul_f32 v[0:1], v[46:47], v[224:225]
	s_nop 0
	v_add_f32_e32 v0, v111, v0
	v_add_f32_e32 v0, v0, v1
	v_min_f32_e32 v1, 0, v0
	v_mul_f32_e64 v0, |v0|, s11
	v_exp_f32_e32 v0, v0
	s_nop 0
	v_add_f32_e32 v0, 1.0, v0
	v_cmp_gt_f32_e32 vcc, s12, v0
	s_nop 1
	v_cndmask_b32_e64 v2, 0, 32, vcc
	v_ldexp_f32 v0, v0, v2
	v_log_f32_e32 v0, v0
	s_nop 0
	v_mul_f32_e32 v2, 0x3f317217, v0
	v_fma_f32 v2, v0, s13, -v2
	v_fmac_f32_e32 v2, 0x3377d1cf, v0
	v_fmac_f32_e32 v2, 0x3f317217, v0
	v_cmp_lt_f32_e64 s[0:1], |v0|, s36
	s_nop 1
	v_cndmask_b32_e64 v0, v0, v2, s[0:1]
	v_cndmask_b32_e32 v2, 0, v60, vcc
	v_sub_f32_e32 v0, v0, v2
	v_sub_f32_e32 v0, v1, v0
	v_fmamk_f32 v111, v0, 0x3d800000, v110
	ds_read_b128 v[210:213], v5 offset:2816
	ds_read_b128 v[214:217], v5 offset:2832
	ds_read_b128 v[218:221], v5 offset:2848
	ds_read_b128 v[222:225], v5 offset:2864
	s_waitcnt lgkmcnt(4)
	v_fma_f32 v112, v65, v240, v69
	v_fmac_f32_e32 v112, v66, v241
	v_fmac_f32_e32 v112, v67, v242
	v_fmac_f32_e32 v112, v68, v243
	v_fmac_f32_e32 v112, v55, v244
	v_fmac_f32_e32 v112, v62, v245
	v_fmac_f32_e32 v112, v63, v246
	v_fmac_f32_e32 v112, v64, v247
	v_fmac_f32_e32 v112, v52, v248
	v_fmac_f32_e32 v112, v53, v249
	v_fmac_f32_e32 v112, v50, v250
	v_fmac_f32_e32 v112, v51, v251
	v_pk_mul_f32 v[0:1], v[48:49], v[252:253]
	s_nop 0
	v_add_f32_e32 v0, v112, v0
	v_add_f32_e32 v112, v0, v1
	v_pk_mul_f32 v[0:1], v[46:47], v[254:255]
	s_nop 0
	v_add_f32_e32 v0, v112, v0
	v_add_f32_e32 v0, v0, v1
	v_min_f32_e32 v1, 0, v0
	v_mul_f32_e64 v0, |v0|, s11
	v_exp_f32_e32 v0, v0
	s_nop 0
	v_add_f32_e32 v0, 1.0, v0
	v_cmp_gt_f32_e32 vcc, s12, v0
	s_nop 1
	v_cndmask_b32_e64 v2, 0, 32, vcc
	v_ldexp_f32 v0, v0, v2
	v_log_f32_e32 v0, v0
	s_nop 0
	v_mul_f32_e32 v2, 0x3f317217, v0
	v_fma_f32 v2, v0, s13, -v2
	v_fmac_f32_e32 v2, 0x3377d1cf, v0
	v_fmac_f32_e32 v2, 0x3f317217, v0
	v_cmp_lt_f32_e64 s[0:1], |v0|, s36
	s_nop 1
	v_cndmask_b32_e64 v0, v0, v2, s[0:1]
	v_cndmask_b32_e32 v2, 0, v60, vcc
	v_sub_f32_e32 v0, v0, v2
	v_sub_f32_e32 v0, v1, v0
	v_fmamk_f32 v112, v0, 0x3d800000, v111
	ds_read_b128 v[240:243], v5 offset:2880
	ds_read_b128 v[244:247], v5 offset:2896
	ds_read_b128 v[248:251], v5 offset:2912
	ds_read_b128 v[252:255], v5 offset:2928
	s_waitcnt lgkmcnt(4)
	v_fma_f32 v113, v65, v210, v69
	v_fmac_f32_e32 v113, v66, v211
	v_fmac_f32_e32 v113, v67, v212
	v_fmac_f32_e32 v113, v68, v213
	v_fmac_f32_e32 v113, v55, v214
	v_fmac_f32_e32 v113, v62, v215
	v_fmac_f32_e32 v113, v63, v216
	v_fmac_f32_e32 v113, v64, v217
	v_fmac_f32_e32 v113, v52, v218
	v_fmac_f32_e32 v113, v53, v219
	v_fmac_f32_e32 v113, v50, v220
	v_fmac_f32_e32 v113, v51, v221
	v_pk_mul_f32 v[0:1], v[48:49], v[222:223]
	s_nop 0
	v_add_f32_e32 v0, v113, v0
	v_add_f32_e32 v113, v0, v1
	v_pk_mul_f32 v[0:1], v[46:47], v[224:225]
	s_nop 0
	v_add_f32_e32 v0, v113, v0
	v_add_f32_e32 v0, v0, v1
	v_min_f32_e32 v1, 0, v0
	v_mul_f32_e64 v0, |v0|, s11
	v_exp_f32_e32 v0, v0
	s_nop 0
	v_add_f32_e32 v0, 1.0, v0
	v_cmp_gt_f32_e32 vcc, s12, v0
	s_nop 1
	v_cndmask_b32_e64 v2, 0, 32, vcc
	v_ldexp_f32 v0, v0, v2
	v_log_f32_e32 v0, v0
	s_nop 0
	v_mul_f32_e32 v2, 0x3f317217, v0
	v_fma_f32 v2, v0, s13, -v2
	v_fmac_f32_e32 v2, 0x3377d1cf, v0
	v_fmac_f32_e32 v2, 0x3f317217, v0
	v_cmp_lt_f32_e64 s[0:1], |v0|, s36
	s_nop 1
	v_cndmask_b32_e64 v0, v0, v2, s[0:1]
	v_cndmask_b32_e32 v2, 0, v60, vcc
	v_sub_f32_e32 v0, v0, v2
	v_sub_f32_e32 v0, v1, v0
	v_fmamk_f32 v113, v0, 0x3d800000, v112
	ds_read_b128 v[210:213], v5 offset:2944
	ds_read_b128 v[214:217], v5 offset:2960
	ds_read_b128 v[218:221], v5 offset:2976
	ds_read_b128 v[222:225], v5 offset:2992
	s_waitcnt lgkmcnt(4)
; __device__ __forceinline__ float log_sigmoid(float x) { return fminf(x, 0.f) - __logf(1.f + __expf(-fabsf(x))); }
; __device__ __forceinline__ void gla_prep_item(LAS unsigned char* lds, int item, const bf16_t* Z, const float* W2, const float* Bg, bf16_t* KDT, float* DEC) {
;     ...
;     float bend = 0.f; float gv[64];
; #pragma unroll
;     for (int t = 0; t < 64; ++t) {
;         float x = bias;
; #pragma unroll
;         for (int r = 0; r < 16; ++r) x += zgs[t * 16 + r] * w[r];
;         gv[t] = log_sigmoid(x) * (1.f / 16.f); bend += gv[t];
;     }
	v_fma_f32 v114, v65, v240, v69
	v_fmac_f32_e32 v114, v66, v241
	v_fmac_f32_e32 v114, v67, v242
	v_fmac_f32_e32 v114, v68, v243
	v_fmac_f32_e32 v114, v55, v244
	v_fmac_f32_e32 v114, v62, v245
	v_fmac_f32_e32 v114, v63, v246
	v_fmac_f32_e32 v114, v64, v247
	v_fmac_f32_e32 v114, v52, v248
	v_fmac_f32_e32 v114, v53, v249
	v_fmac_f32_e32 v114, v50, v250
	v_fmac_f32_e32 v114, v51, v251
	v_pk_mul_f32 v[0:1], v[48:49], v[252:253]
	s_nop 0
	v_add_f32_e32 v0, v114, v0
	v_add_f32_e32 v114, v0, v1
	v_pk_mul_f32 v[0:1], v[46:47], v[254:255]
	s_nop 0
	v_add_f32_e32 v0, v114, v0
	v_add_f32_e32 v0, v0, v1
	v_min_f32_e32 v1, 0, v0
	v_mul_f32_e64 v0, |v0|, s11
	v_exp_f32_e32 v0, v0
	s_nop 0
	v_add_f32_e32 v0, 1.0, v0
	v_cmp_gt_f32_e32 vcc, s12, v0
	s_nop 1
	v_cndmask_b32_e64 v2, 0, 32, vcc
	v_ldexp_f32 v0, v0, v2
	v_log_f32_e32 v0, v0
	s_nop 0
	v_mul_f32_e32 v2, 0x3f317217, v0
	v_fma_f32 v2, v0, s13, -v2
	v_fmac_f32_e32 v2, 0x3377d1cf, v0
	v_fmac_f32_e32 v2, 0x3f317217, v0
	v_cmp_lt_f32_e64 s[0:1], |v0|, s36
	s_nop 1
	v_cndmask_b32_e64 v0, v0, v2, s[0:1]
	v_cndmask_b32_e32 v2, 0, v60, vcc
	v_sub_f32_e32 v0, v0, v2
	v_sub_f32_e32 v0, v1, v0
	v_fmamk_f32 v114, v0, 0x3d800000, v113
	ds_read_b128 v[240:243], v5 offset:3008
	ds_read_b128 v[244:247], v5 offset:3024
	ds_read_b128 v[248:251], v5 offset:3040
	ds_read_b128 v[252:255], v5 offset:3056
	s_waitcnt lgkmcnt(4)
	v_fma_f32 v115, v65, v210, v69
	v_fmac_f32_e32 v115, v66, v211
	v_fmac_f32_e32 v115, v67, v212
	v_fmac_f32_e32 v115, v68, v213
	v_fmac_f32_e32 v115, v55, v214
	v_fmac_f32_e32 v115, v62, v215
	v_fmac_f32_e32 v115, v63, v216
	v_fmac_f32_e32 v115, v64, v217
	v_fmac_f32_e32 v115, v52, v218
	v_fmac_f32_e32 v115, v53, v219
	v_fmac_f32_e32 v115, v50, v220
	v_fmac_f32_e32 v115, v51, v221
	v_pk_mul_f32 v[0:1], v[48:49], v[222:223]
	s_nop 0
	v_add_f32_e32 v0, v115, v0
	v_add_f32_e32 v115, v0, v1
	v_pk_mul_f32 v[0:1], v[46:47], v[224:225]
	s_nop 0
	v_add_f32_e32 v0, v115, v0
	v_add_f32_e32 v0, v0, v1
	v_min_f32_e32 v1, 0, v0
	v_mul_f32_e64 v0, |v0|, s11
	v_exp_f32_e32 v0, v0
	s_nop 0
	v_add_f32_e32 v0, 1.0, v0
	v_cmp_gt_f32_e32 vcc, s12, v0
	s_nop 1
	v_cndmask_b32_e64 v2, 0, 32, vcc
	v_ldexp_f32 v0, v0, v2
	v_log_f32_e32 v0, v0
	s_nop 0
	v_mul_f32_e32 v2, 0x3f317217, v0
	v_fma_f32 v2, v0, s13, -v2
	v_fmac_f32_e32 v2, 0x3377d1cf, v0
	v_fmac_f32_e32 v2, 0x3f317217, v0
	v_cmp_lt_f32_e64 s[0:1], |v0|, s36
	s_nop 1
	v_cndmask_b32_e64 v0, v0, v2, s[0:1]
	v_cndmask_b32_e32 v2, 0, v60, vcc
	v_sub_f32_e32 v0, v0, v2
	v_sub_f32_e32 v0, v1, v0
	v_fmamk_f32 v115, v0, 0x3d800000, v114
	ds_read_b128 v[210:213], v5 offset:3072
	ds_read_b128 v[214:217], v5 offset:3088
	ds_read_b128 v[218:221], v5 offset:3104
	ds_read_b128 v[222:225], v5 offset:3120
	s_waitcnt lgkmcnt(4)
	v_fma_f32 v116, v65, v240, v69
	v_fmac_f32_e32 v116, v66, v241
	v_fmac_f32_e32 v116, v67, v242
	v_fmac_f32_e32 v116, v68, v243
	v_fmac_f32_e32 v116, v55, v244
	v_fmac_f32_e32 v116, v62, v245
	v_fmac_f32_e32 v116, v63, v246
	v_fmac_f32_e32 v116, v64, v247
	v_fmac_f32_e32 v116, v52, v248
	v_fmac_f32_e32 v116, v53, v249
	v_fmac_f32_e32 v116, v50, v250
	v_fmac_f32_e32 v116, v51, v251
	v_pk_mul_f32 v[0:1], v[48:49], v[252:253]
	s_nop 0
	v_add_f32_e32 v0, v116, v0
	v_add_f32_e32 v116, v0, v1
	v_pk_mul_f32 v[0:1], v[46:47], v[254:255]
	s_nop 0
	v_add_f32_e32 v0, v116, v0
	v_add_f32_e32 v0, v0, v1
	v_min_f32_e32 v1, 0, v0
	v_mul_f32_e64 v0, |v0|, s11
	v_exp_f32_e32 v0, v0
	s_nop 0
	v_add_f32_e32 v0, 1.0, v0
	v_cmp_gt_f32_e32 vcc, s12, v0
	s_nop 1
	v_cndmask_b32_e64 v2, 0, 32, vcc
	v_ldexp_f32 v0, v0, v2
	v_log_f32_e32 v0, v0
	s_nop 0
	v_mul_f32_e32 v2, 0x3f317217, v0
	v_fma_f32 v2, v0, s13, -v2
	v_fmac_f32_e32 v2, 0x3377d1cf, v0
	v_fmac_f32_e32 v2, 0x3f317217, v0
	v_cmp_lt_f32_e64 s[0:1], |v0|, s36
	s_nop 1
	v_cndmask_b32_e64 v0, v0, v2, s[0:1]
	v_cndmask_b32_e32 v2, 0, v60, vcc
	v_sub_f32_e32 v0, v0, v2
	v_sub_f32_e32 v0, v1, v0
	v_fmamk_f32 v116, v0, 0x3d800000, v115
	ds_read_b128 v[240:243], v5 offset:3136
	ds_read_b128 v[244:247], v5 offset:3152
	ds_read_b128 v[248:251], v5 offset:3168
	ds_read_b128 v[252:255], v5 offset:3184
	s_waitcnt lgkmcnt(4)
	v_fma_f32 v117, v65, v210, v69
	v_fmac_f32_e32 v117, v66, v211
	v_fmac_f32_e32 v117, v67, v212
	v_fmac_f32_e32 v117, v68, v213
	v_fmac_f32_e32 v117, v55, v214
	v_fmac_f32_e32 v117, v62, v215
	v_fmac_f32_e32 v117, v63, v216
	v_fmac_f32_e32 v117, v64, v217
	v_fmac_f32_e32 v117, v52, v218
	v_fmac_f32_e32 v117, v53, v219
	v_fmac_f32_e32 v117, v50, v220
	v_fmac_f32_e32 v117, v51, v221
	v_pk_mul_f32 v[0:1], v[48:49], v[222:223]
	s_nop 0
	v_add_f32_e32 v0, v117, v0
	v_add_f32_e32 v117, v0, v1
	v_pk_mul_f32 v[0:1], v[46:47], v[224:225]
	s_nop 0
	v_add_f32_e32 v0, v117, v0
	v_add_f32_e32 v0, v0, v1
	v_min_f32_e32 v1, 0, v0
	v_mul_f32_e64 v0, |v0|, s11
	v_exp_f32_e32 v0, v0
	s_nop 0
	v_add_f32_e32 v0, 1.0, v0
	v_cmp_gt_f32_e32 vcc, s12, v0
	s_nop 1
	v_cndmask_b32_e64 v2, 0, 32, vcc
	v_ldexp_f32 v0, v0, v2
	v_log_f32_e32 v0, v0
	s_nop 0
	v_mul_f32_e32 v2, 0x3f317217, v0
	v_fma_f32 v2, v0, s13, -v2
	v_fmac_f32_e32 v2, 0x3377d1cf, v0
	v_fmac_f32_e32 v2, 0x3f317217, v0
	v_cmp_lt_f32_e64 s[0:1], |v0|, s36
	s_nop 1
	v_cndmask_b32_e64 v0, v0, v2, s[0:1]
	v_cndmask_b32_e32 v2, 0, v60, vcc
	v_sub_f32_e32 v0, v0, v2
	v_sub_f32_e32 v0, v1, v0
	v_fmamk_f32 v117, v0, 0x3d800000, v116
	ds_read_b128 v[210:213], v5 offset:3200
	ds_read_b128 v[214:217], v5 offset:3216
	ds_read_b128 v[218:221], v5 offset:3232
	ds_read_b128 v[222:225], v5 offset:3248
	s_waitcnt lgkmcnt(4)
; __device__ __forceinline__ float log_sigmoid(float x) { return fminf(x, 0.f) - __logf(1.f + __expf(-fabsf(x))); }
; __device__ __forceinline__ void gla_prep_item(LAS unsigned char* lds, int item, const bf16_t* Z, const float* W2, const float* Bg, bf16_t* KDT, float* DEC) {
;     ...
;     float bend = 0.f; float gv[64];
; #pragma unroll
;     for (int t = 0; t < 64; ++t) {
;         float x = bias;
; #pragma unroll
;         for (int r = 0; r < 16; ++r) x += zgs[t * 16 + r] * w[r];
;         gv[t] = log_sigmoid(x) * (1.f / 16.f); bend += gv[t];
;     }
	v_fma_f32 v118, v65, v240, v69
	v_fmac_f32_e32 v118, v66, v241
	v_fmac_f32_e32 v118, v67, v242
	v_fmac_f32_e32 v118, v68, v243
	v_fmac_f32_e32 v118, v55, v244
	v_fmac_f32_e32 v118, v62, v245
	v_fmac_f32_e32 v118, v63, v246
	v_fmac_f32_e32 v118, v64, v247
	v_fmac_f32_e32 v118, v52, v248
	v_fmac_f32_e32 v118, v53, v249
	v_fmac_f32_e32 v118, v50, v250
	v_fmac_f32_e32 v118, v51, v251
	v_pk_mul_f32 v[0:1], v[48:49], v[252:253]
	s_nop 0
	v_add_f32_e32 v0, v118, v0
	v_add_f32_e32 v118, v0, v1
	v_pk_mul_f32 v[0:1], v[46:47], v[254:255]
	s_nop 0
	v_add_f32_e32 v0, v118, v0
	v_add_f32_e32 v0, v0, v1
	v_min_f32_e32 v1, 0, v0
	v_mul_f32_e64 v0, |v0|, s11
	v_exp_f32_e32 v0, v0
	s_nop 0
	v_add_f32_e32 v0, 1.0, v0
	v_cmp_gt_f32_e32 vcc, s12, v0
	s_nop 1
	v_cndmask_b32_e64 v2, 0, 32, vcc
	v_ldexp_f32 v0, v0, v2
	v_log_f32_e32 v0, v0
	s_nop 0
	v_mul_f32_e32 v2, 0x3f317217, v0
	v_fma_f32 v2, v0, s13, -v2
	v_fmac_f32_e32 v2, 0x3377d1cf, v0
	v_fmac_f32_e32 v2, 0x3f317217, v0
	v_cmp_lt_f32_e64 s[0:1], |v0|, s36
	s_nop 1
	v_cndmask_b32_e64 v0, v0, v2, s[0:1]
	v_cndmask_b32_e32 v2, 0, v60, vcc
	v_sub_f32_e32 v0, v0, v2
	v_sub_f32_e32 v0, v1, v0
	v_fmamk_f32 v118, v0, 0x3d800000, v117
	ds_read_b128 v[240:243], v5 offset:3264
	ds_read_b128 v[244:247], v5 offset:3280
	ds_read_b128 v[248:251], v5 offset:3296
	ds_read_b128 v[252:255], v5 offset:3312
	s_waitcnt lgkmcnt(4)
	v_fma_f32 v119, v65, v210, v69
	v_fmac_f32_e32 v119, v66, v211
	v_fmac_f32_e32 v119, v67, v212
	v_fmac_f32_e32 v119, v68, v213
	v_fmac_f32_e32 v119, v55, v214
	v_fmac_f32_e32 v119, v62, v215
	v_fmac_f32_e32 v119, v63, v216
	v_fmac_f32_e32 v119, v64, v217
	v_fmac_f32_e32 v119, v52, v218
	v_fmac_f32_e32 v119, v53, v219
	v_fmac_f32_e32 v119, v50, v220
	v_fmac_f32_e32 v119, v51, v221
	v_pk_mul_f32 v[0:1], v[48:49], v[222:223]
	s_nop 0
	v_add_f32_e32 v0, v119, v0
	v_add_f32_e32 v119, v0, v1
	v_pk_mul_f32 v[0:1], v[46:47], v[224:225]
	s_nop 0
	v_add_f32_e32 v0, v119, v0
	v_add_f32_e32 v0, v0, v1
	v_min_f32_e32 v1, 0, v0
	v_mul_f32_e64 v0, |v0|, s11
	v_exp_f32_e32 v0, v0
	s_nop 0
	v_add_f32_e32 v0, 1.0, v0
	v_cmp_gt_f32_e32 vcc, s12, v0
	s_nop 1
	v_cndmask_b32_e64 v2, 0, 32, vcc
	v_ldexp_f32 v0, v0, v2
	v_log_f32_e32 v0, v0
	s_nop 0
	v_mul_f32_e32 v2, 0x3f317217, v0
	v_fma_f32 v2, v0, s13, -v2
	v_fmac_f32_e32 v2, 0x3377d1cf, v0
	v_fmac_f32_e32 v2, 0x3f317217, v0
	v_cmp_lt_f32_e64 s[0:1], |v0|, s36
	s_nop 1
	v_cndmask_b32_e64 v0, v0, v2, s[0:1]
	v_cndmask_b32_e32 v2, 0, v60, vcc
	v_sub_f32_e32 v0, v0, v2
	v_sub_f32_e32 v0, v1, v0
	v_fmamk_f32 v119, v0, 0x3d800000, v118
	ds_read_b128 v[210:213], v5 offset:3328
	ds_read_b128 v[214:217], v5 offset:3344
	ds_read_b128 v[218:221], v5 offset:3360
	ds_read_b128 v[222:225], v5 offset:3376
	s_waitcnt lgkmcnt(4)
	v_fma_f32 v120, v65, v240, v69
	v_fmac_f32_e32 v120, v66, v241
	v_fmac_f32_e32 v120, v67, v242
	v_fmac_f32_e32 v120, v68, v243
	v_fmac_f32_e32 v120, v55, v244
	v_fmac_f32_e32 v120, v62, v245
	v_fmac_f32_e32 v120, v63, v246
	v_fmac_f32_e32 v120, v64, v247
	v_fmac_f32_e32 v120, v52, v248
	v_fmac_f32_e32 v120, v53, v249
	v_fmac_f32_e32 v120, v50, v250
	v_fmac_f32_e32 v120, v51, v251
	v_pk_mul_f32 v[0:1], v[48:49], v[252:253]
	s_nop 0
	v_add_f32_e32 v0, v120, v0
	v_add_f32_e32 v120, v0, v1
	v_pk_mul_f32 v[0:1], v[46:47], v[254:255]
	s_nop 0
	v_add_f32_e32 v0, v120, v0
	v_add_f32_e32 v0, v0, v1
	v_min_f32_e32 v1, 0, v0
	v_mul_f32_e64 v0, |v0|, s11
	v_exp_f32_e32 v0, v0
	s_nop 0
	v_add_f32_e32 v0, 1.0, v0
	v_cmp_gt_f32_e32 vcc, s12, v0
	s_nop 1
	v_cndmask_b32_e64 v2, 0, 32, vcc
	v_ldexp_f32 v0, v0, v2
	v_log_f32_e32 v0, v0
	s_nop 0
	v_mul_f32_e32 v2, 0x3f317217, v0
	v_fma_f32 v2, v0, s13, -v2
	v_fmac_f32_e32 v2, 0x3377d1cf, v0
	v_fmac_f32_e32 v2, 0x3f317217, v0
	v_cmp_lt_f32_e64 s[0:1], |v0|, s36
	s_nop 1
	v_cndmask_b32_e64 v0, v0, v2, s[0:1]
	v_cndmask_b32_e32 v2, 0, v60, vcc
	v_sub_f32_e32 v0, v0, v2
	v_sub_f32_e32 v0, v1, v0
	v_fmamk_f32 v120, v0, 0x3d800000, v119
	ds_read_b128 v[240:243], v5 offset:3392
	ds_read_b128 v[244:247], v5 offset:3408
	ds_read_b128 v[248:251], v5 offset:3424
	ds_read_b128 v[252:255], v5 offset:3440
	s_waitcnt lgkmcnt(4)
	v_fma_f32 v121, v65, v210, v69
	v_fmac_f32_e32 v121, v66, v211
	v_fmac_f32_e32 v121, v67, v212
	v_fmac_f32_e32 v121, v68, v213
	v_fmac_f32_e32 v121, v55, v214
	v_fmac_f32_e32 v121, v62, v215
	v_fmac_f32_e32 v121, v63, v216
	v_fmac_f32_e32 v121, v64, v217
	v_fmac_f32_e32 v121, v52, v218
	v_fmac_f32_e32 v121, v53, v219
	v_fmac_f32_e32 v121, v50, v220
	v_fmac_f32_e32 v121, v51, v221
	v_pk_mul_f32 v[0:1], v[48:49], v[222:223]
	s_nop 0
	v_add_f32_e32 v0, v121, v0
	v_add_f32_e32 v121, v0, v1
	v_pk_mul_f32 v[0:1], v[46:47], v[224:225]
	s_nop 0
	v_add_f32_e32 v0, v121, v0
	v_add_f32_e32 v0, v0, v1
	v_min_f32_e32 v1, 0, v0
	v_mul_f32_e64 v0, |v0|, s11
	v_exp_f32_e32 v0, v0
	s_nop 0
	v_add_f32_e32 v0, 1.0, v0
	v_cmp_gt_f32_e32 vcc, s12, v0
	s_nop 1
	v_cndmask_b32_e64 v2, 0, 32, vcc
	v_ldexp_f32 v0, v0, v2
	v_log_f32_e32 v0, v0
	s_nop 0
	v_mul_f32_e32 v2, 0x3f317217, v0
	v_fma_f32 v2, v0, s13, -v2
	v_fmac_f32_e32 v2, 0x3377d1cf, v0
	v_fmac_f32_e32 v2, 0x3f317217, v0
	v_cmp_lt_f32_e64 s[0:1], |v0|, s36
	s_nop 1
	v_cndmask_b32_e64 v0, v0, v2, s[0:1]
	v_cndmask_b32_e32 v2, 0, v60, vcc
	v_sub_f32_e32 v0, v0, v2
	v_sub_f32_e32 v0, v1, v0
	v_fmamk_f32 v121, v0, 0x3d800000, v120
	ds_read_b128 v[210:213], v5 offset:3456
	ds_read_b128 v[214:217], v5 offset:3472
	ds_read_b128 v[218:221], v5 offset:3488
	ds_read_b128 v[222:225], v5 offset:3504
	s_waitcnt lgkmcnt(4)
; __device__ __forceinline__ float log_sigmoid(float x) { return fminf(x, 0.f) - __logf(1.f + __expf(-fabsf(x))); }
; __device__ __forceinline__ void gla_prep_item(LAS unsigned char* lds, int item, const bf16_t* Z, const float* W2, const float* Bg, bf16_t* KDT, float* DEC) {
;     ...
;     float bend = 0.f; float gv[64];
; #pragma unroll
;     for (int t = 0; t < 64; ++t) {
;         float x = bias;
; #pragma unroll
;         for (int r = 0; r < 16; ++r) x += zgs[t * 16 + r] * w[r];
;         gv[t] = log_sigmoid(x) * (1.f / 16.f); bend += gv[t];
;     }
	v_fma_f32 v122, v65, v240, v69
	v_fmac_f32_e32 v122, v66, v241
	v_fmac_f32_e32 v122, v67, v242
	v_fmac_f32_e32 v122, v68, v243
	v_fmac_f32_e32 v122, v55, v244
	v_fmac_f32_e32 v122, v62, v245
	v_fmac_f32_e32 v122, v63, v246
	v_fmac_f32_e32 v122, v64, v247
	v_fmac_f32_e32 v122, v52, v248
	v_fmac_f32_e32 v122, v53, v249
	v_fmac_f32_e32 v122, v50, v250
	v_fmac_f32_e32 v122, v51, v251
	v_pk_mul_f32 v[0:1], v[48:49], v[252:253]
	s_nop 0
	v_add_f32_e32 v0, v122, v0
	v_add_f32_e32 v122, v0, v1
	v_pk_mul_f32 v[0:1], v[46:47], v[254:255]
	s_nop 0
	v_add_f32_e32 v0, v122, v0
	v_add_f32_e32 v0, v0, v1
	v_min_f32_e32 v1, 0, v0
	v_mul_f32_e64 v0, |v0|, s11
	v_exp_f32_e32 v0, v0
	s_nop 0
	v_add_f32_e32 v0, 1.0, v0
	v_cmp_gt_f32_e32 vcc, s12, v0
	s_nop 1
	v_cndmask_b32_e64 v2, 0, 32, vcc
	v_ldexp_f32 v0, v0, v2
	v_log_f32_e32 v0, v0
	s_nop 0
	v_mul_f32_e32 v2, 0x3f317217, v0
	v_fma_f32 v2, v0, s13, -v2
	v_fmac_f32_e32 v2, 0x3377d1cf, v0
	v_fmac_f32_e32 v2, 0x3f317217, v0
	v_cmp_lt_f32_e64 s[0:1], |v0|, s36
	s_nop 1
	v_cndmask_b32_e64 v0, v0, v2, s[0:1]
	v_cndmask_b32_e32 v2, 0, v60, vcc
	v_sub_f32_e32 v0, v0, v2
	v_sub_f32_e32 v0, v1, v0
	v_fmamk_f32 v122, v0, 0x3d800000, v121
	ds_read_b128 v[240:243], v5 offset:3520
	ds_read_b128 v[244:247], v5 offset:3536
	ds_read_b128 v[248:251], v5 offset:3552
	ds_read_b128 v[252:255], v5 offset:3568
	s_waitcnt lgkmcnt(4)
	v_fma_f32 v123, v65, v210, v69
	v_fmac_f32_e32 v123, v66, v211
	v_fmac_f32_e32 v123, v67, v212
	v_fmac_f32_e32 v123, v68, v213
	v_fmac_f32_e32 v123, v55, v214
	v_fmac_f32_e32 v123, v62, v215
	v_fmac_f32_e32 v123, v63, v216
	v_fmac_f32_e32 v123, v64, v217
	v_fmac_f32_e32 v123, v52, v218
	v_fmac_f32_e32 v123, v53, v219
	v_fmac_f32_e32 v123, v50, v220
	v_fmac_f32_e32 v123, v51, v221
	v_pk_mul_f32 v[0:1], v[48:49], v[222:223]
	s_nop 0
	v_add_f32_e32 v0, v123, v0
	v_add_f32_e32 v123, v0, v1
	v_pk_mul_f32 v[0:1], v[46:47], v[224:225]
	s_nop 0
	v_add_f32_e32 v0, v123, v0
	v_add_f32_e32 v0, v0, v1
	v_min_f32_e32 v1, 0, v0
	v_mul_f32_e64 v0, |v0|, s11
	v_exp_f32_e32 v0, v0
	s_nop 0
	v_add_f32_e32 v0, 1.0, v0
	v_cmp_gt_f32_e32 vcc, s12, v0
	s_nop 1
	v_cndmask_b32_e64 v2, 0, 32, vcc
	v_ldexp_f32 v0, v0, v2
	v_log_f32_e32 v0, v0
	s_nop 0
	v_mul_f32_e32 v2, 0x3f317217, v0
	v_fma_f32 v2, v0, s13, -v2
	v_fmac_f32_e32 v2, 0x3377d1cf, v0
	v_fmac_f32_e32 v2, 0x3f317217, v0
	v_cmp_lt_f32_e64 s[0:1], |v0|, s36
	s_nop 1
	v_cndmask_b32_e64 v0, v0, v2, s[0:1]
	v_cndmask_b32_e32 v2, 0, v60, vcc
	v_sub_f32_e32 v0, v0, v2
	v_sub_f32_e32 v0, v1, v0
	v_fmamk_f32 v123, v0, 0x3d800000, v122
	ds_read_b128 v[210:213], v5 offset:3584
	ds_read_b128 v[214:217], v5 offset:3600
	ds_read_b128 v[218:221], v5 offset:3616
	ds_read_b128 v[222:225], v5 offset:3632
	s_waitcnt lgkmcnt(4)
	v_fma_f32 v124, v65, v240, v69
	v_fmac_f32_e32 v124, v66, v241
	v_fmac_f32_e32 v124, v67, v242
	v_fmac_f32_e32 v124, v68, v243
	v_fmac_f32_e32 v124, v55, v244
	v_fmac_f32_e32 v124, v62, v245
	v_fmac_f32_e32 v124, v63, v246
	v_fmac_f32_e32 v124, v64, v247
	v_fmac_f32_e32 v124, v52, v248
	v_fmac_f32_e32 v124, v53, v249
	v_fmac_f32_e32 v124, v50, v250
	v_fmac_f32_e32 v124, v51, v251
	v_pk_mul_f32 v[0:1], v[48:49], v[252:253]
	s_nop 0
	v_add_f32_e32 v0, v124, v0
	v_add_f32_e32 v124, v0, v1
	v_pk_mul_f32 v[0:1], v[46:47], v[254:255]
	s_nop 0
	v_add_f32_e32 v0, v124, v0
	v_add_f32_e32 v0, v0, v1
	v_min_f32_e32 v1, 0, v0
	v_mul_f32_e64 v0, |v0|, s11
	v_exp_f32_e32 v0, v0
	s_nop 0
	v_add_f32_e32 v0, 1.0, v0
	v_cmp_gt_f32_e32 vcc, s12, v0
	s_nop 1
	v_cndmask_b32_e64 v2, 0, 32, vcc
	v_ldexp_f32 v0, v0, v2
	v_log_f32_e32 v0, v0
	s_nop 0
	v_mul_f32_e32 v2, 0x3f317217, v0
	v_fma_f32 v2, v0, s13, -v2
	v_fmac_f32_e32 v2, 0x3377d1cf, v0
	v_fmac_f32_e32 v2, 0x3f317217, v0
	v_cmp_lt_f32_e64 s[0:1], |v0|, s36
	s_nop 1
	v_cndmask_b32_e64 v0, v0, v2, s[0:1]
	v_cndmask_b32_e32 v2, 0, v60, vcc
	v_sub_f32_e32 v0, v0, v2
	v_sub_f32_e32 v0, v1, v0
	v_fmamk_f32 v124, v0, 0x3d800000, v123
	ds_read_b128 v[240:243], v5 offset:3648
	ds_read_b128 v[244:247], v5 offset:3664
	ds_read_b128 v[248:251], v5 offset:3680
	ds_read_b128 v[252:255], v5 offset:3696
	s_waitcnt lgkmcnt(4)
	v_fma_f32 v125, v65, v210, v69
	v_fmac_f32_e32 v125, v66, v211
	v_fmac_f32_e32 v125, v67, v212
	v_fmac_f32_e32 v125, v68, v213
	v_fmac_f32_e32 v125, v55, v214
	v_fmac_f32_e32 v125, v62, v215
	v_fmac_f32_e32 v125, v63, v216
	v_fmac_f32_e32 v125, v64, v217
	v_fmac_f32_e32 v125, v52, v218
	v_fmac_f32_e32 v125, v53, v219
	v_fmac_f32_e32 v125, v50, v220
	v_fmac_f32_e32 v125, v51, v221
	v_pk_mul_f32 v[0:1], v[48:49], v[222:223]
	s_nop 0
	v_add_f32_e32 v0, v125, v0
	v_add_f32_e32 v125, v0, v1
	v_pk_mul_f32 v[0:1], v[46:47], v[224:225]
	s_nop 0
	v_add_f32_e32 v0, v125, v0
	v_add_f32_e32 v0, v0, v1
	v_min_f32_e32 v1, 0, v0
	v_mul_f32_e64 v0, |v0|, s11
	v_exp_f32_e32 v0, v0
	s_nop 0
	v_add_f32_e32 v0, 1.0, v0
	v_cmp_gt_f32_e32 vcc, s12, v0
	s_nop 1
	v_cndmask_b32_e64 v2, 0, 32, vcc
	v_ldexp_f32 v0, v0, v2
	v_log_f32_e32 v0, v0
	s_nop 0
	v_mul_f32_e32 v2, 0x3f317217, v0
	v_fma_f32 v2, v0, s13, -v2
	v_fmac_f32_e32 v2, 0x3377d1cf, v0
	v_fmac_f32_e32 v2, 0x3f317217, v0
	v_cmp_lt_f32_e64 s[0:1], |v0|, s36
	s_nop 1
	v_cndmask_b32_e64 v0, v0, v2, s[0:1]
	v_cndmask_b32_e32 v2, 0, v60, vcc
	v_sub_f32_e32 v0, v0, v2
	v_sub_f32_e32 v0, v1, v0
	v_fmamk_f32 v125, v0, 0x3d800000, v124
	ds_read_b128 v[210:213], v5 offset:3712
	ds_read_b128 v[214:217], v5 offset:3728
	ds_read_b128 v[218:221], v5 offset:3744
	ds_read_b128 v[222:225], v5 offset:3760
	s_waitcnt lgkmcnt(4)
; __device__ __forceinline__ float log_sigmoid(float x) { return fminf(x, 0.f) - __logf(1.f + __expf(-fabsf(x))); }
; __device__ __forceinline__ void gla_prep_item(LAS unsigned char* lds, int item, const bf16_t* Z, const float* W2, const float* Bg, bf16_t* KDT, float* DEC) {
;     ...
;     float bend = 0.f; float gv[64];
; #pragma unroll
;     for (int t = 0; t < 64; ++t) {
;         float x = bias;
; #pragma unroll
;         for (int r = 0; r < 16; ++r) x += zgs[t * 16 + r] * w[r];
;         gv[t] = log_sigmoid(x) * (1.f / 16.f); bend += gv[t];
;     }
	v_fma_f32 v126, v65, v240, v69
	v_fmac_f32_e32 v126, v66, v241
	v_fmac_f32_e32 v126, v67, v242
	v_fmac_f32_e32 v126, v68, v243
	v_fmac_f32_e32 v126, v55, v244
	v_fmac_f32_e32 v126, v62, v245
	v_fmac_f32_e32 v126, v63, v246
	v_fmac_f32_e32 v126, v64, v247
	v_fmac_f32_e32 v126, v52, v248
	v_fmac_f32_e32 v126, v53, v249
	v_fmac_f32_e32 v126, v50, v250
	v_fmac_f32_e32 v126, v51, v251
	v_pk_mul_f32 v[0:1], v[48:49], v[252:253]
	s_nop 0
	v_add_f32_e32 v0, v126, v0
	v_add_f32_e32 v126, v0, v1
	v_pk_mul_f32 v[0:1], v[46:47], v[254:255]
	s_nop 0
	v_add_f32_e32 v0, v126, v0
	v_add_f32_e32 v0, v0, v1
	v_min_f32_e32 v1, 0, v0
	v_mul_f32_e64 v0, |v0|, s11
	v_exp_f32_e32 v0, v0
	s_nop 0
	v_add_f32_e32 v0, 1.0, v0
	v_cmp_gt_f32_e32 vcc, s12, v0
	s_nop 1
	v_cndmask_b32_e64 v2, 0, 32, vcc
	v_ldexp_f32 v0, v0, v2
	v_log_f32_e32 v0, v0
	s_nop 0
	v_mul_f32_e32 v2, 0x3f317217, v0
	v_fma_f32 v2, v0, s13, -v2
	v_fmac_f32_e32 v2, 0x3377d1cf, v0
	v_fmac_f32_e32 v2, 0x3f317217, v0
	v_cmp_lt_f32_e64 s[0:1], |v0|, s36
	s_nop 1
	v_cndmask_b32_e64 v0, v0, v2, s[0:1]
	v_cndmask_b32_e32 v2, 0, v60, vcc
	v_sub_f32_e32 v0, v0, v2
	v_sub_f32_e32 v0, v1, v0
	v_fmamk_f32 v126, v0, 0x3d800000, v125
	ds_read_b128 v[240:243], v5 offset:3776
	ds_read_b128 v[244:247], v5 offset:3792
	ds_read_b128 v[248:251], v5 offset:3808
	ds_read_b128 v[252:255], v5 offset:3824
	s_waitcnt lgkmcnt(4)
	v_fma_f32 v127, v65, v210, v69
	v_fmac_f32_e32 v127, v66, v211
	v_fmac_f32_e32 v127, v67, v212
	v_fmac_f32_e32 v127, v68, v213
	v_fmac_f32_e32 v127, v55, v214
	v_fmac_f32_e32 v127, v62, v215
	v_fmac_f32_e32 v127, v63, v216
	v_fmac_f32_e32 v127, v64, v217
	v_fmac_f32_e32 v127, v52, v218
	v_fmac_f32_e32 v127, v53, v219
	v_fmac_f32_e32 v127, v50, v220
	v_fmac_f32_e32 v127, v51, v221
	v_pk_mul_f32 v[0:1], v[48:49], v[222:223]
	s_nop 0
	v_add_f32_e32 v0, v127, v0
	v_add_f32_e32 v127, v0, v1
	v_pk_mul_f32 v[0:1], v[46:47], v[224:225]
	s_nop 0
	v_add_f32_e32 v0, v127, v0
	v_add_f32_e32 v0, v0, v1
	v_min_f32_e32 v1, 0, v0
	v_mul_f32_e64 v0, |v0|, s11
	v_exp_f32_e32 v0, v0
	s_nop 0
	v_add_f32_e32 v0, 1.0, v0
	v_cmp_gt_f32_e32 vcc, s12, v0
	s_nop 1
	v_cndmask_b32_e64 v2, 0, 32, vcc
	v_ldexp_f32 v0, v0, v2
	v_log_f32_e32 v0, v0
	s_nop 0
	v_mul_f32_e32 v2, 0x3f317217, v0
	v_fma_f32 v2, v0, s13, -v2
	v_fmac_f32_e32 v2, 0x3377d1cf, v0
	v_fmac_f32_e32 v2, 0x3f317217, v0
	v_cmp_lt_f32_e64 s[0:1], |v0|, s36
	s_nop 1
	v_cndmask_b32_e64 v0, v0, v2, s[0:1]
	v_cndmask_b32_e32 v2, 0, v60, vcc
	v_sub_f32_e32 v0, v0, v2
	v_sub_f32_e32 v0, v1, v0
	v_fmamk_f32 v127, v0, 0x3d800000, v126
	ds_read_b128 v[210:213], v5 offset:3840
	ds_read_b128 v[214:217], v5 offset:3856
	ds_read_b128 v[218:221], v5 offset:3872
	ds_read_b128 v[222:225], v5 offset:3888
	s_waitcnt lgkmcnt(4)
	v_fma_f32 v128, v65, v240, v69
	v_fmac_f32_e32 v128, v66, v241
	v_fmac_f32_e32 v128, v67, v242
	v_fmac_f32_e32 v128, v68, v243
	v_fmac_f32_e32 v128, v55, v244
	v_fmac_f32_e32 v128, v62, v245
	v_fmac_f32_e32 v128, v63, v246
	v_fmac_f32_e32 v128, v64, v247
	v_fmac_f32_e32 v128, v52, v248
	v_fmac_f32_e32 v128, v53, v249
	v_fmac_f32_e32 v128, v50, v250
	v_fmac_f32_e32 v128, v51, v251
	v_pk_mul_f32 v[0:1], v[48:49], v[252:253]
	s_nop 0
	v_add_f32_e32 v0, v128, v0
	v_add_f32_e32 v128, v0, v1
	v_pk_mul_f32 v[0:1], v[46:47], v[254:255]
	s_nop 0
	v_add_f32_e32 v0, v128, v0
	v_add_f32_e32 v0, v0, v1
	v_min_f32_e32 v1, 0, v0
	v_mul_f32_e64 v0, |v0|, s11
	v_exp_f32_e32 v0, v0
	s_nop 0
	v_add_f32_e32 v0, 1.0, v0
	v_cmp_gt_f32_e32 vcc, s12, v0
	s_nop 1
	v_cndmask_b32_e64 v2, 0, 32, vcc
	v_ldexp_f32 v0, v0, v2
	v_log_f32_e32 v0, v0
	s_nop 0
	v_mul_f32_e32 v2, 0x3f317217, v0
	v_fma_f32 v2, v0, s13, -v2
	v_fmac_f32_e32 v2, 0x3377d1cf, v0
	v_fmac_f32_e32 v2, 0x3f317217, v0
	v_cmp_lt_f32_e64 s[0:1], |v0|, s36
	s_nop 1
	v_cndmask_b32_e64 v0, v0, v2, s[0:1]
	v_cndmask_b32_e32 v2, 0, v60, vcc
	v_sub_f32_e32 v0, v0, v2
	v_sub_f32_e32 v0, v1, v0
	v_fmamk_f32 v128, v0, 0x3d800000, v127
	ds_read_b128 v[240:243], v5 offset:3904
	ds_read_b128 v[244:247], v5 offset:3920
	ds_read_b128 v[248:251], v5 offset:3936
	ds_read_b128 v[252:255], v5 offset:3952
	s_waitcnt lgkmcnt(4)
	v_fma_f32 v129, v65, v210, v69
	v_fmac_f32_e32 v129, v66, v211
	v_fmac_f32_e32 v129, v67, v212
	v_fmac_f32_e32 v129, v68, v213
	v_fmac_f32_e32 v129, v55, v214
	v_fmac_f32_e32 v129, v62, v215
	v_fmac_f32_e32 v129, v63, v216
	v_fmac_f32_e32 v129, v64, v217
	v_fmac_f32_e32 v129, v52, v218
	v_fmac_f32_e32 v129, v53, v219
	v_fmac_f32_e32 v129, v50, v220
	v_fmac_f32_e32 v129, v51, v221
	v_pk_mul_f32 v[0:1], v[48:49], v[222:223]
	s_nop 0
	v_add_f32_e32 v0, v129, v0
	v_add_f32_e32 v129, v0, v1
	v_pk_mul_f32 v[0:1], v[46:47], v[224:225]
	s_nop 0
	v_add_f32_e32 v0, v129, v0
	v_add_f32_e32 v0, v0, v1
	v_min_f32_e32 v1, 0, v0
	v_mul_f32_e64 v0, |v0|, s11
	v_exp_f32_e32 v0, v0
	s_nop 0
	v_add_f32_e32 v0, 1.0, v0
	v_cmp_gt_f32_e32 vcc, s12, v0
	s_nop 1
	v_cndmask_b32_e64 v2, 0, 32, vcc
	v_ldexp_f32 v0, v0, v2
	v_log_f32_e32 v0, v0
	s_nop 0
	v_mul_f32_e32 v2, 0x3f317217, v0
	v_fma_f32 v2, v0, s13, -v2
	v_fmac_f32_e32 v2, 0x3377d1cf, v0
	v_fmac_f32_e32 v2, 0x3f317217, v0
	v_cmp_lt_f32_e64 s[0:1], |v0|, s36
	s_nop 1
	v_cndmask_b32_e64 v0, v0, v2, s[0:1]
	v_cndmask_b32_e32 v2, 0, v60, vcc
	v_sub_f32_e32 v0, v0, v2
	v_sub_f32_e32 v0, v1, v0
	v_fmamk_f32 v129, v0, 0x3d800000, v128
	ds_read_b128 v[210:213], v5 offset:3968
	ds_read_b128 v[214:217], v5 offset:3984
	ds_read_b128 v[218:221], v5 offset:4000
	ds_read_b128 v[222:225], v5 offset:4016
	s_waitcnt lgkmcnt(4)
; __device__ __forceinline__ float log_sigmoid(float x) { return fminf(x, 0.f) - __logf(1.f + __expf(-fabsf(x))); }
; __device__ __forceinline__ void gla_prep_item(LAS unsigned char* lds, int item, const bf16_t* Z, const float* W2, const float* Bg, bf16_t* KDT, float* DEC) {
;     ...
;     float bend = 0.f; float gv[64];
; #pragma unroll
;     for (int t = 0; t < 64; ++t) {
;         float x = bias;
; #pragma unroll
;         for (int r = 0; r < 16; ++r) x += zgs[t * 16 + r] * w[r];
;         gv[t] = log_sigmoid(x) * (1.f / 16.f); bend += gv[t];
;     }
;     float bc = 0.f;
;     bf16_t* dst = KDT + (size_t)((b * 4 + h) * 32 + c) * 8192 + (size_t)((kd >> 4) * 2 * 64 + (kd & 15)) * 8;
;     const bf16_t* gk = Z + row0 * ZLD + ZGK + col;
; #pragma unroll
;     for (int t8 = 0; t8 < 8; ++t8) {
;         float kv[8];
; #pragma unroll
;         for (int e = 0; e < 8; ++e) {
;             const int t = t8 * 8 + e;
;             bc += gv[t];
;             kv[e] = bf2f(gk[(size_t)t * ZLD]) * __expf(bend - bc);
	v_fma_f32 v130, v65, v240, v69
	v_fmac_f32_e32 v130, v66, v241
	v_fmac_f32_e32 v130, v67, v242
	v_fmac_f32_e32 v130, v68, v243
	v_fmac_f32_e32 v130, v55, v244
	v_fmac_f32_e32 v130, v62, v245
	v_fmac_f32_e32 v130, v63, v246
	v_fmac_f32_e32 v130, v64, v247
	v_fmac_f32_e32 v130, v52, v248
	v_fmac_f32_e32 v130, v53, v249
	v_pk_mul_f32 v[0:1], v[50:51], v[250:251]
	s_nop 0
	v_add_f32_e32 v0, v130, v0
	v_add_f32_e32 v130, v0, v1
	v_pk_mul_f32 v[0:1], v[48:49], v[252:253]
	s_nop 0
	v_add_f32_e32 v0, v130, v0
	v_add_f32_e32 v130, v0, v1
	v_pk_mul_f32 v[0:1], v[46:47], v[254:255]
	s_nop 0
	v_add_f32_e32 v0, v130, v0
	v_add_f32_e32 v0, v0, v1
	v_min_f32_e32 v1, 0, v0
	v_mul_f32_e64 v0, |v0|, s11
	v_exp_f32_e32 v0, v0
	s_nop 0
	v_add_f32_e32 v0, 1.0, v0
	v_cmp_gt_f32_e32 vcc, s12, v0
	s_nop 1
	v_cndmask_b32_e64 v2, 0, 32, vcc
	v_ldexp_f32 v0, v0, v2
	v_log_f32_e32 v0, v0
	s_nop 0
	v_mul_f32_e32 v2, 0x3f317217, v0
	v_fma_f32 v2, v0, s13, -v2
	v_fmac_f32_e32 v2, 0x3377d1cf, v0
	v_fmac_f32_e32 v2, 0x3f317217, v0
	v_cmp_lt_f32_e64 s[0:1], |v0|, s36
	s_nop 1
	v_cndmask_b32_e64 v0, v0, v2, s[0:1]
	v_cndmask_b32_e32 v2, 0, v60, vcc
	v_sub_f32_e32 v0, v0, v2
	v_sub_f32_e32 v0, v1, v0
	v_fmamk_f32 v130, v0, 0x3d800000, v129
	ds_read_b128 v[240:243], v5 offset:4032
	ds_read_b128 v[244:247], v5 offset:4048
	ds_read_b128 v[248:251], v5 offset:4064
	ds_read_b128 v[252:255], v5 offset:4080
	s_waitcnt lgkmcnt(4)
	v_fma_f32 v131, v65, v210, v69
	v_fmac_f32_e32 v131, v66, v211
	v_fmac_f32_e32 v131, v67, v212
	v_fmac_f32_e32 v131, v68, v213
	v_fmac_f32_e32 v131, v55, v214
	v_fmac_f32_e32 v131, v62, v215
	v_fmac_f32_e32 v131, v63, v216
	v_fmac_f32_e32 v131, v64, v217
	v_fmac_f32_e32 v131, v52, v218
	v_fmac_f32_e32 v131, v53, v219
	v_pk_mul_f32 v[0:1], v[50:51], v[220:221]
	s_nop 0
	v_add_f32_e32 v0, v131, v0
	v_add_f32_e32 v131, v0, v1
	v_pk_mul_f32 v[0:1], v[48:49], v[222:223]
	s_nop 0
	v_add_f32_e32 v0, v131, v0
	v_add_f32_e32 v131, v0, v1
	v_pk_mul_f32 v[0:1], v[46:47], v[224:225]
	s_nop 0
	v_add_f32_e32 v0, v131, v0
	v_add_f32_e32 v0, v0, v1
	v_min_f32_e32 v1, 0, v0
	v_mul_f32_e64 v0, |v0|, s11
	v_exp_f32_e32 v0, v0
	s_nop 0
	v_add_f32_e32 v0, 1.0, v0
	v_cmp_gt_f32_e32 vcc, s12, v0
	s_nop 1
	v_cndmask_b32_e64 v2, 0, 32, vcc
	v_ldexp_f32 v0, v0, v2
	v_log_f32_e32 v0, v0
	s_nop 0
	v_mul_f32_e32 v2, 0x3f317217, v0
	v_fma_f32 v2, v0, s13, -v2
	v_fmac_f32_e32 v2, 0x3377d1cf, v0
	v_fmac_f32_e32 v2, 0x3f317217, v0
	v_cmp_lt_f32_e64 s[0:1], |v0|, s36
	s_nop 1
	v_cndmask_b32_e64 v0, v0, v2, s[0:1]
	v_cndmask_b32_e32 v2, 0, v60, vcc
	v_sub_f32_e32 v0, v0, v2
	v_sub_f32_e32 v0, v1, v0
	v_fmamk_f32 v131, v0, 0x3d800000, v130
	s_waitcnt lgkmcnt(0)
	v_fmac_f32_e32 v69, v65, v240
	v_fmac_f32_e32 v69, v66, v241
	v_fmac_f32_e32 v69, v67, v242
	v_fmac_f32_e32 v69, v68, v243
	v_fmac_f32_e32 v69, v55, v244
	v_fmac_f32_e32 v69, v62, v245
	v_fmac_f32_e32 v69, v63, v246
	v_fmac_f32_e32 v69, v64, v247
	v_pk_mul_f32 v[0:1], v[52:53], v[248:249]
	s_nop 0
	v_add_f32_e32 v0, v69, v0
	v_add_f32_e32 v52, v0, v1
	v_pk_mul_f32 v[0:1], v[50:51], v[250:251]
	s_nop 0
	v_add_f32_e32 v0, v52, v0
	v_add_f32_e32 v50, v0, v1
	v_pk_mul_f32 v[0:1], v[48:49], v[252:253]
	s_nop 0
	v_add_f32_e32 v0, v50, v0
	v_add_f32_e32 v48, v0, v1
	v_pk_mul_f32 v[0:1], v[46:47], v[254:255]
	s_nop 0
	v_add_f32_e32 v0, v48, v0
	v_add_f32_e32 v0, v0, v1
	v_min_f32_e32 v1, 0, v0
	v_mul_f32_e64 v0, |v0|, s11
	v_exp_f32_e32 v0, v0
	s_nop 0
	v_add_f32_e32 v0, 1.0, v0
	v_cmp_gt_f32_e32 vcc, s12, v0
	s_nop 1
	v_cndmask_b32_e64 v2, 0, 32, vcc
	v_ldexp_f32 v0, v0, v2
	v_log_f32_e32 v0, v0
	s_nop 0
	v_mul_f32_e32 v2, 0x3f317217, v0
	v_fma_f32 v2, v0, s13, -v2
	v_fmac_f32_e32 v2, 0x3377d1cf, v0
	v_fmac_f32_e32 v2, 0x3f317217, v0
	v_cmp_lt_f32_e64 s[0:1], |v0|, s36
	s_nop 1
	v_cndmask_b32_e64 v0, v0, v2, s[0:1]
	v_mad_u64_u32 v[46:47], s[0:1], s6, v59, v[42:43]
	s_movk_i32 s0, 0x2000
	v_cndmask_b32_e32 v2, 0, v60, vcc
	v_add_u32_e32 v47, s7, v47
	v_add_co_u32_e32 v50, vcc, s0, v46
	v_sub_f32_e32 v0, v0, v2
	s_nop 0
	v_addc_co_u32_e32 v51, vcc, 0, v47, vcc
	s_waitcnt vmcnt(0)
	v_mov_b32_e32 v50, v141
	s_nop 0
	v_mov_b32_e32 v52, v140
	s_movk_i32 s0, 0x3000
	v_sub_f32_e32 v0, v1, v0
	v_fmamk_f32 v62, v0, 0x3d800000, v131
	v_sub_f32_e32 v48, v62, v54
	v_sub_f32_e32 v49, v62, v70
	v_mul_f32_e32 v48, 0x3fb8aa3b, v48
	v_mul_f32_e32 v49, 0x3fb8aa3b, v49
	v_exp_f32_e32 v48, v48
	v_exp_f32_e32 v49, v49
	v_lshl_add_u32 v0, s8, 7, v56
	v_or_b32_e32 v0, s9, v0
	v_ashrrev_i32_e32 v1, 31, v0
	v_lshlrev_b64 v[2:3], 14, v[0:1]
	v_lshl_add_u64 v[2:3], v[38:39], 0, v[2:3]
	v_lshlrev_b64 v[0:1], 9, v[0:1]
	v_lshl_add_u64 v[0:1], v[40:41], 0, v[0:1]
	s_nop 0
	v_lshlrev_b32_e32 v51, 16, v50
	s_nop 0
	v_lshlrev_b32_e32 v50, 16, v52
	v_add_co_u32_e32 v52, vcc, s0, v46
	s_movk_i32 s0, 0x5000
	s_nop 0
	v_addc_co_u32_e32 v53, vcc, 0, v47, vcc
	v_mov_b32_e32 v54, v142
	v_add_co_u32_e32 v52, vcc, s0, v46
	s_movk_i32 s0, 0x6000
	s_nop 0
	v_addc_co_u32_e32 v53, vcc, 0, v47, vcc
	v_mov_b32_e32 v52, v143
	v_pk_mul_f32 v[48:49], v[48:49], v[50:51]
	v_sub_f32_e32 v50, v62, v71
	v_sub_f32_e32 v51, v62, v72
	v_mul_f32_e32 v50, 0x3fb8aa3b, v50
	v_mul_f32_e32 v51, 0x3fb8aa3b, v51
	v_exp_f32_e32 v50, v50
	v_exp_f32_e32 v51, v51
	v_cvt_pk_bf16_f32 v48, v48, v49
	s_nop 0
	v_lshlrev_b32_e32 v53, 16, v52
	v_lshlrev_b32_e32 v52, 16, v54
	v_add_co_u32_e32 v54, vcc, s0, v46
	s_mov_b32 s0, 0x8000
	s_nop 0
	v_addc_co_u32_e32 v55, vcc, 0, v47, vcc
	v_mov_b32_e32 v63, v144
	v_add_co_u32_e32 v54, vcc, s0, v46
	s_mov_b32 s0, 0x9000
	s_nop 0
	v_addc_co_u32_e32 v55, vcc, 0, v47, vcc
	v_mov_b32_e32 v54, v145
	v_add_co_u32_e32 v64, vcc, s0, v46
	s_mov_b32 s0, 0xb000
	s_nop 0
; __device__ __forceinline__ unsigned pk2(float lo, float hi) { f32x2_t v = {lo, hi}; bf16x2_t b = __builtin_convertvector(v, bf16x2_t); return __builtin_bit_cast(unsigned, b); }
; __device__ __forceinline__ void gla_prep_item(LAS unsigned char* lds, int item, const bf16_t* Z, const float* W2, const float* Bg, bf16_t* KDT, float* DEC) {
;     ...
; #pragma unroll
;     for (int t8 = 0; t8 < 8; ++t8) {
;         float kv[8];
; #pragma unroll
;         for (int e = 0; e < 8; ++e) {
;             const int t = t8 * 8 + e;
;             bc += gv[t];
;             kv[e] = bf2f(gk[(size_t)t * ZLD]) * __expf(bend - bc);
;         }
;         u32x4 o; o.x = pk2(kv[0], kv[1]); o.y = pk2(kv[2], kv[3]); o.z = pk2(kv[4], kv[5]); o.w = pk2(kv[6], kv[7]);
;         *(u32x4*)(dst + ((t8 >> 2) * 64 + (t8 & 3) * 16) * 8) = o;
;     }
	v_addc_co_u32_e32 v65, vcc, 0, v47, vcc
	v_pk_mul_f32 v[50:51], v[50:51], v[52:53]
	v_sub_f32_e32 v52, v62, v73
	v_sub_f32_e32 v53, v62, v74
	v_mul_f32_e32 v52, 0x3fb8aa3b, v52
	v_mul_f32_e32 v53, 0x3fb8aa3b, v53
	v_exp_f32_e32 v52, v52
	v_exp_f32_e32 v53, v53
	v_cvt_pk_bf16_f32 v49, v50, v51
	s_nop 0
	v_lshlrev_b32_e32 v55, 16, v54
	v_lshlrev_b32_e32 v54, 16, v63
	v_mov_b32_e32 v63, v146
	v_add_co_u32_e32 v64, vcc, s0, v46
	v_pk_mul_f32 v[52:53], v[52:53], v[54:55]
	s_nop 0
	v_addc_co_u32_e32 v65, vcc, 0, v47, vcc
	v_mov_b32_e32 v64, v147
	v_sub_f32_e32 v54, v62, v75
	v_sub_f32_e32 v55, v62, v77
	v_mul_f32_e32 v54, 0x3fb8aa3b, v54
	v_mul_f32_e32 v55, 0x3fb8aa3b, v55
	v_exp_f32_e32 v54, v54
	v_exp_f32_e32 v55, v55
	v_cvt_pk_bf16_f32 v50, v52, v53
	s_mov_b32 s0, 0xc000
	s_nop 0
	v_lshlrev_b32_e32 v65, 16, v64
	v_lshlrev_b32_e32 v64, 16, v63
	v_pk_mul_f32 v[54:55], v[54:55], v[64:65]
	s_nop 0
	v_cvt_pk_bf16_f32 v51, v54, v55
	global_store_dwordx4 v[2:3], v[48:51], off
	s_nop 1
	v_add_co_u32_e32 v50, vcc, s0, v46
	s_mov_b32 s0, 0xe000
	s_nop 0
	v_addc_co_u32_e32 v51, vcc, 0, v47, vcc
	v_mov_b32_e32 v52, v148
	v_add_co_u32_e32 v50, vcc, s0, v46
	s_mov_b32 s0, 0xf000
	s_nop 0
	v_addc_co_u32_e32 v51, vcc, 0, v47, vcc
	v_mov_b32_e32 v50, v149
	v_sub_f32_e32 v48, v62, v76
	v_sub_f32_e32 v49, v62, v78
	v_mul_f32_e32 v48, 0x3fb8aa3b, v48
	v_mul_f32_e32 v49, 0x3fb8aa3b, v49
	v_exp_f32_e32 v48, v48
	v_exp_f32_e32 v49, v49
	s_nop 0
	v_lshlrev_b32_e32 v51, 16, v50
	v_lshlrev_b32_e32 v50, 16, v52
	v_add_co_u32_e32 v52, vcc, s0, v46
	s_mov_b32 s0, 0x11000
	s_nop 0
	v_addc_co_u32_e32 v53, vcc, 0, v47, vcc
	v_mov_b32_e32 v54, v150
	v_add_co_u32_e32 v52, vcc, s0, v46
	s_mov_b32 s0, 0x12000
	s_nop 0
	v_addc_co_u32_e32 v53, vcc, 0, v47, vcc
	v_mov_b32_e32 v52, v151
	v_pk_mul_f32 v[48:49], v[48:49], v[50:51]
	v_sub_f32_e32 v50, v62, v79
	v_sub_f32_e32 v51, v62, v80
	v_mul_f32_e32 v50, 0x3fb8aa3b, v50
	v_mul_f32_e32 v51, 0x3fb8aa3b, v51
	v_exp_f32_e32 v50, v50
	v_exp_f32_e32 v51, v51
	v_cvt_pk_bf16_f32 v48, v48, v49
	s_nop 0
	v_lshlrev_b32_e32 v53, 16, v52
	v_lshlrev_b32_e32 v52, 16, v54
	v_add_co_u32_e32 v54, vcc, s0, v46
	s_mov_b32 s0, 0x14000
	s_nop 0
	v_addc_co_u32_e32 v55, vcc, 0, v47, vcc
	v_mov_b32_e32 v63, v152
	v_add_co_u32_e32 v54, vcc, s0, v46
	s_mov_b32 s0, 0x15000
	s_nop 0
	v_addc_co_u32_e32 v55, vcc, 0, v47, vcc
	v_mov_b32_e32 v54, v153
	v_add_co_u32_e32 v64, vcc, s0, v46
	s_mov_b32 s0, 0x17000
	s_nop 0
	v_addc_co_u32_e32 v65, vcc, 0, v47, vcc
	v_pk_mul_f32 v[50:51], v[50:51], v[52:53]
	v_sub_f32_e32 v52, v62, v81
	v_sub_f32_e32 v53, v62, v82
	v_mul_f32_e32 v52, 0x3fb8aa3b, v52
	v_mul_f32_e32 v53, 0x3fb8aa3b, v53
	v_exp_f32_e32 v52, v52
	v_exp_f32_e32 v53, v53
	v_cvt_pk_bf16_f32 v49, v50, v51
	s_nop 0
	v_lshlrev_b32_e32 v55, 16, v54
	v_lshlrev_b32_e32 v54, 16, v63
	v_mov_b32_e32 v63, v154
	v_add_co_u32_e32 v64, vcc, s0, v46
	v_pk_mul_f32 v[52:53], v[52:53], v[54:55]
	s_nop 0
	v_addc_co_u32_e32 v65, vcc, 0, v47, vcc
	v_mov_b32_e32 v64, v155
	v_sub_f32_e32 v54, v62, v83
	v_sub_f32_e32 v55, v62, v84
	v_mul_f32_e32 v54, 0x3fb8aa3b, v54
	v_mul_f32_e32 v55, 0x3fb8aa3b, v55
	v_exp_f32_e32 v54, v54
	v_exp_f32_e32 v55, v55
	v_cvt_pk_bf16_f32 v50, v52, v53
	s_mov_b32 s0, 0x18000
	s_nop 0
	v_lshlrev_b32_e32 v65, 16, v64
	v_lshlrev_b32_e32 v64, 16, v63
	v_pk_mul_f32 v[54:55], v[54:55], v[64:65]
	s_nop 0
	v_cvt_pk_bf16_f32 v51, v54, v55
	global_store_dwordx4 v[2:3], v[48:51], off offset:256
	s_nop 1
	v_add_co_u32_e32 v50, vcc, s0, v46
	s_mov_b32 s0, 0x1a000
	s_nop 0
	v_addc_co_u32_e32 v51, vcc, 0, v47, vcc
	v_mov_b32_e32 v52, v156
	v_add_co_u32_e32 v50, vcc, s0, v46
	s_mov_b32 s0, 0x1b000
	s_nop 0
	v_addc_co_u32_e32 v51, vcc, 0, v47, vcc
	v_mov_b32_e32 v50, v157
	v_sub_f32_e32 v48, v62, v85
	v_sub_f32_e32 v49, v62, v86
	v_mul_f32_e32 v48, 0x3fb8aa3b, v48
	v_mul_f32_e32 v49, 0x3fb8aa3b, v49
	v_exp_f32_e32 v48, v48
	v_exp_f32_e32 v49, v49
	s_nop 0
	v_lshlrev_b32_e32 v51, 16, v50
	v_lshlrev_b32_e32 v50, 16, v52
	v_add_co_u32_e32 v52, vcc, s0, v46
	s_mov_b32 s0, 0x1d000
	s_nop 0
	v_addc_co_u32_e32 v53, vcc, 0, v47, vcc
	v_mov_b32_e32 v54, v158
	v_add_co_u32_e32 v52, vcc, s0, v46
	s_mov_b32 s0, 0x1e000
	s_nop 0
	v_addc_co_u32_e32 v53, vcc, 0, v47, vcc
	v_mov_b32_e32 v52, v159
	v_pk_mul_f32 v[48:49], v[48:49], v[50:51]
	v_sub_f32_e32 v50, v62, v87
	v_sub_f32_e32 v51, v62, v88
	v_mul_f32_e32 v50, 0x3fb8aa3b, v50
	v_mul_f32_e32 v51, 0x3fb8aa3b, v51
	v_exp_f32_e32 v50, v50
	v_exp_f32_e32 v51, v51
	v_cvt_pk_bf16_f32 v48, v48, v49
	s_nop 0
	v_lshlrev_b32_e32 v53, 16, v52
	v_lshlrev_b32_e32 v52, 16, v54
	v_add_co_u32_e32 v54, vcc, s0, v46
	s_mov_b32 s0, 0x20000
	s_nop 0
	v_addc_co_u32_e32 v55, vcc, 0, v47, vcc
	v_mov_b32_e32 v63, v160
	v_add_co_u32_e32 v54, vcc, s0, v46
	s_mov_b32 s0, 0x21000
	s_nop 0
	v_addc_co_u32_e32 v55, vcc, 0, v47, vcc
	v_mov_b32_e32 v54, v161
	v_add_co_u32_e32 v64, vcc, s0, v46
	s_mov_b32 s0, 0x23000
	s_nop 0
	v_addc_co_u32_e32 v65, vcc, 0, v47, vcc
	v_pk_mul_f32 v[50:51], v[50:51], v[52:53]
	v_sub_f32_e32 v52, v62, v89
	v_sub_f32_e32 v53, v62, v90
	v_mul_f32_e32 v52, 0x3fb8aa3b, v52
	v_mul_f32_e32 v53, 0x3fb8aa3b, v53
	v_exp_f32_e32 v52, v52
	v_exp_f32_e32 v53, v53
	v_cvt_pk_bf16_f32 v49, v50, v51
	s_nop 0
	v_lshlrev_b32_e32 v55, 16, v54
	v_lshlrev_b32_e32 v54, 16, v63
	v_mov_b32_e32 v63, v162
	v_add_co_u32_e32 v64, vcc, s0, v46
	v_pk_mul_f32 v[52:53], v[52:53], v[54:55]
	s_nop 0
	v_addc_co_u32_e32 v65, vcc, 0, v47, vcc
	v_mov_b32_e32 v64, v163
	v_sub_f32_e32 v54, v62, v91
	v_sub_f32_e32 v55, v62, v92
	v_mul_f32_e32 v54, 0x3fb8aa3b, v54
	v_mul_f32_e32 v55, 0x3fb8aa3b, v55
	v_exp_f32_e32 v54, v54
	v_exp_f32_e32 v55, v55
	v_cvt_pk_bf16_f32 v50, v52, v53
; __device__ __forceinline__ unsigned pk2(float lo, float hi) { f32x2_t v = {lo, hi}; bf16x2_t b = __builtin_convertvector(v, bf16x2_t); return __builtin_bit_cast(unsigned, b); }
; __device__ __forceinline__ void gla_prep_item(LAS unsigned char* lds, int item, const bf16_t* Z, const float* W2, const float* Bg, bf16_t* KDT, float* DEC) {
;     ...
; #pragma unroll
;     for (int t8 = 0; t8 < 8; ++t8) {
;         float kv[8];
; #pragma unroll
;         for (int e = 0; e < 8; ++e) {
;             const int t = t8 * 8 + e;
;             bc += gv[t];
;             kv[e] = bf2f(gk[(size_t)t * ZLD]) * __expf(bend - bc);
;         }
;         u32x4 o; o.x = pk2(kv[0], kv[1]); o.y = pk2(kv[2], kv[3]); o.z = pk2(kv[4], kv[5]); o.w = pk2(kv[6], kv[7]);
;         *(u32x4*)(dst + ((t8 >> 2) * 64 + (t8 & 3) * 16) * 8) = o;
;     }
	s_mov_b32 s0, 0x24000
	s_nop 0
	v_lshlrev_b32_e32 v65, 16, v64
	v_lshlrev_b32_e32 v64, 16, v63
	v_pk_mul_f32 v[54:55], v[54:55], v[64:65]
	s_nop 0
	v_cvt_pk_bf16_f32 v51, v54, v55
	global_store_dwordx4 v[2:3], v[48:51], off offset:512
	s_nop 1
	v_add_co_u32_e32 v50, vcc, s0, v46
	s_mov_b32 s0, 0x26000
	s_nop 0
	v_addc_co_u32_e32 v51, vcc, 0, v47, vcc
	v_mov_b32_e32 v52, v164
	v_add_co_u32_e32 v50, vcc, s0, v46
	s_mov_b32 s0, 0x27000
	s_nop 0
	v_addc_co_u32_e32 v51, vcc, 0, v47, vcc
	v_mov_b32_e32 v50, v165
	v_sub_f32_e32 v48, v62, v93
	v_sub_f32_e32 v49, v62, v94
	v_mul_f32_e32 v48, 0x3fb8aa3b, v48
	v_mul_f32_e32 v49, 0x3fb8aa3b, v49
	v_exp_f32_e32 v48, v48
	v_exp_f32_e32 v49, v49
	s_nop 0
	v_lshlrev_b32_e32 v51, 16, v50
	v_lshlrev_b32_e32 v50, 16, v52
	v_add_co_u32_e32 v52, vcc, s0, v46
	s_mov_b32 s0, 0x29000
	s_nop 0
	v_addc_co_u32_e32 v53, vcc, 0, v47, vcc
	v_mov_b32_e32 v54, v166
	v_add_co_u32_e32 v52, vcc, s0, v46
	s_mov_b32 s0, 0x2a000
	s_nop 0
	v_addc_co_u32_e32 v53, vcc, 0, v47, vcc
	v_mov_b32_e32 v52, v167
	v_pk_mul_f32 v[48:49], v[48:49], v[50:51]
	v_sub_f32_e32 v50, v62, v95
	v_sub_f32_e32 v51, v62, v96
	v_mul_f32_e32 v50, 0x3fb8aa3b, v50
	v_mul_f32_e32 v51, 0x3fb8aa3b, v51
	v_exp_f32_e32 v50, v50
	v_exp_f32_e32 v51, v51
	v_cvt_pk_bf16_f32 v48, v48, v49
	s_nop 0
	v_lshlrev_b32_e32 v53, 16, v52
	v_lshlrev_b32_e32 v52, 16, v54
	v_add_co_u32_e32 v54, vcc, s0, v46
	s_mov_b32 s0, 0x2c000
	s_nop 0
	v_addc_co_u32_e32 v55, vcc, 0, v47, vcc
	v_mov_b32_e32 v63, v168
	v_add_co_u32_e32 v54, vcc, s0, v46
	s_mov_b32 s0, 0x2d000
	s_nop 0
	v_addc_co_u32_e32 v55, vcc, 0, v47, vcc
	v_mov_b32_e32 v54, v169
	v_add_co_u32_e32 v64, vcc, s0, v46
	s_mov_b32 s0, 0x2f000
	s_nop 0
	v_addc_co_u32_e32 v65, vcc, 0, v47, vcc
	v_pk_mul_f32 v[50:51], v[50:51], v[52:53]
	v_sub_f32_e32 v52, v62, v97
	v_sub_f32_e32 v53, v62, v98
	v_mul_f32_e32 v52, 0x3fb8aa3b, v52
	v_mul_f32_e32 v53, 0x3fb8aa3b, v53
	v_exp_f32_e32 v52, v52
	v_exp_f32_e32 v53, v53
	v_cvt_pk_bf16_f32 v49, v50, v51
	s_nop 0
	v_lshlrev_b32_e32 v55, 16, v54
	v_lshlrev_b32_e32 v54, 16, v63
	v_mov_b32_e32 v63, v170
	v_add_co_u32_e32 v64, vcc, s0, v46
	v_pk_mul_f32 v[52:53], v[52:53], v[54:55]
	s_nop 0
	v_addc_co_u32_e32 v65, vcc, 0, v47, vcc
	v_mov_b32_e32 v64, v171
	v_sub_f32_e32 v54, v62, v99
	v_sub_f32_e32 v55, v62, v100
	v_mul_f32_e32 v54, 0x3fb8aa3b, v54
	v_mul_f32_e32 v55, 0x3fb8aa3b, v55
	v_exp_f32_e32 v54, v54
	v_exp_f32_e32 v55, v55
	v_cvt_pk_bf16_f32 v50, v52, v53
	s_mov_b32 s0, 0x30000
	s_nop 0
	v_lshlrev_b32_e32 v65, 16, v64
	v_lshlrev_b32_e32 v64, 16, v63
	v_pk_mul_f32 v[54:55], v[54:55], v[64:65]
	s_nop 0
	v_cvt_pk_bf16_f32 v51, v54, v55
	global_store_dwordx4 v[2:3], v[48:51], off offset:768
	s_nop 1
	v_add_co_u32_e32 v50, vcc, s0, v46
	s_mov_b32 s0, 0x32000
	s_nop 0
	v_addc_co_u32_e32 v51, vcc, 0, v47, vcc
	v_mov_b32_e32 v52, v172
	v_add_co_u32_e32 v50, vcc, s0, v46
	s_mov_b32 s0, 0x33000
	s_nop 0
	v_addc_co_u32_e32 v51, vcc, 0, v47, vcc
	v_mov_b32_e32 v50, v173
	v_sub_f32_e32 v48, v62, v101
	v_sub_f32_e32 v49, v62, v102
	v_mul_f32_e32 v48, 0x3fb8aa3b, v48
	v_mul_f32_e32 v49, 0x3fb8aa3b, v49
	v_exp_f32_e32 v48, v48
	v_exp_f32_e32 v49, v49
	s_nop 0
	v_lshlrev_b32_e32 v51, 16, v50
	v_lshlrev_b32_e32 v50, 16, v52
	v_add_co_u32_e32 v52, vcc, s0, v46
	s_mov_b32 s0, 0x35000
	s_nop 0
	v_addc_co_u32_e32 v53, vcc, 0, v47, vcc
	v_mov_b32_e32 v54, v174
	v_add_co_u32_e32 v52, vcc, s0, v46
	s_mov_b32 s0, 0x36000
	s_nop 0
	v_addc_co_u32_e32 v53, vcc, 0, v47, vcc
	v_mov_b32_e32 v52, v175
	v_pk_mul_f32 v[48:49], v[48:49], v[50:51]
	v_sub_f32_e32 v50, v62, v103
	v_sub_f32_e32 v51, v62, v104
	v_mul_f32_e32 v50, 0x3fb8aa3b, v50
	v_mul_f32_e32 v51, 0x3fb8aa3b, v51
	v_exp_f32_e32 v50, v50
	v_exp_f32_e32 v51, v51
	v_cvt_pk_bf16_f32 v48, v48, v49
	s_nop 0
	v_lshlrev_b32_e32 v53, 16, v52
	v_lshlrev_b32_e32 v52, 16, v54
	v_add_co_u32_e32 v54, vcc, s0, v46
	s_mov_b32 s0, 0x38000
	s_nop 0
	v_addc_co_u32_e32 v55, vcc, 0, v47, vcc
	v_mov_b32_e32 v63, v176
	v_add_co_u32_e32 v54, vcc, s0, v46
	s_mov_b32 s0, 0x39000
	s_nop 0
	v_addc_co_u32_e32 v55, vcc, 0, v47, vcc
	v_mov_b32_e32 v54, v177
	v_add_co_u32_e32 v64, vcc, s0, v46
	s_mov_b32 s0, 0x3b000
	s_nop 0
	v_addc_co_u32_e32 v65, vcc, 0, v47, vcc
	v_pk_mul_f32 v[50:51], v[50:51], v[52:53]
	v_sub_f32_e32 v52, v62, v105
	v_sub_f32_e32 v53, v62, v106
	v_mul_f32_e32 v52, 0x3fb8aa3b, v52
	v_mul_f32_e32 v53, 0x3fb8aa3b, v53
	v_exp_f32_e32 v52, v52
	v_exp_f32_e32 v53, v53
	v_cvt_pk_bf16_f32 v49, v50, v51
	s_nop 0
	v_lshlrev_b32_e32 v55, 16, v54
	v_lshlrev_b32_e32 v54, 16, v63
	v_mov_b32_e32 v63, v178
	v_add_co_u32_e32 v64, vcc, s0, v46
	v_pk_mul_f32 v[52:53], v[52:53], v[54:55]
	s_nop 0
	v_addc_co_u32_e32 v65, vcc, 0, v47, vcc
	v_mov_b32_e32 v64, v179
	v_sub_f32_e32 v54, v62, v107
	v_sub_f32_e32 v55, v62, v108
	v_mul_f32_e32 v54, 0x3fb8aa3b, v54
	v_mul_f32_e32 v55, 0x3fb8aa3b, v55
	v_exp_f32_e32 v54, v54
	v_exp_f32_e32 v55, v55
	v_cvt_pk_bf16_f32 v50, v52, v53
	s_mov_b32 s0, 0x3c000
	s_nop 0
	v_lshlrev_b32_e32 v65, 16, v64
	v_lshlrev_b32_e32 v64, 16, v63
	v_pk_mul_f32 v[54:55], v[54:55], v[64:65]
	s_nop 0
	v_cvt_pk_bf16_f32 v51, v54, v55
	global_store_dwordx4 v[2:3], v[48:51], off offset:1024
	s_nop 1
	v_add_co_u32_e32 v50, vcc, s0, v46
	s_mov_b32 s0, 0x3e000
	s_nop 0
	v_addc_co_u32_e32 v51, vcc, 0, v47, vcc
	v_mov_b32_e32 v52, v180
	v_add_co_u32_e32 v50, vcc, s0, v46
	s_mov_b32 s0, 0x3f000
	s_nop 0
	v_addc_co_u32_e32 v51, vcc, 0, v47, vcc
	v_mov_b32_e32 v50, v181
	v_sub_f32_e32 v48, v62, v109
	v_sub_f32_e32 v49, v62, v110
	v_mul_f32_e32 v48, 0x3fb8aa3b, v48
	v_mul_f32_e32 v49, 0x3fb8aa3b, v49
	v_exp_f32_e32 v48, v48
	v_exp_f32_e32 v49, v49
	s_nop 0
	v_lshlrev_b32_e32 v51, 16, v50
; __device__ __forceinline__ unsigned pk2(float lo, float hi) { f32x2_t v = {lo, hi}; bf16x2_t b = __builtin_convertvector(v, bf16x2_t); return __builtin_bit_cast(unsigned, b); }
; __device__ __forceinline__ void gla_prep_item(LAS unsigned char* lds, int item, const bf16_t* Z, const float* W2, const float* Bg, bf16_t* KDT, float* DEC) {
;     ...
; #pragma unroll
;     for (int t8 = 0; t8 < 8; ++t8) {
;         float kv[8];
; #pragma unroll
;         for (int e = 0; e < 8; ++e) {
;             const int t = t8 * 8 + e;
;             bc += gv[t];
;             kv[e] = bf2f(gk[(size_t)t * ZLD]) * __expf(bend - bc);
;         }
;         u32x4 o; o.x = pk2(kv[0], kv[1]); o.y = pk2(kv[2], kv[3]); o.z = pk2(kv[4], kv[5]); o.w = pk2(kv[6], kv[7]);
;         *(u32x4*)(dst + ((t8 >> 2) * 64 + (t8 & 3) * 16) * 8) = o;
;     }
	v_lshlrev_b32_e32 v50, 16, v52
	v_add_co_u32_e32 v52, vcc, s0, v46
	s_mov_b32 s0, 0x41000
	s_nop 0
	v_addc_co_u32_e32 v53, vcc, 0, v47, vcc
	v_mov_b32_e32 v54, v182
	v_add_co_u32_e32 v52, vcc, s0, v46
	s_mov_b32 s0, 0x42000
	s_nop 0
	v_addc_co_u32_e32 v53, vcc, 0, v47, vcc
	v_mov_b32_e32 v52, v183
	v_pk_mul_f32 v[48:49], v[48:49], v[50:51]
	v_sub_f32_e32 v50, v62, v111
	v_sub_f32_e32 v51, v62, v112
	v_mul_f32_e32 v50, 0x3fb8aa3b, v50
	v_mul_f32_e32 v51, 0x3fb8aa3b, v51
	v_exp_f32_e32 v50, v50
	v_exp_f32_e32 v51, v51
	v_cvt_pk_bf16_f32 v48, v48, v49
	s_nop 0
	v_lshlrev_b32_e32 v53, 16, v52
	v_lshlrev_b32_e32 v52, 16, v54
	v_add_co_u32_e32 v54, vcc, s0, v46
	s_mov_b32 s0, 0x44000
	s_nop 0
	v_addc_co_u32_e32 v55, vcc, 0, v47, vcc
	v_mov_b32_e32 v63, v186
	v_add_co_u32_e32 v54, vcc, s0, v46
	s_mov_b32 s0, 0x45000
	s_nop 0
	v_addc_co_u32_e32 v55, vcc, 0, v47, vcc
	v_mov_b32_e32 v54, v187
	v_add_co_u32_e32 v64, vcc, s0, v46
	s_mov_b32 s0, 0x47000
	s_nop 0
	v_addc_co_u32_e32 v65, vcc, 0, v47, vcc
	v_pk_mul_f32 v[50:51], v[50:51], v[52:53]
	v_sub_f32_e32 v52, v62, v113
	v_sub_f32_e32 v53, v62, v114
	v_mul_f32_e32 v52, 0x3fb8aa3b, v52
	v_mul_f32_e32 v53, 0x3fb8aa3b, v53
	v_exp_f32_e32 v52, v52
	v_exp_f32_e32 v53, v53
	v_cvt_pk_bf16_f32 v49, v50, v51
	s_nop 0
	v_lshlrev_b32_e32 v55, 16, v54
	v_lshlrev_b32_e32 v54, 16, v63
	v_mov_b32_e32 v63, v188
	v_add_co_u32_e32 v64, vcc, s0, v46
	v_pk_mul_f32 v[52:53], v[52:53], v[54:55]
	s_nop 0
	v_addc_co_u32_e32 v65, vcc, 0, v47, vcc
	v_mov_b32_e32 v64, v189
	v_sub_f32_e32 v54, v62, v115
	v_sub_f32_e32 v55, v62, v116
	v_mul_f32_e32 v54, 0x3fb8aa3b, v54
	v_mul_f32_e32 v55, 0x3fb8aa3b, v55
	v_exp_f32_e32 v54, v54
	v_exp_f32_e32 v55, v55
	v_cvt_pk_bf16_f32 v50, v52, v53
	s_mov_b32 s0, 0x48000
	s_nop 0
	v_lshlrev_b32_e32 v65, 16, v64
	v_lshlrev_b32_e32 v64, 16, v63
	v_pk_mul_f32 v[54:55], v[54:55], v[64:65]
	s_nop 0
	v_cvt_pk_bf16_f32 v51, v54, v55
	global_store_dwordx4 v[2:3], v[48:51], off offset:1280
	s_nop 1
	v_add_co_u32_e32 v50, vcc, s0, v46
	s_mov_b32 s0, 0x4a000
	s_nop 0
	v_addc_co_u32_e32 v51, vcc, 0, v47, vcc
	v_mov_b32_e32 v52, v190
	v_add_co_u32_e32 v50, vcc, s0, v46
	s_mov_b32 s0, 0x4b000
	s_nop 0
	v_addc_co_u32_e32 v51, vcc, 0, v47, vcc
	v_mov_b32_e32 v50, v191
	v_sub_f32_e32 v48, v62, v117
	v_sub_f32_e32 v49, v62, v118
	v_mul_f32_e32 v48, 0x3fb8aa3b, v48
	v_mul_f32_e32 v49, 0x3fb8aa3b, v49
	v_exp_f32_e32 v48, v48
	v_exp_f32_e32 v49, v49
	s_nop 0
	v_lshlrev_b32_e32 v51, 16, v50
	v_lshlrev_b32_e32 v50, 16, v52
	v_add_co_u32_e32 v52, vcc, s0, v46
	s_mov_b32 s0, 0x4d000
	s_nop 0
	v_addc_co_u32_e32 v53, vcc, 0, v47, vcc
	v_mov_b32_e32 v54, v192
	v_add_co_u32_e32 v52, vcc, s0, v46
	s_mov_b32 s0, 0x4e000
	s_nop 0
	v_addc_co_u32_e32 v53, vcc, 0, v47, vcc
	v_mov_b32_e32 v52, v193
	v_pk_mul_f32 v[48:49], v[48:49], v[50:51]
	v_sub_f32_e32 v50, v62, v119
	v_sub_f32_e32 v51, v62, v120
	v_mul_f32_e32 v50, 0x3fb8aa3b, v50
	v_mul_f32_e32 v51, 0x3fb8aa3b, v51
	v_exp_f32_e32 v50, v50
	v_exp_f32_e32 v51, v51
	v_cvt_pk_bf16_f32 v48, v48, v49
	s_nop 0
	v_lshlrev_b32_e32 v53, 16, v52
	v_lshlrev_b32_e32 v52, 16, v54
	v_add_co_u32_e32 v54, vcc, s0, v46
	s_mov_b32 s0, 0x50000
	s_nop 0
	v_addc_co_u32_e32 v55, vcc, 0, v47, vcc
	v_mov_b32_e32 v63, v194
	v_add_co_u32_e32 v54, vcc, s0, v46
	s_mov_b32 s0, 0x51000
	s_nop 0
	v_addc_co_u32_e32 v55, vcc, 0, v47, vcc
	v_mov_b32_e32 v54, v195
	v_add_co_u32_e32 v64, vcc, s0, v46
	s_mov_b32 s0, 0x53000
	s_nop 0
	v_addc_co_u32_e32 v65, vcc, 0, v47, vcc
	v_pk_mul_f32 v[50:51], v[50:51], v[52:53]
	v_sub_f32_e32 v52, v62, v121
	v_sub_f32_e32 v53, v62, v122
	v_mul_f32_e32 v52, 0x3fb8aa3b, v52
; __device__ __forceinline__ unsigned pk2(float lo, float hi) { f32x2_t v = {lo, hi}; bf16x2_t b = __builtin_convertvector(v, bf16x2_t); return __builtin_bit_cast(unsigned, b); }
; __device__ __forceinline__ void gla_prep_item(LAS unsigned char* lds, int item, const bf16_t* Z, const float* W2, const float* Bg, bf16_t* KDT, float* DEC) {
;     ...
; #pragma unroll
;     for (int t8 = 0; t8 < 8; ++t8) {
;         float kv[8];
; #pragma unroll
;         for (int e = 0; e < 8; ++e) {
;             const int t = t8 * 8 + e;
;             bc += gv[t];
;             kv[e] = bf2f(gk[(size_t)t * ZLD]) * __expf(bend - bc);
;         }
;         u32x4 o; o.x = pk2(kv[0], kv[1]); o.y = pk2(kv[2], kv[3]); o.z = pk2(kv[4], kv[5]); o.w = pk2(kv[6], kv[7]);
;         *(u32x4*)(dst + ((t8 >> 2) * 64 + (t8 & 3) * 16) * 8) = o;
;     }
;     DEC[(size_t)((b * 4 + h) * 32 + c) * 128 + kd] = expf(bend);
;     __syncthreads();
; }
	v_mul_f32_e32 v53, 0x3fb8aa3b, v53
	v_exp_f32_e32 v52, v52
	v_exp_f32_e32 v53, v53
	v_cvt_pk_bf16_f32 v49, v50, v51
	s_nop 0
	v_lshlrev_b32_e32 v55, 16, v54
	v_lshlrev_b32_e32 v54, 16, v63
	v_mov_b32_e32 v63, v196
	v_add_co_u32_e32 v64, vcc, s0, v46
	v_pk_mul_f32 v[52:53], v[52:53], v[54:55]
	s_nop 0
	v_addc_co_u32_e32 v65, vcc, 0, v47, vcc
	v_mov_b32_e32 v64, v197
	v_sub_f32_e32 v54, v62, v123
	v_sub_f32_e32 v55, v62, v124
	v_mul_f32_e32 v54, 0x3fb8aa3b, v54
	v_mul_f32_e32 v55, 0x3fb8aa3b, v55
	v_exp_f32_e32 v54, v54
	v_exp_f32_e32 v55, v55
	v_cvt_pk_bf16_f32 v50, v52, v53
	s_mov_b32 s0, 0x3fb8aa3b
	s_nop 0
	v_lshlrev_b32_e32 v65, 16, v64
	v_lshlrev_b32_e32 v64, 16, v63
	v_pk_mul_f32 v[54:55], v[54:55], v[64:65]
	s_nop 0
	v_cvt_pk_bf16_f32 v51, v54, v55
	global_store_dwordx4 v[2:3], v[48:51], off offset:1536
	s_nop 1
	v_add_co_u32_e32 v50, vcc, s37, v46
	v_sub_f32_e32 v48, v62, v125
	s_nop 0
	v_addc_co_u32_e32 v51, vcc, 0, v47, vcc
	v_mov_b32_e32 v52, v198
	v_add_co_u32_e32 v50, vcc, s52, v46
	v_sub_f32_e32 v49, v62, v126
	s_nop 0
	v_addc_co_u32_e32 v51, vcc, 0, v47, vcc
	v_mov_b32_e32 v50, v199
	v_mul_f32_e32 v48, 0x3fb8aa3b, v48
	v_mul_f32_e32 v49, 0x3fb8aa3b, v49
	v_exp_f32_e32 v48, v48
	v_exp_f32_e32 v49, v49
	s_nop 0
	v_lshlrev_b32_e32 v51, 16, v50
	v_lshlrev_b32_e32 v50, 16, v52
	v_add_co_u32_e32 v52, vcc, s53, v46
	v_pk_mul_f32 v[48:49], v[48:49], v[50:51]
	s_nop 0
	v_addc_co_u32_e32 v53, vcc, 0, v47, vcc
	v_mov_b32_e32 v54, v200
	v_add_co_u32_e32 v52, vcc, s58, v46
	v_sub_f32_e32 v50, v62, v127
	s_nop 0
	v_addc_co_u32_e32 v53, vcc, 0, v47, vcc
	v_mov_b32_e32 v52, v201
	v_sub_f32_e32 v51, v62, v128
	v_mul_f32_e32 v50, 0x3fb8aa3b, v50
	v_mul_f32_e32 v51, 0x3fb8aa3b, v51
	v_exp_f32_e32 v50, v50
	v_exp_f32_e32 v51, v51
	s_nop 0
	v_lshlrev_b32_e32 v53, 16, v52
	v_lshlrev_b32_e32 v52, 16, v54
	v_add_co_u32_e32 v54, vcc, s59, v46
	v_pk_mul_f32 v[50:51], v[50:51], v[52:53]
	s_nop 0
	v_addc_co_u32_e32 v55, vcc, 0, v47, vcc
	v_mov_b32_e32 v63, v202
	v_add_co_u32_e32 v54, vcc, s60, v46
	v_sub_f32_e32 v52, v62, v129
	s_nop 0
	v_addc_co_u32_e32 v55, vcc, 0, v47, vcc
	v_mov_b32_e32 v54, v203
	v_add_co_u32_e32 v64, vcc, s61, v46
	v_sub_f32_e32 v53, v62, v130
	s_nop 0
	v_addc_co_u32_e32 v65, vcc, 0, v47, vcc
	v_add_co_u32_e32 v46, vcc, s62, v46
	v_mul_f32_e32 v52, 0x3fb8aa3b, v52
	s_nop 0
	v_addc_co_u32_e32 v47, vcc, 0, v47, vcc
	v_mov_b32_e32 v46, v205
	v_mul_f32_e32 v53, 0x3fb8aa3b, v53
	v_exp_f32_e32 v52, v52
	v_exp_f32_e32 v53, v53
	v_cmp_ngt_f32_e32 vcc, s63, v62
	s_nop 0
	v_lshlrev_b32_e32 v55, 16, v54
	v_lshlrev_b32_e32 v54, 16, v63
	v_mov_b32_e32 v63, v204
	v_pk_mul_f32 v[52:53], v[52:53], v[54:55]
	v_sub_f32_e32 v54, v62, v131
	v_sub_f32_e32 v55, v62, v62
	v_mul_f32_e32 v54, 0x3fb8aa3b, v54
	v_mul_f32_e32 v55, 0x3fb8aa3b, v55
	v_exp_f32_e32 v54, v54
	v_exp_f32_e32 v55, v55
	s_nop 0
	v_lshlrev_b32_e32 v47, 16, v46
	s_nop 0
	v_lshlrev_b32_e32 v46, 16, v63
	v_pk_mul_f32 v[54:55], v[54:55], v[46:47]
	v_cvt_pk_bf16_f32 v46, v48, v49
	v_cvt_pk_bf16_f32 v47, v50, v51
	v_cvt_pk_bf16_f32 v48, v52, v53
	v_cvt_pk_bf16_f32 v49, v54, v55
	global_store_dwordx4 v[2:3], v[46:49], off offset:1792
	v_mul_f32_e32 v2, 0x3fb8aa3b, v62
	v_fma_f32 v3, v62, s0, -v2
	v_rndne_f32_e32 v46, v2
	v_fmac_f32_e32 v3, 0x32a5705f, v62
	v_sub_f32_e32 v2, v2, v46
	v_add_f32_e32 v2, v2, v3
	v_exp_f32_e32 v2, v2
	v_cvt_i32_f32_e32 v3, v46
	v_ldexp_f32 v2, v2, v3
	v_cndmask_b32_e32 v2, 0, v2, vcc
	v_cmp_nlt_f32_e32 vcc, s64, v62
	s_nop 1
	v_cndmask_b32_e32 v2, v61, v2, vcc
	global_store_dword v[0:1], v2, off
	s_barrier
	s_cbranch_scc0 .LBB0_597
	s_branch .LBB0_595
